# ds_bpermute row reductions replaced by v_permlane16/32_swap; rows_rstd 1/sqrt via v_rsq_f32 plus one Newton step (f32)
# speedup vs baseline: 1.0279x; 1.0070x over previous
; #define GAS_ __attribute__((address_space(1)))
; __device__ __forceinline__ unsigned pk2(float lo, float hi) { f32x2_t v = {lo, hi}; bf16x2_t b = __builtin_convertvector(v, bf16x2_t); return __builtin_bit_cast(unsigned, b); }
; __device__ __forceinline__ void rows_rstd(float (&rs)[2][4], const float* SS, int row0, int fq) {
;     ...
;         for (int m = 0; m < 4; ++m) { float s = (q[ai][m][0] + q[ai][m][1]) + (q[ai][m][2] + q[ai][m][3]); s += __shfl_xor(s, 16); s += __shfl_xor(s, 32);
;             rs[ai][m] = 1.0f / sqrtf(s * (1.0f / 1024.0f) + 1e-5f); }
;     __device__ __forceinline__ void operator()(const f32x4 (&acc)[2][2][4][2], const Unit& u, int wr, int wc, int fr, int fq) const {
;     ...
;                 const int row = row0 + ai * 128 + m * 16;
;                 const f32x4 c4 = cc[m], s4 = ss[m];
;                 bf16_t* rowp = HM ? Z + ((size_t)(((row >> 12) * 3 + (col0 >> 10)) * 16 + ((col0 & 1023) >> 6)) * T + (row & (T - 1))) * 64 + (col0 & 63) : Z + (size_t)row * ldz + col0;
;                 constexpr int bjstep = HM ? 2 * T * 64 : 128;
;                 const float rs = SS ? rsv[ai][m] : 1.0f;
; #pragma unroll
;                 for (int bj = 0; bj < 2; ++bj) {
;                     const int h = u.pn * 2 + bj;
;                     if (HM == 0 && col0 + bj * 128 >= 2072) continue;
;                     const float sc = ((scaleMask >> h) & 1u) ? rs * C2 : rs;
;                     f32x4 v0 = acc[ai][bj][m][0] * sc, v1 = acc[ai][bj][m][1] * sc;
;                     int off = bj * bjstep;
;                     if ((dualMask >> h) & 1u) { u32x4 w; w.x = pk2(v0[0], v0[1]); w.y = pk2(v0[2], v0[3]); w.z = pk2(v1[0], v1[1]); w.w = pk2(v1[2], v1[3]); *(GAS_ u32x4*)(rowp + off) = w; off += dualOff; }
.LBB0_227:
	s_waitcnt lgkmcnt(7)
	v_add_f32_e32 v115, v186, v187
	v_fmamk_f32 v115, v115, 0x3a800000, v212
	v_rsq_f32_e32 v119, v115
	s_nop 0
	v_mul_f32_e32 v168, v115, v119
	v_fma_f32 v168, -v168, v119, 1.0
	v_mul_f32_e32 v187, 0.5, v119
	v_fma_f32 v115, v187, v168, v119
	s_nop 1
	v_lshl_or_b32 v186, s0, 8, v207
	v_cmp_gt_i32_e64 s[6:7], s54, v186
	v_mov_b64_e32 v[222:223], s[16:17]
	v_ashrrev_i32_e32 v187, 31, v186
	v_mad_i64_i32 v[202:203], s[4:5], v202, s53, v[222:223]
	v_lshl_add_u64 v[202:203], v[186:187], 1, v[202:203]
	v_mul_f32_e32 v168, 0x3e38aa3b, v115
	s_and_saveexec_b64 s[4:5], s[6:7]
	s_cbranch_execz .LBB0_232
	s_lshl_b32 s0, 1, s23
	s_and_b32 s10, s0, 0x1405
	s_cmp_eq_u32 s10, 0
	s_cselect_b64 vcc, -1, 0
	v_cndmask_b32_e32 v222, v168, v115, vcc
	s_and_b32 s10, s0, 5
	v_pk_mul_f32 v[158:159], v[158:159], v[222:223] op_sel_hi:[1,0]
	v_pk_mul_f32 v[156:157], v[156:157], v[222:223] op_sel_hi:[1,0]
	v_pk_mul_f32 v[154:155], v[154:155], v[222:223] op_sel_hi:[1,0]
	s_cmp_eq_u32 s10, 0
	v_pk_mul_f32 v[152:153], v[152:153], v[222:223] op_sel_hi:[1,0]
	s_cbranch_scc1 .LBB0_312
	v_cvt_pk_bf16_f32 v222, v156, v157
	v_cvt_pk_bf16_f32 v223, v158, v159
	v_cvt_pk_bf16_f32 v224, v152, v153
	v_cvt_pk_bf16_f32 v225, v154, v155
	s_mov_b64 s[10:11], 0x900
	global_store_dwordx4 v[202:203], v[222:225], off
	s_and_b32 s0, s0, 0x5545
	s_cmp_eq_u32 s0, 0
	s_cbranch_scc1 .LBB0_231

; #define GAS_ __attribute__((address_space(1)))
; __device__ __forceinline__ unsigned pk2(float lo, float hi) { f32x2_t v = {lo, hi}; bf16x2_t b = __builtin_convertvector(v, bf16x2_t); return __builtin_bit_cast(unsigned, b); }
; __device__ __forceinline__ void rows_rstd(float (&rs)[2][4], const float* SS, int row0, int fq) {
;     ...
;         for (int m = 0; m < 4; ++m) { float s = (q[ai][m][0] + q[ai][m][1]) + (q[ai][m][2] + q[ai][m][3]); s += __shfl_xor(s, 16); s += __shfl_xor(s, 32);
;             rs[ai][m] = 1.0f / sqrtf(s * (1.0f / 1024.0f) + 1e-5f); }
;     __device__ __forceinline__ void operator()(const f32x4 (&acc)[2][2][4][2], const Unit& u, int wr, int wc, int fr, int fq) const {
;     ...
;                 const float rs = SS ? rsv[ai][m] : 1.0f;
; #pragma unroll
;                 for (int bj = 0; bj < 2; ++bj) {
;                     const int h = u.pn * 2 + bj;
;                     if (HM == 0 && col0 + bj * 128 >= 2072) continue;
;                     const float sc = ((scaleMask >> h) & 1u) ? rs * C2 : rs;
;                     f32x4 v0 = acc[ai][bj][m][0] * sc, v1 = acc[ai][bj][m][1] * sc;
;                     int off = bj * bjstep;
;                     if ((dualMask >> h) & 1u) { u32x4 w; w.x = pk2(v0[0], v0[1]); w.y = pk2(v0[2], v0[3]); w.z = pk2(v1[0], v1[1]); w.w = pk2(v1[2], v1[3]); *(GAS_ u32x4*)(rowp + off) = w; off += dualOff; }
.LBB0_237:
	s_or_b64 exec, exec, s[10:11]
	s_waitcnt lgkmcnt(6)
	v_add_f32_e32 v115, v220, v221
	v_fmamk_f32 v115, v115, 0x3a800000, v212
	v_rsq_f32_e32 v119, v115
	s_nop 0
	v_mul_f32_e32 v144, v115, v119
	v_fma_f32 v144, -v144, v119, 1.0
	v_mul_f32_e32 v146, 0.5, v119
	v_fma_f32 v115, v146, v144, v119
	s_nop 1
	v_mov_b64_e32 v[144:145], s[16:17]
	v_mad_i64_i32 v[144:145], s[10:11], v200, s53, v[144:145]
	v_lshl_add_u64 v[144:145], v[186:187], 1, v[144:145]
	v_mul_f32_e32 v119, 0x3e38aa3b, v115
	s_and_saveexec_b64 s[10:11], s[6:7]
	s_cbranch_execz .LBB0_242
	s_lshl_b32 s0, 1, s23
	s_and_b32 s25, s0, 0x1405
	s_cmp_eq_u32 s25, 0
	s_cselect_b64 vcc, -1, 0
	v_cndmask_b32_e32 v146, v119, v115, vcc
	s_and_b32 s25, s0, 5
	v_pk_mul_f32 v[142:143], v[142:143], v[146:147] op_sel_hi:[1,0]
	v_pk_mul_f32 v[140:141], v[140:141], v[146:147] op_sel_hi:[1,0]
	v_pk_mul_f32 v[138:139], v[138:139], v[146:147] op_sel_hi:[1,0]
	s_cmp_eq_u32 s25, 0
	v_pk_mul_f32 v[136:137], v[136:137], v[146:147] op_sel_hi:[1,0]
	s_cbranch_scc1 .LBB0_314
	v_cvt_pk_bf16_f32 v146, v140, v141
	v_cvt_pk_bf16_f32 v147, v142, v143
	v_cvt_pk_bf16_f32 v148, v136, v137
	v_cvt_pk_bf16_f32 v149, v138, v139
	s_mov_b64 s[34:35], 0x900
	global_store_dwordx4 v[144:145], v[146:149], off
	s_and_b32 s0, s0, 0x5545
	s_cmp_eq_u32 s0, 0
	s_cbranch_scc1 .LBB0_241

; #define GAS_ __attribute__((address_space(1)))
; __device__ __forceinline__ unsigned pk2(float lo, float hi) { f32x2_t v = {lo, hi}; bf16x2_t b = __builtin_convertvector(v, bf16x2_t); return __builtin_bit_cast(unsigned, b); }
; __device__ __forceinline__ void rows_rstd(float (&rs)[2][4], const float* SS, int row0, int fq) {
;     ...
;         for (int m = 0; m < 4; ++m) { float s = (q[ai][m][0] + q[ai][m][1]) + (q[ai][m][2] + q[ai][m][3]); s += __shfl_xor(s, 16); s += __shfl_xor(s, 32);
;             rs[ai][m] = 1.0f / sqrtf(s * (1.0f / 1024.0f) + 1e-5f); }
;     __device__ __forceinline__ void operator()(const f32x4 (&acc)[2][2][4][2], const Unit& u, int wr, int wc, int fr, int fq) const {
;     ...
;                 const float rs = SS ? rsv[ai][m] : 1.0f;
; #pragma unroll
;                 for (int bj = 0; bj < 2; ++bj) {
;                     const int h = u.pn * 2 + bj;
;                     if (HM == 0 && col0 + bj * 128 >= 2072) continue;
;                     const float sc = ((scaleMask >> h) & 1u) ? rs * C2 : rs;
;                     f32x4 v0 = acc[ai][bj][m][0] * sc, v1 = acc[ai][bj][m][1] * sc;
;                     int off = bj * bjstep;
;                     if ((dualMask >> h) & 1u) { u32x4 w; w.x = pk2(v0[0], v0[1]); w.y = pk2(v0[2], v0[3]); w.z = pk2(v1[0], v1[1]); w.w = pk2(v1[2], v1[3]); *(GAS_ u32x4*)(rowp + off) = w; off += dualOff; }
.LBB0_247:
	s_or_b64 exec, exec, s[10:11]
	s_waitcnt lgkmcnt(5)
	v_add_f32_e32 v115, v218, v219
	v_fmamk_f32 v115, v115, 0x3a800000, v212
	v_rsq_f32_e32 v119, v115
	s_nop 0
	v_mul_f32_e32 v128, v115, v119
	v_fma_f32 v128, -v128, v119, 1.0
	v_mul_f32_e32 v130, 0.5, v119
	v_fma_f32 v115, v130, v128, v119
	s_nop 1
	v_mov_b64_e32 v[128:129], s[16:17]
	v_mad_i64_i32 v[128:129], s[10:11], v198, s53, v[128:129]
	v_lshl_add_u64 v[128:129], v[186:187], 1, v[128:129]
	v_mul_f32_e32 v119, 0x3e38aa3b, v115
	s_and_saveexec_b64 s[10:11], s[6:7]
	s_cbranch_execz .LBB0_252
	s_lshl_b32 s0, 1, s23
	s_and_b32 s25, s0, 0x1405
	s_cmp_eq_u32 s25, 0
	s_cselect_b64 vcc, -1, 0
	v_cndmask_b32_e32 v130, v119, v115, vcc
	s_and_b32 s25, s0, 5
	v_pk_mul_f32 v[126:127], v[126:127], v[130:131] op_sel_hi:[1,0]
	v_pk_mul_f32 v[124:125], v[124:125], v[130:131] op_sel_hi:[1,0]
	v_pk_mul_f32 v[122:123], v[122:123], v[130:131] op_sel_hi:[1,0]
	s_cmp_eq_u32 s25, 0
	v_pk_mul_f32 v[120:121], v[120:121], v[130:131] op_sel_hi:[1,0]
	s_cbranch_scc1 .LBB0_316
	v_cvt_pk_bf16_f32 v130, v124, v125
	v_cvt_pk_bf16_f32 v131, v126, v127
	v_cvt_pk_bf16_f32 v132, v120, v121
	v_cvt_pk_bf16_f32 v133, v122, v123
	s_mov_b64 s[34:35], 0x900
	global_store_dwordx4 v[128:129], v[130:133], off
	s_and_b32 s0, s0, 0x5545
	s_cmp_eq_u32 s0, 0
	s_cbranch_scc1 .LBB0_251

; #define GAS_ __attribute__((address_space(1)))
; __device__ __forceinline__ unsigned pk2(float lo, float hi) { f32x2_t v = {lo, hi}; bf16x2_t b = __builtin_convertvector(v, bf16x2_t); return __builtin_bit_cast(unsigned, b); }
; __device__ __forceinline__ void rows_rstd(float (&rs)[2][4], const float* SS, int row0, int fq) {
;     ...
;         for (int m = 0; m < 4; ++m) { float s = (q[ai][m][0] + q[ai][m][1]) + (q[ai][m][2] + q[ai][m][3]); s += __shfl_xor(s, 16); s += __shfl_xor(s, 32);
;             rs[ai][m] = 1.0f / sqrtf(s * (1.0f / 1024.0f) + 1e-5f); }
;     __device__ __forceinline__ void operator()(const f32x4 (&acc)[2][2][4][2], const Unit& u, int wr, int wc, int fr, int fq) const {
;     ...
;                 const float rs = SS ? rsv[ai][m] : 1.0f;
; #pragma unroll
;                 for (int bj = 0; bj < 2; ++bj) {
;                     const int h = u.pn * 2 + bj;
;                     if (HM == 0 && col0 + bj * 128 >= 2072) continue;
;                     const float sc = ((scaleMask >> h) & 1u) ? rs * C2 : rs;
;                     f32x4 v0 = acc[ai][bj][m][0] * sc, v1 = acc[ai][bj][m][1] * sc;
;                     int off = bj * bjstep;
;                     if ((dualMask >> h) & 1u) { u32x4 w; w.x = pk2(v0[0], v0[1]); w.y = pk2(v0[2], v0[3]); w.z = pk2(v1[0], v1[1]); w.w = pk2(v1[2], v1[3]); *(GAS_ u32x4*)(rowp + off) = w; off += dualOff; }
.LBB0_257:
	s_or_b64 exec, exec, s[10:11]
	s_waitcnt lgkmcnt(4)
	v_add_f32_e32 v104, v216, v217
	v_fmamk_f32 v104, v104, 0x3a800000, v212
	v_rsq_f32_e32 v105, v104
	s_nop 0
	v_mul_f32_e32 v108, v104, v105
	v_fma_f32 v108, -v108, v105, 1.0
	v_mul_f32_e32 v107, 0.5, v105
	v_fma_f32 v106, v107, v108, v105
	s_nop 1
	v_mov_b64_e32 v[104:105], s[16:17]
	v_mad_i64_i32 v[104:105], s[10:11], v196, s53, v[104:105]
	v_lshl_add_u64 v[104:105], v[186:187], 1, v[104:105]
	v_mul_f32_e32 v107, 0x3e38aa3b, v106
	s_and_saveexec_b64 s[10:11], s[6:7]
	s_cbranch_execz .LBB0_262
	s_lshl_b32 s0, 1, s23
	s_and_b32 s25, s0, 0x1405
	s_cmp_eq_u32 s25, 0
	s_cselect_b64 vcc, -1, 0
	v_cndmask_b32_e32 v108, v107, v106, vcc
	s_and_b32 s25, s0, 5
	v_pk_mul_f32 v[102:103], v[102:103], v[108:109] op_sel_hi:[1,0]
	v_pk_mul_f32 v[100:101], v[100:101], v[108:109] op_sel_hi:[1,0]
	v_pk_mul_f32 v[98:99], v[98:99], v[108:109] op_sel_hi:[1,0]
	s_cmp_eq_u32 s25, 0
	v_pk_mul_f32 v[96:97], v[96:97], v[108:109] op_sel_hi:[1,0]
	s_cbranch_scc1 .LBB0_318
	v_cvt_pk_bf16_f32 v108, v100, v101
	v_cvt_pk_bf16_f32 v109, v102, v103
	v_cvt_pk_bf16_f32 v110, v96, v97
	v_cvt_pk_bf16_f32 v111, v98, v99
	s_mov_b64 s[34:35], 0x900
	global_store_dwordx4 v[104:105], v[108:111], off
	s_and_b32 s0, s0, 0x5545
	s_cmp_eq_u32 s0, 0
	s_cbranch_scc1 .LBB0_261

; #define GAS_ __attribute__((address_space(1)))
; __device__ __forceinline__ unsigned pk2(float lo, float hi) { f32x2_t v = {lo, hi}; bf16x2_t b = __builtin_convertvector(v, bf16x2_t); return __builtin_bit_cast(unsigned, b); }
; __device__ __forceinline__ void rows_rstd(float (&rs)[2][4], const float* SS, int row0, int fq) {
;     ...
;         for (int m = 0; m < 4; ++m) { float s = (q[ai][m][0] + q[ai][m][1]) + (q[ai][m][2] + q[ai][m][3]); s += __shfl_xor(s, 16); s += __shfl_xor(s, 32);
;             rs[ai][m] = 1.0f / sqrtf(s * (1.0f / 1024.0f) + 1e-5f); }
;     __device__ __forceinline__ void operator()(const f32x4 (&acc)[2][2][4][2], const Unit& u, int wr, int wc, int fr, int fq) const {
;     ...
;                 const float rs = SS ? rsv[ai][m] : 1.0f;
; #pragma unroll
;                 for (int bj = 0; bj < 2; ++bj) {
;                     const int h = u.pn * 2 + bj;
;                     if (HM == 0 && col0 + bj * 128 >= 2072) continue;
;                     const float sc = ((scaleMask >> h) & 1u) ? rs * C2 : rs;
;                     f32x4 v0 = acc[ai][bj][m][0] * sc, v1 = acc[ai][bj][m][1] * sc;
;                     int off = bj * bjstep;
;                     if ((dualMask >> h) & 1u) { u32x4 w; w.x = pk2(v0[0], v0[1]); w.y = pk2(v0[2], v0[3]); w.z = pk2(v1[0], v1[1]); w.w = pk2(v1[2], v1[3]); *(GAS_ u32x4*)(rowp + off) = w; off += dualOff; }
.LBB0_269:
	s_waitcnt lgkmcnt(3)
	v_add_f32_e32 v80, v201, v214
	v_fmamk_f32 v80, v80, 0x3a800000, v212
	v_rsq_f32_e32 v81, v80
	s_nop 0
	v_mul_f32_e32 v82, v80, v81
	v_fma_f32 v82, -v82, v81, 1.0
	v_mul_f32_e32 v83, 0.5, v81
	v_fma_f32 v84, v83, v82, v81
	s_nop 1
	v_mov_b64_e32 v[80:81], s[16:17]
	v_mad_i64_i32 v[80:81], s[10:11], v192, s53, v[80:81]
	v_mov_b32_e32 v82, v113
	v_mov_b32_e32 v83, v117
	v_lshl_add_u64 v[80:81], v[186:187], 1, v[80:81]
	v_mul_f32_e32 v85, 0x3e38aa3b, v84
	s_and_saveexec_b64 s[10:11], s[6:7]
	s_cbranch_execz .LBB0_274
	s_lshl_b32 s0, 1, s23
	s_and_b32 s25, s0, 0x1405
	s_cmp_eq_u32 s25, 0
	s_cselect_b64 vcc, -1, 0
	v_cndmask_b32_e32 v86, v85, v84, vcc
	s_and_b32 s25, s0, 5
	v_pk_mul_f32 v[70:71], v[70:71], v[86:87] op_sel_hi:[1,0]
	v_pk_mul_f32 v[68:69], v[68:69], v[86:87] op_sel_hi:[1,0]
	v_pk_mul_f32 v[66:67], v[66:67], v[86:87] op_sel_hi:[1,0]
	s_cmp_eq_u32 s25, 0
	v_pk_mul_f32 v[64:65], v[64:65], v[86:87] op_sel_hi:[1,0]
	s_cbranch_scc1 .LBB0_320
	v_cvt_pk_bf16_f32 v96, v68, v69
	v_cvt_pk_bf16_f32 v97, v70, v71
	v_cvt_pk_bf16_f32 v98, v64, v65
	v_cvt_pk_bf16_f32 v99, v66, v67
	s_mov_b64 s[30:31], 0x900
	global_store_dwordx4 v[80:81], v[96:99], off
	s_and_b32 s0, s0, 0x5545
	s_cmp_eq_u32 s0, 0
	s_cbranch_scc1 .LBB0_273

; #define GAS_ __attribute__((address_space(1)))
; __device__ __forceinline__ unsigned pk2(float lo, float hi) { f32x2_t v = {lo, hi}; bf16x2_t b = __builtin_convertvector(v, bf16x2_t); return __builtin_bit_cast(unsigned, b); }
; __device__ __forceinline__ void rows_rstd(float (&rs)[2][4], const float* SS, int row0, int fq) {
;     ...
;         for (int m = 0; m < 4; ++m) { float s = (q[ai][m][0] + q[ai][m][1]) + (q[ai][m][2] + q[ai][m][3]); s += __shfl_xor(s, 16); s += __shfl_xor(s, 32);
;             rs[ai][m] = 1.0f / sqrtf(s * (1.0f / 1024.0f) + 1e-5f); }
;     __device__ __forceinline__ void operator()(const f32x4 (&acc)[2][2][4][2], const Unit& u, int wr, int wc, int fr, int fq) const {
;     ...
;                 const float rs = SS ? rsv[ai][m] : 1.0f;
; #pragma unroll
;                 for (int bj = 0; bj < 2; ++bj) {
;                     const int h = u.pn * 2 + bj;
;                     if (HM == 0 && col0 + bj * 128 >= 2072) continue;
;                     const float sc = ((scaleMask >> h) & 1u) ? rs * C2 : rs;
;                     f32x4 v0 = acc[ai][bj][m][0] * sc, v1 = acc[ai][bj][m][1] * sc;
;                     int off = bj * bjstep;
;                     if ((dualMask >> h) & 1u) { u32x4 w; w.x = pk2(v0[0], v0[1]); w.y = pk2(v0[2], v0[3]); w.z = pk2(v1[0], v1[1]); w.w = pk2(v1[2], v1[3]); *(GAS_ u32x4*)(rowp + off) = w; off += dualOff; }
.LBB0_279:
	s_or_b64 exec, exec, s[10:11]
	s_waitcnt lgkmcnt(2)
	v_add_f32_e32 v56, v197, v199
	v_fmamk_f32 v56, v56, 0x3a800000, v212
	v_rsq_f32_e32 v57, v56
	s_nop 0
	v_mul_f32_e32 v60, v56, v57
	v_fma_f32 v60, -v60, v57, 1.0
	v_mul_f32_e32 v59, 0.5, v57
	v_fma_f32 v58, v59, v60, v57
	s_nop 1
	v_mov_b64_e32 v[56:57], s[16:17]
	v_mad_i64_i32 v[56:57], s[10:11], v190, s53, v[56:57]
	v_lshl_add_u64 v[56:57], v[186:187], 1, v[56:57]
	v_mul_f32_e32 v59, 0x3e38aa3b, v58
	s_and_saveexec_b64 s[10:11], s[6:7]
	s_cbranch_execz .LBB0_284
	s_lshl_b32 s0, 1, s23
	s_and_b32 s25, s0, 0x1405
	s_cmp_eq_u32 s25, 0
	s_cselect_b64 vcc, -1, 0
	v_cndmask_b32_e32 v60, v59, v58, vcc
	s_and_b32 s25, s0, 5
	v_pk_mul_f32 v[46:47], v[46:47], v[60:61] op_sel_hi:[1,0]
	v_pk_mul_f32 v[44:45], v[44:45], v[60:61] op_sel_hi:[1,0]
	v_pk_mul_f32 v[42:43], v[42:43], v[60:61] op_sel_hi:[1,0]
	s_cmp_eq_u32 s25, 0
	v_pk_mul_f32 v[40:41], v[40:41], v[60:61] op_sel_hi:[1,0]
	s_cbranch_scc1 .LBB0_322
	v_cvt_pk_bf16_f32 v60, v44, v45
	v_cvt_pk_bf16_f32 v61, v46, v47
	v_cvt_pk_bf16_f32 v62, v40, v41
	v_cvt_pk_bf16_f32 v63, v42, v43
	s_mov_b64 s[30:31], 0x900
	global_store_dwordx4 v[56:57], v[60:63], off
	s_and_b32 s0, s0, 0x5545
	s_cmp_eq_u32 s0, 0
	s_cbranch_scc1 .LBB0_283

; #define GAS_ __attribute__((address_space(1)))
; __device__ __forceinline__ unsigned pk2(float lo, float hi) { f32x2_t v = {lo, hi}; bf16x2_t b = __builtin_convertvector(v, bf16x2_t); return __builtin_bit_cast(unsigned, b); }
; __device__ __forceinline__ void rows_rstd(float (&rs)[2][4], const float* SS, int row0, int fq) {
;     ...
;         for (int m = 0; m < 4; ++m) { float s = (q[ai][m][0] + q[ai][m][1]) + (q[ai][m][2] + q[ai][m][3]); s += __shfl_xor(s, 16); s += __shfl_xor(s, 32);
;             rs[ai][m] = 1.0f / sqrtf(s * (1.0f / 1024.0f) + 1e-5f); }
;     __device__ __forceinline__ void operator()(const f32x4 (&acc)[2][2][4][2], const Unit& u, int wr, int wc, int fr, int fq) const {
;     ...
;                 const float rs = SS ? rsv[ai][m] : 1.0f;
; #pragma unroll
;                 for (int bj = 0; bj < 2; ++bj) {
;                     const int h = u.pn * 2 + bj;
;                     if (HM == 0 && col0 + bj * 128 >= 2072) continue;
;                     const float sc = ((scaleMask >> h) & 1u) ? rs * C2 : rs;
;                     f32x4 v0 = acc[ai][bj][m][0] * sc, v1 = acc[ai][bj][m][1] * sc;
;                     int off = bj * bjstep;
;                     if ((dualMask >> h) & 1u) { u32x4 w; w.x = pk2(v0[0], v0[1]); w.y = pk2(v0[2], v0[3]); w.z = pk2(v1[0], v1[1]); w.w = pk2(v1[2], v1[3]); *(GAS_ u32x4*)(rowp + off) = w; off += dualOff; }
.LBB0_289:
	s_or_b64 exec, exec, s[10:11]
	s_waitcnt lgkmcnt(1)
	v_add_f32_e32 v32, v191, v193
	v_fmamk_f32 v32, v32, 0x3a800000, v212
	v_rsq_f32_e32 v33, v32
	s_nop 0
	v_mul_f32_e32 v36, v32, v33
	v_fma_f32 v36, -v36, v33, 1.0
	v_mul_f32_e32 v35, 0.5, v33
	v_fma_f32 v34, v35, v36, v33
	s_nop 1
	v_mov_b64_e32 v[32:33], s[16:17]
	v_mad_i64_i32 v[32:33], s[10:11], v188, s53, v[32:33]
	v_lshl_add_u64 v[32:33], v[186:187], 1, v[32:33]
	v_mul_f32_e32 v35, 0x3e38aa3b, v34
	s_and_saveexec_b64 s[10:11], s[6:7]
	s_cbranch_execz .LBB0_294
	s_lshl_b32 s0, 1, s23
	s_and_b32 s25, s0, 0x1405
	s_cmp_eq_u32 s25, 0
	s_cselect_b64 vcc, -1, 0
	v_cndmask_b32_e32 v36, v35, v34, vcc
	s_and_b32 s25, s0, 5
	v_pk_mul_f32 v[30:31], v[30:31], v[36:37] op_sel_hi:[1,0]
	v_pk_mul_f32 v[28:29], v[28:29], v[36:37] op_sel_hi:[1,0]
	v_pk_mul_f32 v[26:27], v[26:27], v[36:37] op_sel_hi:[1,0]
	s_cmp_eq_u32 s25, 0
	v_pk_mul_f32 v[24:25], v[24:25], v[36:37] op_sel_hi:[1,0]
	s_cbranch_scc1 .LBB0_324
	v_cvt_pk_bf16_f32 v36, v28, v29
	v_cvt_pk_bf16_f32 v37, v30, v31
	v_cvt_pk_bf16_f32 v38, v24, v25
	v_cvt_pk_bf16_f32 v39, v26, v27
	s_mov_b64 s[30:31], 0x900
	global_store_dwordx4 v[32:33], v[36:39], off
	s_and_b32 s0, s0, 0x5545
	s_cmp_eq_u32 s0, 0
	s_cbranch_scc1 .LBB0_293

; #define GAS_ __attribute__((address_space(1)))
; __device__ __forceinline__ unsigned pk2(float lo, float hi) { f32x2_t v = {lo, hi}; bf16x2_t b = __builtin_convertvector(v, bf16x2_t); return __builtin_bit_cast(unsigned, b); }
; __device__ __forceinline__ void rows_rstd(float (&rs)[2][4], const float* SS, int row0, int fq) {
;     ...
;         for (int m = 0; m < 4; ++m) { float s = (q[ai][m][0] + q[ai][m][1]) + (q[ai][m][2] + q[ai][m][3]); s += __shfl_xor(s, 16); s += __shfl_xor(s, 32);
;             rs[ai][m] = 1.0f / sqrtf(s * (1.0f / 1024.0f) + 1e-5f); }
;     __device__ __forceinline__ void operator()(const f32x4 (&acc)[2][2][4][2], const Unit& u, int wr, int wc, int fr, int fq) const {
;     ...
;                 const float rs = SS ? rsv[ai][m] : 1.0f;
; #pragma unroll
;                 for (int bj = 0; bj < 2; ++bj) {
;                     const int h = u.pn * 2 + bj;
;                     if (HM == 0 && col0 + bj * 128 >= 2072) continue;
;                     const float sc = ((scaleMask >> h) & 1u) ? rs * C2 : rs;
;                     f32x4 v0 = acc[ai][bj][m][0] * sc, v1 = acc[ai][bj][m][1] * sc;
;                     int off = bj * bjstep;
;                     if ((dualMask >> h) & 1u) { u32x4 w; w.x = pk2(v0[0], v0[1]); w.y = pk2(v0[2], v0[3]); w.z = pk2(v1[0], v1[1]); w.w = pk2(v1[2], v1[3]); *(GAS_ u32x4*)(rowp + off) = w; off += dualOff; }
.LBB0_299:
	s_or_b64 exec, exec, s[10:11]
	s_waitcnt lgkmcnt(0)
	v_add_f32_e32 v16, v185, v189
	v_fmamk_f32 v16, v16, 0x3a800000, v212
	v_rsq_f32_e32 v17, v16
	s_nop 0
	v_mul_f32_e32 v20, v16, v17
	v_fma_f32 v20, -v20, v17, 1.0
	v_mul_f32_e32 v19, 0.5, v17
	v_fma_f32 v18, v19, v20, v17
	s_nop 1
	v_mov_b64_e32 v[16:17], s[16:17]
	v_mad_i64_i32 v[16:17], s[10:11], v184, s53, v[16:17]
	v_lshl_add_u64 v[16:17], v[186:187], 1, v[16:17]
	v_mul_f32_e32 v19, 0x3e38aa3b, v18
	s_and_saveexec_b64 s[10:11], s[6:7]
	s_cbranch_execz .LBB0_304
	s_lshl_b32 s0, 1, s23
	s_and_b32 s6, s0, 0x1405
	s_cmp_eq_u32 s6, 0
	s_cselect_b64 vcc, -1, 0
	v_cndmask_b32_e32 v20, v19, v18, vcc
	s_and_b32 s6, s0, 5
	v_pk_mul_f32 v[14:15], v[14:15], v[20:21] op_sel_hi:[1,0]
	v_pk_mul_f32 v[12:13], v[12:13], v[20:21] op_sel_hi:[1,0]
	v_pk_mul_f32 v[10:11], v[10:11], v[20:21] op_sel_hi:[1,0]
	s_cmp_eq_u32 s6, 0
	v_pk_mul_f32 v[8:9], v[8:9], v[20:21] op_sel_hi:[1,0]
	s_cbranch_scc1 .LBB0_326
	v_cvt_pk_bf16_f32 v20, v12, v13
	v_cvt_pk_bf16_f32 v21, v14, v15
	v_cvt_pk_bf16_f32 v22, v8, v9
	v_cvt_pk_bf16_f32 v23, v10, v11
	s_mov_b64 s[6:7], 0x900
	global_store_dwordx4 v[16:17], v[20:23], off
	s_and_b32 s0, s0, 0x5545
	s_cmp_eq_u32 s0, 0
	s_cbranch_scc1 .LBB0_303

; #define GAS_ __attribute__((address_space(1)))
;     __device__ __forceinline__ void operator()(const f32x4 (&acc)[2][2][4][2], const Unit& u, int wr, int wc, int fr, int fq) const {
;     ...
;         for (int ai = 0; ai < 2; ++ai) {
;             f32x4 bs[4][2][2]; u32x4 bh[4][2];
; #pragma unroll
;             for (int m = 0; m < 4; ++m) { const size_t off = (size_t)(row0 + ai * 128 + m * 16) * ldc + col0;
; #pragma unroll
;                 for (int bj = 0; bj < 2; ++bj) {
;                     if (BASE_F32) { bs[m][bj][0] = *(const GAS_ f32x4*)(basef + off + bj * 128); bs[m][bj][1] = *(const GAS_ f32x4*)(basef + off + bj * 128 + 4); }
;                     else bh[m][bj] = *(const GAS_ u32x4*)(XB + off + bj * 128); } }
;             asm volatile("" ::: "memory");
; #pragma unroll
;             for (int m = 0; m < 4; ++m) {
;                 const size_t off = (size_t)(row0 + ai * 128 + m * 16) * ldc + col0;
;                 float ssq = 0.f;
; #pragma unroll
;                 for (int bj = 0; bj < 2; ++bj) {
;                     f32x4 b0, b1;
;                     if (BASE_F32) { b0 = bs[m][bj][0]; b1 = bs[m][bj][1]; }
;                     else { const u32x4 h = bh[m][bj];
;                         b0 = (f32x4){__builtin_bit_cast(float, h.x << 16), __builtin_bit_cast(float, h.x & 0xffff0000u), __builtin_bit_cast(float, h.y << 16), __builtin_bit_cast(float, h.y & 0xffff0000u)};
;                         b1 = (f32x4){__builtin_bit_cast(float, h.z << 16), __builtin_bit_cast(float, h.z & 0xffff0000u), __builtin_bit_cast(float, h.w << 16), __builtin_bit_cast(float, h.w & 0xffff0000u)}; }
;                     const f32x4 v0 = b0 + acc[ai][bj][m][0], v1 = b1 + acc[ai][bj][m][1];
;                     ssq += ((v0[0] * v0[0] + v0[1] * v0[1]) + (v0[2] * v0[2] + v0[3] * v0[3])) + ((v1[0] * v1[0] + v1[1] * v1[1]) + (v1[2] * v1[2] + v1[3] * v1[3]));
;                     u32x4 w; w.x = pk2(v0[0], v0[1]); w.y = pk2(v0[2], v0[3]); w.z = pk2(v1[0], v1[1]); w.w = pk2(v1[2], v1[3]); *(GAS_ u32x4*)(XB + off + bj * 128) = w;
;                 }
;                 ssq += __shfl_xor(ssq, 16); ssq += __shfl_xor(ssq, 32);
;                 if (fq == 0) *(GAS_ float*)(SS + (size_t)(row0 + ai * 128 + m * 16) * 16 + u.pn * 4 + wc) = ssq;
.LBB0_858:
	v_lshl_or_b32 v168, s0, 8, v182
	v_lshl_add_u32 v172, s26, 8, v180
	v_ashrrev_i32_e32 v169, 31, v168
	v_lshlrev_b64 v[198:199], 1, v[168:169]
	v_ashrrev_i32_e32 v173, 31, v172
	v_lshl_add_u64 v[170:171], s[10:11], 0, v[198:199]
	v_lshlrev_b64 v[200:201], 11, v[172:173]
	v_lshl_add_u64 v[128:129], v[170:171], 0, v[200:201]
	global_load_dwordx4 v[190:193], v[128:129], off
	global_load_dwordx4 v[194:197], v[128:129], off offset:256
	v_or_b32_e32 v178, 16, v172
	v_or_b32_e32 v176, 32, v172
	v_or_b32_e32 v174, 48, v172
	v_ashrrev_i32_e32 v179, 31, v178
	v_ashrrev_i32_e32 v177, 31, v176
	v_ashrrev_i32_e32 v175, 31, v174
	v_lshlrev_b64 v[128:129], 11, v[178:179]
	v_lshlrev_b64 v[130:131], 11, v[176:177]
	v_lshlrev_b64 v[132:133], 11, v[174:175]
	v_lshl_add_u64 v[128:129], v[170:171], 0, v[128:129]
	v_lshl_add_u64 v[130:131], v[170:171], 0, v[130:131]
	v_lshl_add_u64 v[188:189], v[170:171], 0, v[132:133]
	global_load_dwordx4 v[148:151], v[128:129], off
	global_load_dwordx4 v[144:147], v[128:129], off offset:256
	global_load_dwordx4 v[140:143], v[130:131], off
	global_load_dwordx4 v[136:139], v[130:131], off offset:256
	global_load_dwordx4 v[132:135], v[188:189], off
	s_nop 0
	global_load_dwordx4 v[128:131], v[188:189], off offset:256
	v_and_b32_e32 v188, 64, v186
	v_xor_b32_e32 v187, 16, v186
	v_add_u32_e32 v188, 64, v188
	v_xor_b32_e32 v189, 32, v186
	v_cmp_lt_i32_e32 vcc, v187, v188
	s_lshl_b32 s26, s0, 2
	s_ashr_i32 s27, s26, 31
	v_cndmask_b32_e32 v187, v186, v187, vcc
	v_cmp_lt_i32_e32 vcc, v189, v188
	v_lshlrev_b32_e32 v188, 2, v187
	s_waitcnt vmcnt(0)
	v_lshlrev_b32_e32 v202, 16, v190
	v_and_b32_e32 v203, 0xffff0000, v190
	v_lshlrev_b32_e32 v190, 16, v191
	v_and_b32_e32 v191, 0xffff0000, v191
	v_lshlrev_b32_e32 v206, 16, v192
	v_and_b32_e32 v207, 0xffff0000, v192
	v_lshlrev_b32_e32 v192, 16, v193
	v_and_b32_e32 v193, 0xffff0000, v193
	v_lshlrev_b32_e32 v208, 16, v194
	v_and_b32_e32 v209, 0xffff0000, v194
	v_lshlrev_b32_e32 v194, 16, v195
	v_and_b32_e32 v195, 0xffff0000, v195
	v_lshlrev_b32_e32 v210, 16, v196
	v_and_b32_e32 v211, 0xffff0000, v196
	v_lshlrev_b32_e32 v196, 16, v197
	v_and_b32_e32 v197, 0xffff0000, v197
	v_cndmask_b32_e32 v189, v186, v189, vcc
	v_pk_add_f32 v[126:127], v[126:127], v[190:191]
	v_pk_add_f32 v[124:125], v[124:125], v[202:203]
	v_pk_add_f32 v[122:123], v[122:123], v[192:193]
	v_pk_add_f32 v[120:121], v[120:121], v[206:207]
	v_pk_add_f32 v[118:119], v[118:119], v[194:195]
	v_pk_add_f32 v[116:117], v[116:117], v[208:209]
	v_pk_add_f32 v[190:191], v[114:115], v[196:197]
	v_pk_add_f32 v[192:193], v[112:113], v[210:211]
	v_lshlrev_b32_e32 v187, 2, v189
	v_mul_f32_e32 v189, v125, v125
	v_mul_f32_e32 v194, v127, v127
	v_mul_f32_e32 v195, v121, v121
	v_mul_f32_e32 v196, v123, v123
	v_cvt_pk_bf16_f32 v112, v124, v125
	v_cvt_pk_bf16_f32 v113, v126, v127
	v_cvt_pk_bf16_f32 v114, v120, v121
	v_cvt_pk_bf16_f32 v115, v122, v123
	v_mul_f32_e32 v121, v117, v117
	v_mul_f32_e32 v123, v119, v119
	v_mul_f32_e32 v125, v193, v193
	v_mul_f32_e32 v127, v191, v191
	v_fmac_f32_e32 v189, v124, v124
	v_fmac_f32_e32 v194, v126, v126
	v_fmac_f32_e32 v195, v120, v120
	v_fmac_f32_e32 v196, v122, v122
	v_fmac_f32_e32 v121, v116, v116
	v_fmac_f32_e32 v123, v118, v118
	v_fmac_f32_e32 v125, v192, v192
	v_fmac_f32_e32 v127, v190, v190
	v_add_f32_e32 v120, v189, v194
	v_add_f32_e32 v122, v195, v196
	v_add_f32_e32 v121, v121, v123
	v_add_f32_e32 v123, v125, v127
	v_add_f32_e32 v120, v120, v122
	v_add_f32_e32 v121, v121, v123
	v_add_f32_e32 v122, v120, v121
	v_mov_b32_e32 v123, v122
	s_nop 1
	v_permlane16_swap_b32_e32 v122, v123
	v_lshl_add_u64 v[120:121], s[10:11], 0, v[200:201]
	v_lshl_add_u64 v[120:121], v[120:121], 0, v[198:199]
	global_store_dwordx4 v[120:121], v[112:115], off
	s_waitcnt lgkmcnt(0)
	s_nop 0
	v_add_f32_e32 v112, v122, v123
	v_mov_b32_e32 v113, v112
	s_nop 1
	v_permlane32_swap_b32_e32 v112, v113
	v_cvt_pk_bf16_f32 v114, v116, v117
	v_cvt_pk_bf16_f32 v115, v118, v119
	v_cvt_pk_bf16_f32 v116, v192, v193
	v_cvt_pk_bf16_f32 v117, v190, v191
	global_store_dwordx4 v[120:121], v[114:117], off offset:256
	s_and_saveexec_b64 s[28:29], s[6:7]
	s_cbranch_execz .LBB0_860
	v_lshlrev_b64 v[114:115], 6, v[172:173]
	v_lshl_add_u64 v[114:115], s[12:13], 0, v[114:115]
	v_lshl_add_u64 v[114:115], s[26:27], 2, v[114:115]
	s_lshl_b32 s0, s43, 2
	v_lshl_add_u64 v[114:115], v[114:115], 0, s[0:1]
	s_waitcnt lgkmcnt(0)
	v_add_f32_e32 v112, v112, v113
	global_store_dword v[114:115], v112, off
; #define GAS_ __attribute__((address_space(1)))
; __device__ __forceinline__ unsigned pk2(float lo, float hi) { f32x2_t v = {lo, hi}; bf16x2_t b = __builtin_convertvector(v, bf16x2_t); return __builtin_bit_cast(unsigned, b); }
;     __device__ __forceinline__ void operator()(const f32x4 (&acc)[2][2][4][2], const Unit& u, int wr, int wc, int fr, int fq) const {
;     ...
;             for (int m = 0; m < 4; ++m) {
;                 const size_t off = (size_t)(row0 + ai * 128 + m * 16) * ldc + col0;
;                 float ssq = 0.f;
; #pragma unroll
;                 for (int bj = 0; bj < 2; ++bj) {
;                     f32x4 b0, b1;
;                     if (BASE_F32) { b0 = bs[m][bj][0]; b1 = bs[m][bj][1]; }
;                     else { const u32x4 h = bh[m][bj];
;                         b0 = (f32x4){__builtin_bit_cast(float, h.x << 16), __builtin_bit_cast(float, h.x & 0xffff0000u), __builtin_bit_cast(float, h.y << 16), __builtin_bit_cast(float, h.y & 0xffff0000u)};
;                         b1 = (f32x4){__builtin_bit_cast(float, h.z << 16), __builtin_bit_cast(float, h.z & 0xffff0000u), __builtin_bit_cast(float, h.w << 16), __builtin_bit_cast(float, h.w & 0xffff0000u)}; }
;                     const f32x4 v0 = b0 + acc[ai][bj][m][0], v1 = b1 + acc[ai][bj][m][1];
;                     ssq += ((v0[0] * v0[0] + v0[1] * v0[1]) + (v0[2] * v0[2] + v0[3] * v0[3])) + ((v1[0] * v1[0] + v1[1] * v1[1]) + (v1[2] * v1[2] + v1[3] * v1[3]));
;                     u32x4 w; w.x = pk2(v0[0], v0[1]); w.y = pk2(v0[2], v0[3]); w.z = pk2(v1[0], v1[1]); w.w = pk2(v1[2], v1[3]); *(GAS_ u32x4*)(XB + off + bj * 128) = w;
;                 }
;                 ssq += __shfl_xor(ssq, 16); ssq += __shfl_xor(ssq, 32);
;                 if (fq == 0) *(GAS_ float*)(SS + (size_t)(row0 + ai * 128 + m * 16) * 16 + u.pn * 4 + wc) = ssq;
;             }
.LBB0_860:
	s_or_b64 exec, exec, s[28:29]
	v_lshlrev_b32_e32 v114, 16, v148
	v_and_b32_e32 v115, 0xffff0000, v148
	v_lshlrev_b32_e32 v116, 16, v149
	v_and_b32_e32 v117, 0xffff0000, v149
	v_lshlrev_b32_e32 v118, 16, v150
	v_and_b32_e32 v119, 0xffff0000, v150
	v_lshlrev_b32_e32 v120, 16, v151
	v_and_b32_e32 v121, 0xffff0000, v151
	v_pk_add_f32 v[110:111], v[110:111], v[116:117]
	v_pk_add_f32 v[108:109], v[108:109], v[114:115]
	v_pk_add_f32 v[114:115], v[106:107], v[120:121]
	v_pk_add_f32 v[106:107], v[104:105], v[118:119]
	v_mul_f32_e32 v104, v109, v109
	v_mul_f32_e32 v105, v111, v111
	v_fmac_f32_e32 v104, v108, v108
	v_fmac_f32_e32 v105, v110, v110
	v_add_f32_e32 v104, v104, v105
	v_mul_f32_e32 v105, v107, v107
	v_mul_f32_e32 v116, v115, v115
	v_fmac_f32_e32 v105, v106, v106
	v_fmac_f32_e32 v116, v114, v114
	v_add_f32_e32 v105, v105, v116
	v_add_f32_e32 v118, v104, v105
	v_cvt_pk_bf16_f32 v104, v108, v109
	v_cvt_pk_bf16_f32 v105, v110, v111
	v_lshlrev_b32_e32 v108, 16, v144
	v_and_b32_e32 v109, 0xffff0000, v144
	v_lshlrev_b32_e32 v110, 16, v145
	v_and_b32_e32 v111, 0xffff0000, v145
	v_cvt_pk_bf16_f32 v106, v106, v107
	v_cvt_pk_bf16_f32 v107, v114, v115
	v_lshlrev_b32_e32 v114, 16, v146
	v_and_b32_e32 v115, 0xffff0000, v146
	v_pk_add_f32 v[102:103], v[102:103], v[110:111]
	v_pk_add_f32 v[100:101], v[100:101], v[108:109]
	v_lshlrev_b32_e32 v116, 16, v147
	v_and_b32_e32 v117, 0xffff0000, v147
	v_pk_add_f32 v[110:111], v[96:97], v[114:115]
	v_mul_f32_e32 v96, v101, v101
	v_mul_f32_e32 v97, v103, v103
	v_pk_add_f32 v[108:109], v[98:99], v[116:117]
	v_fmac_f32_e32 v96, v100, v100
	v_fmac_f32_e32 v97, v102, v102
	v_add_f32_e32 v96, v96, v97
	v_mul_f32_e32 v97, v111, v111
	v_mul_f32_e32 v98, v109, v109
	v_fmac_f32_e32 v97, v110, v110
	v_fmac_f32_e32 v98, v108, v108
	v_add_f32_e32 v97, v97, v98
	v_add_f32_e32 v96, v96, v97
	v_add_f32_e32 v99, v118, v96
	v_mov_b32_e32 v114, v99
	s_nop 1
	v_permlane16_swap_b32_e32 v99, v114
	s_waitcnt lgkmcnt(1)
	v_lshlrev_b64 v[112:113], 10, v[178:179]
	v_lshl_add_u64 v[96:97], v[112:113], 1, s[10:11]
	v_lshl_add_u64 v[112:113], v[168:169], 1, v[96:97]
	v_cvt_pk_bf16_f32 v98, v100, v101
	s_waitcnt lgkmcnt(0)
	v_add_f32_e32 v96, v99, v114
	v_mov_b32_e32 v97, v96
	s_nop 1
	v_permlane32_swap_b32_e32 v96, v97
	v_cvt_pk_bf16_f32 v99, v102, v103
	v_cvt_pk_bf16_f32 v100, v110, v111
	v_cvt_pk_bf16_f32 v101, v108, v109
	global_store_dwordx4 v[112:113], v[104:107], off
	global_store_dwordx4 v[112:113], v[98:101], off offset:256
	s_and_saveexec_b64 s[28:29], s[6:7]
	s_cbranch_execz .LBB0_862
	v_lshlrev_b64 v[98:99], 6, v[178:179]
	v_lshl_add_u64 v[98:99], s[12:13], 0, v[98:99]
	v_lshl_add_u64 v[98:99], s[26:27], 2, v[98:99]
	s_lshl_b32 s0, s43, 2
	v_lshl_add_u64 v[98:99], v[98:99], 0, s[0:1]
	s_waitcnt lgkmcnt(0)
	v_add_f32_e32 v96, v96, v97
	global_store_dword v[98:99], v96, off
.LBB0_862:
	s_or_b64 exec, exec, s[28:29]
	v_lshlrev_b32_e32 v98, 16, v140
	v_and_b32_e32 v99, 0xffff0000, v140
	v_lshlrev_b32_e32 v100, 16, v141
	v_and_b32_e32 v101, 0xffff0000, v141
	v_lshlrev_b32_e32 v102, 16, v142
	v_and_b32_e32 v103, 0xffff0000, v142
	v_lshlrev_b32_e32 v104, 16, v143
	v_and_b32_e32 v105, 0xffff0000, v143
	v_pk_add_f32 v[94:95], v[94:95], v[100:101]
	v_pk_add_f32 v[92:93], v[92:93], v[98:99]
	v_pk_add_f32 v[98:99], v[90:91], v[104:105]
	v_pk_add_f32 v[90:91], v[88:89], v[102:103]
	v_mul_f32_e32 v88, v93, v93
	v_mul_f32_e32 v89, v95, v95
	v_fmac_f32_e32 v88, v92, v92
	v_fmac_f32_e32 v89, v94, v94
	v_add_f32_e32 v88, v88, v89
	v_mul_f32_e32 v89, v91, v91
	v_mul_f32_e32 v100, v99, v99
	v_fmac_f32_e32 v89, v90, v90
	v_fmac_f32_e32 v100, v98, v98
	v_add_f32_e32 v89, v89, v100
	v_add_f32_e32 v102, v88, v89
	v_cvt_pk_bf16_f32 v88, v92, v93
	v_cvt_pk_bf16_f32 v89, v94, v95
	v_lshlrev_b32_e32 v92, 16, v136
	v_and_b32_e32 v93, 0xffff0000, v136
	v_lshlrev_b32_e32 v94, 16, v137
	v_and_b32_e32 v95, 0xffff0000, v137
	v_cvt_pk_bf16_f32 v90, v90, v91
	v_cvt_pk_bf16_f32 v91, v98, v99
	v_lshlrev_b32_e32 v98, 16, v138
	v_and_b32_e32 v99, 0xffff0000, v138
	v_pk_add_f32 v[86:87], v[86:87], v[94:95]
	v_pk_add_f32 v[84:85], v[84:85], v[92:93]
	v_lshlrev_b32_e32 v100, 16, v139
	v_and_b32_e32 v101, 0xffff0000, v139
	v_pk_add_f32 v[94:95], v[80:81], v[98:99]
	v_mul_f32_e32 v80, v85, v85
	v_mul_f32_e32 v81, v87, v87
	v_pk_add_f32 v[92:93], v[82:83], v[100:101]
	v_fmac_f32_e32 v80, v84, v84
	v_fmac_f32_e32 v81, v86, v86
	v_add_f32_e32 v80, v80, v81
	v_mul_f32_e32 v81, v95, v95
	v_mul_f32_e32 v82, v93, v93
	v_fmac_f32_e32 v81, v94, v94
	v_fmac_f32_e32 v82, v92, v92
	v_add_f32_e32 v81, v81, v82
	v_add_f32_e32 v80, v80, v81
	v_add_f32_e32 v83, v102, v80
	v_mov_b32_e32 v98, v83
	s_nop 1
	v_permlane16_swap_b32_e32 v83, v98
	s_waitcnt lgkmcnt(1)
	v_lshlrev_b64 v[96:97], 10, v[176:177]
	v_lshl_add_u64 v[80:81], v[96:97], 1, s[10:11]
	v_lshl_add_u64 v[96:97], v[168:169], 1, v[80:81]
	v_cvt_pk_bf16_f32 v82, v84, v85
	s_waitcnt lgkmcnt(0)
	v_add_f32_e32 v80, v83, v98
	v_mov_b32_e32 v81, v80
	s_nop 1
	v_permlane32_swap_b32_e32 v80, v81
	v_cvt_pk_bf16_f32 v83, v86, v87
	v_cvt_pk_bf16_f32 v84, v94, v95
	v_cvt_pk_bf16_f32 v85, v92, v93
	global_store_dwordx4 v[96:97], v[88:91], off
	global_store_dwordx4 v[96:97], v[82:85], off offset:256
	s_and_saveexec_b64 s[28:29], s[6:7]
	s_cbranch_execz .LBB0_864
	v_lshlrev_b64 v[82:83], 6, v[176:177]
	v_lshl_add_u64 v[82:83], s[12:13], 0, v[82:83]
	v_lshl_add_u64 v[82:83], s[26:27], 2, v[82:83]
	s_lshl_b32 s0, s43, 2
	v_lshl_add_u64 v[82:83], v[82:83], 0, s[0:1]
	s_waitcnt lgkmcnt(0)
	v_add_f32_e32 v80, v80, v81
	global_store_dword v[82:83], v80, off
; #define GAS_ __attribute__((address_space(1)))
;     __device__ __forceinline__ void operator()(const f32x4 (&acc)[2][2][4][2], const Unit& u, int wr, int wc, int fr, int fq) const {
;     ...
;         for (int ai = 0; ai < 2; ++ai) {
;             f32x4 bs[4][2][2]; u32x4 bh[4][2];
; #pragma unroll
;             for (int m = 0; m < 4; ++m) { const size_t off = (size_t)(row0 + ai * 128 + m * 16) * ldc + col0;
; #pragma unroll
;                 for (int bj = 0; bj < 2; ++bj) {
;                     if (BASE_F32) { bs[m][bj][0] = *(const GAS_ f32x4*)(basef + off + bj * 128); bs[m][bj][1] = *(const GAS_ f32x4*)(basef + off + bj * 128 + 4); }
;                     else bh[m][bj] = *(const GAS_ u32x4*)(XB + off + bj * 128); } }
;             asm volatile("" ::: "memory");
; #pragma unroll
;             for (int m = 0; m < 4; ++m) {
;                 const size_t off = (size_t)(row0 + ai * 128 + m * 16) * ldc + col0;
;                 float ssq = 0.f;
; #pragma unroll
;                 for (int bj = 0; bj < 2; ++bj) {
;                     f32x4 b0, b1;
;                     if (BASE_F32) { b0 = bs[m][bj][0]; b1 = bs[m][bj][1]; }
;                     else { const u32x4 h = bh[m][bj];
;                         b0 = (f32x4){__builtin_bit_cast(float, h.x << 16), __builtin_bit_cast(float, h.x & 0xffff0000u), __builtin_bit_cast(float, h.y << 16), __builtin_bit_cast(float, h.y & 0xffff0000u)};
;                         b1 = (f32x4){__builtin_bit_cast(float, h.z << 16), __builtin_bit_cast(float, h.z & 0xffff0000u), __builtin_bit_cast(float, h.w << 16), __builtin_bit_cast(float, h.w & 0xffff0000u)}; }
;                     const f32x4 v0 = b0 + acc[ai][bj][m][0], v1 = b1 + acc[ai][bj][m][1];
;                     ssq += ((v0[0] * v0[0] + v0[1] * v0[1]) + (v0[2] * v0[2] + v0[3] * v0[3])) + ((v1[0] * v1[0] + v1[1] * v1[1]) + (v1[2] * v1[2] + v1[3] * v1[3]));
;                     u32x4 w; w.x = pk2(v0[0], v0[1]); w.y = pk2(v0[2], v0[3]); w.z = pk2(v1[0], v1[1]); w.w = pk2(v1[2], v1[3]); *(GAS_ u32x4*)(XB + off + bj * 128) = w;
;                 }
;                 ssq += __shfl_xor(ssq, 16); ssq += __shfl_xor(ssq, 32);
;                 if (fq == 0) *(GAS_ float*)(SS + (size_t)(row0 + ai * 128 + m * 16) * 16 + u.pn * 4 + wc) = ssq;
;             }
.LBB0_864:
	s_or_b64 exec, exec, s[28:29]
	v_lshlrev_b32_e32 v82, 16, v132
	v_and_b32_e32 v83, 0xffff0000, v132
	v_lshlrev_b32_e32 v84, 16, v133
	v_and_b32_e32 v85, 0xffff0000, v133
	v_lshlrev_b32_e32 v86, 16, v134
	v_and_b32_e32 v87, 0xffff0000, v134
	v_lshlrev_b32_e32 v88, 16, v135
	v_and_b32_e32 v89, 0xffff0000, v135
	v_pk_add_f32 v[78:79], v[78:79], v[84:85]
	v_pk_add_f32 v[76:77], v[76:77], v[82:83]
	v_pk_add_f32 v[82:83], v[74:75], v[88:89]
	v_pk_add_f32 v[74:75], v[72:73], v[86:87]
	v_mul_f32_e32 v72, v77, v77
	v_mul_f32_e32 v73, v79, v79
	v_fmac_f32_e32 v72, v76, v76
	v_fmac_f32_e32 v73, v78, v78
	v_add_f32_e32 v72, v72, v73
	v_mul_f32_e32 v73, v75, v75
	v_mul_f32_e32 v84, v83, v83
	v_fmac_f32_e32 v73, v74, v74
	v_fmac_f32_e32 v84, v82, v82
	v_add_f32_e32 v73, v73, v84
	v_add_f32_e32 v86, v72, v73
	v_cvt_pk_bf16_f32 v72, v76, v77
	v_cvt_pk_bf16_f32 v73, v78, v79
	v_lshlrev_b32_e32 v76, 16, v128
	v_and_b32_e32 v77, 0xffff0000, v128
	v_lshlrev_b32_e32 v78, 16, v129
	v_and_b32_e32 v79, 0xffff0000, v129
	v_cvt_pk_bf16_f32 v74, v74, v75
	v_cvt_pk_bf16_f32 v75, v82, v83
	v_lshlrev_b32_e32 v82, 16, v130
	v_and_b32_e32 v83, 0xffff0000, v130
	v_pk_add_f32 v[70:71], v[70:71], v[78:79]
	v_pk_add_f32 v[68:69], v[68:69], v[76:77]
	v_lshlrev_b32_e32 v84, 16, v131
	v_and_b32_e32 v85, 0xffff0000, v131
	v_pk_add_f32 v[78:79], v[64:65], v[82:83]
	v_mul_f32_e32 v64, v69, v69
	v_mul_f32_e32 v65, v71, v71
	v_pk_add_f32 v[76:77], v[66:67], v[84:85]
	v_fmac_f32_e32 v64, v68, v68
	v_fmac_f32_e32 v65, v70, v70
	v_add_f32_e32 v64, v64, v65
	v_mul_f32_e32 v65, v79, v79
	v_mul_f32_e32 v66, v77, v77
	v_fmac_f32_e32 v65, v78, v78
	v_fmac_f32_e32 v66, v76, v76
	v_add_f32_e32 v65, v65, v66
	v_add_f32_e32 v64, v64, v65
	v_add_f32_e32 v67, v86, v64
	v_mov_b32_e32 v82, v67
	s_nop 1
	v_permlane16_swap_b32_e32 v67, v82
	s_waitcnt lgkmcnt(1)
	v_lshlrev_b64 v[80:81], 10, v[174:175]
	v_lshl_add_u64 v[64:65], v[80:81], 1, s[10:11]
	v_lshl_add_u64 v[80:81], v[168:169], 1, v[64:65]
	v_cvt_pk_bf16_f32 v66, v68, v69
	s_waitcnt lgkmcnt(0)
	v_add_f32_e32 v64, v67, v82
	v_mov_b32_e32 v65, v64
	s_nop 1
	v_permlane32_swap_b32_e32 v64, v65
	v_cvt_pk_bf16_f32 v67, v70, v71
	v_cvt_pk_bf16_f32 v68, v78, v79
	v_cvt_pk_bf16_f32 v69, v76, v77
	global_store_dwordx4 v[80:81], v[72:75], off
	global_store_dwordx4 v[80:81], v[66:69], off offset:256
	s_and_saveexec_b64 s[28:29], s[6:7]
	s_cbranch_execz .LBB0_866
	v_lshlrev_b64 v[66:67], 6, v[174:175]
	v_lshl_add_u64 v[66:67], s[12:13], 0, v[66:67]
	v_lshl_add_u64 v[66:67], s[26:27], 2, v[66:67]
	s_lshl_b32 s0, s43, 2
	v_lshl_add_u64 v[66:67], v[66:67], 0, s[0:1]
	s_waitcnt lgkmcnt(0)
	v_add_f32_e32 v64, v64, v65
	global_store_dword v[66:67], v64, off
.LBB0_866:
	s_or_b64 exec, exec, s[28:29]
	v_add_u32_e32 v94, 0x80, v172
	v_ashrrev_i32_e32 v95, 31, v94
	v_lshlrev_b64 v[104:105], 11, v[94:95]
	s_waitcnt lgkmcnt(0)
	v_lshl_add_u64 v[64:65], v[170:171], 0, v[104:105]
	global_load_dwordx4 v[96:99], v[64:65], off
	global_load_dwordx4 v[100:103], v[64:65], off offset:256
	v_add_u32_e32 v92, 0x90, v172
	v_add_u32_e32 v90, 0xa0, v172
	v_add_u32_e32 v88, 0xb0, v172
	v_ashrrev_i32_e32 v93, 31, v92
	v_ashrrev_i32_e32 v91, 31, v90
	v_ashrrev_i32_e32 v89, 31, v88
	v_lshlrev_b64 v[64:65], 11, v[92:93]
	v_lshlrev_b64 v[66:67], 11, v[90:91]
	v_lshlrev_b64 v[68:69], 11, v[88:89]
	v_lshl_add_u64 v[64:65], v[170:171], 0, v[64:65]
	v_lshl_add_u64 v[66:67], v[170:171], 0, v[66:67]
	v_lshl_add_u64 v[106:107], v[170:171], 0, v[68:69]
	global_load_dwordx4 v[84:87], v[64:65], off
	global_load_dwordx4 v[80:83], v[64:65], off offset:256
	global_load_dwordx4 v[76:79], v[66:67], off
	global_load_dwordx4 v[72:75], v[66:67], off offset:256
	global_load_dwordx4 v[68:71], v[106:107], off
	s_nop 0
	global_load_dwordx4 v[64:67], v[106:107], off offset:256
	s_waitcnt vmcnt(7)
	v_lshlrev_b32_e32 v106, 16, v96
	v_and_b32_e32 v107, 0xffff0000, v96
	v_lshlrev_b32_e32 v96, 16, v97
	v_and_b32_e32 v97, 0xffff0000, v97
	v_lshlrev_b32_e32 v108, 16, v98
	v_and_b32_e32 v109, 0xffff0000, v98
	v_lshlrev_b32_e32 v98, 16, v99
	v_and_b32_e32 v99, 0xffff0000, v99
	s_waitcnt vmcnt(6)
	v_lshlrev_b32_e32 v110, 16, v100
	v_and_b32_e32 v111, 0xffff0000, v100
	v_lshlrev_b32_e32 v100, 16, v101
	v_and_b32_e32 v101, 0xffff0000, v101
	v_lshlrev_b32_e32 v112, 16, v102
	v_and_b32_e32 v113, 0xffff0000, v102
	v_lshlrev_b32_e32 v102, 16, v103
	v_and_b32_e32 v103, 0xffff0000, v103
	v_pk_add_f32 v[62:63], v[62:63], v[96:97]
	v_pk_add_f32 v[60:61], v[60:61], v[106:107]
	v_pk_add_f32 v[58:59], v[58:59], v[98:99]
	v_pk_add_f32 v[56:57], v[56:57], v[108:109]
	v_pk_add_f32 v[54:55], v[54:55], v[100:101]
	v_pk_add_f32 v[52:53], v[52:53], v[110:111]
	v_pk_add_f32 v[96:97], v[50:51], v[102:103]
	v_pk_add_f32 v[98:99], v[48:49], v[112:113]
	v_mul_f32_e32 v100, v61, v61
	v_mul_f32_e32 v101, v63, v63
	v_mul_f32_e32 v102, v57, v57
	v_mul_f32_e32 v103, v59, v59
	v_cvt_pk_bf16_f32 v48, v60, v61
	v_cvt_pk_bf16_f32 v49, v62, v63
	v_cvt_pk_bf16_f32 v50, v56, v57
	v_cvt_pk_bf16_f32 v51, v58, v59
	v_mul_f32_e32 v57, v53, v53
	v_mul_f32_e32 v59, v55, v55
	v_mul_f32_e32 v61, v99, v99
	v_mul_f32_e32 v63, v97, v97
	v_fmac_f32_e32 v100, v60, v60
	v_fmac_f32_e32 v101, v62, v62
	v_fmac_f32_e32 v102, v56, v56
	v_fmac_f32_e32 v103, v58, v58
	v_fmac_f32_e32 v57, v52, v52
	v_fmac_f32_e32 v59, v54, v54
	v_fmac_f32_e32 v61, v98, v98
	v_fmac_f32_e32 v63, v96, v96
	v_add_f32_e32 v56, v100, v101
	v_add_f32_e32 v58, v102, v103
	v_add_f32_e32 v57, v57, v59
	v_add_f32_e32 v59, v61, v63
	v_add_f32_e32 v56, v56, v58
	v_add_f32_e32 v57, v57, v59
	v_add_f32_e32 v58, v56, v57
	v_mov_b32_e32 v59, v58
	s_nop 1
	v_permlane16_swap_b32_e32 v58, v59
	v_lshl_add_u64 v[56:57], s[10:11], 0, v[104:105]
	v_lshl_add_u64 v[56:57], v[168:169], 1, v[56:57]
	global_store_dwordx4 v[56:57], v[48:51], off
	s_waitcnt lgkmcnt(0)
	s_nop 0
	v_add_f32_e32 v48, v58, v59
	v_mov_b32_e32 v49, v48
	s_nop 1
	v_permlane32_swap_b32_e32 v48, v49
	v_cvt_pk_bf16_f32 v50, v52, v53
	v_cvt_pk_bf16_f32 v51, v54, v55
	v_cvt_pk_bf16_f32 v52, v98, v99
	v_cvt_pk_bf16_f32 v53, v96, v97
	global_store_dwordx4 v[56:57], v[50:53], off offset:256
	s_and_saveexec_b64 s[28:29], s[6:7]
	s_cbranch_execz .LBB0_868
	v_lshlrev_b64 v[50:51], 6, v[94:95]
	v_lshl_add_u64 v[50:51], s[12:13], 0, v[50:51]
	v_lshl_add_u64 v[50:51], s[26:27], 2, v[50:51]
	s_lshl_b32 s0, s43, 2
	v_lshl_add_u64 v[50:51], v[50:51], 0, s[0:1]
	s_waitcnt lgkmcnt(0)
	v_add_f32_e32 v48, v48, v49
	global_store_dword v[50:51], v48, off
; #define GAS_ __attribute__((address_space(1)))
; __device__ __forceinline__ unsigned pk2(float lo, float hi) { f32x2_t v = {lo, hi}; bf16x2_t b = __builtin_convertvector(v, bf16x2_t); return __builtin_bit_cast(unsigned, b); }
;     __device__ __forceinline__ void operator()(const f32x4 (&acc)[2][2][4][2], const Unit& u, int wr, int wc, int fr, int fq) const {
;     ...
;                 for (int bj = 0; bj < 2; ++bj) {
;                     f32x4 b0, b1;
;                     if (BASE_F32) { b0 = bs[m][bj][0]; b1 = bs[m][bj][1]; }
;                     else { const u32x4 h = bh[m][bj];
;                         b0 = (f32x4){__builtin_bit_cast(float, h.x << 16), __builtin_bit_cast(float, h.x & 0xffff0000u), __builtin_bit_cast(float, h.y << 16), __builtin_bit_cast(float, h.y & 0xffff0000u)};
;                         b1 = (f32x4){__builtin_bit_cast(float, h.z << 16), __builtin_bit_cast(float, h.z & 0xffff0000u), __builtin_bit_cast(float, h.w << 16), __builtin_bit_cast(float, h.w & 0xffff0000u)}; }
;                     const f32x4 v0 = b0 + acc[ai][bj][m][0], v1 = b1 + acc[ai][bj][m][1];
;                     ssq += ((v0[0] * v0[0] + v0[1] * v0[1]) + (v0[2] * v0[2] + v0[3] * v0[3])) + ((v1[0] * v1[0] + v1[1] * v1[1]) + (v1[2] * v1[2] + v1[3] * v1[3]));
;                     u32x4 w; w.x = pk2(v0[0], v0[1]); w.y = pk2(v0[2], v0[3]); w.z = pk2(v1[0], v1[1]); w.w = pk2(v1[2], v1[3]); *(GAS_ u32x4*)(XB + off + bj * 128) = w;
;                 }
;                 ssq += __shfl_xor(ssq, 16); ssq += __shfl_xor(ssq, 32);
;                 if (fq == 0) *(GAS_ float*)(SS + (size_t)(row0 + ai * 128 + m * 16) * 16 + u.pn * 4 + wc) = ssq;
.LBB0_868:
	s_or_b64 exec, exec, s[28:29]
	s_waitcnt vmcnt(7)
	v_lshlrev_b32_e32 v50, 16, v84
	v_and_b32_e32 v51, 0xffff0000, v84
	v_lshlrev_b32_e32 v52, 16, v85
	v_and_b32_e32 v53, 0xffff0000, v85
	v_lshlrev_b32_e32 v54, 16, v86
	v_and_b32_e32 v55, 0xffff0000, v86
	v_lshlrev_b32_e32 v56, 16, v87
	v_and_b32_e32 v57, 0xffff0000, v87
	v_pk_add_f32 v[46:47], v[46:47], v[52:53]
	v_pk_add_f32 v[44:45], v[44:45], v[50:51]
	v_pk_add_f32 v[50:51], v[42:43], v[56:57]
	v_pk_add_f32 v[42:43], v[40:41], v[54:55]
	v_mul_f32_e32 v40, v45, v45
	v_mul_f32_e32 v41, v47, v47
	v_fmac_f32_e32 v40, v44, v44
	v_fmac_f32_e32 v41, v46, v46
	v_add_f32_e32 v40, v40, v41
	v_mul_f32_e32 v41, v43, v43
	v_mul_f32_e32 v52, v51, v51
	v_fmac_f32_e32 v41, v42, v42
	v_fmac_f32_e32 v52, v50, v50
	v_add_f32_e32 v41, v41, v52
	v_add_f32_e32 v54, v40, v41
	v_cvt_pk_bf16_f32 v40, v44, v45
	v_cvt_pk_bf16_f32 v41, v46, v47
	s_waitcnt vmcnt(6)
	v_lshlrev_b32_e32 v44, 16, v80
	v_and_b32_e32 v45, 0xffff0000, v80
	v_lshlrev_b32_e32 v46, 16, v81
	v_and_b32_e32 v47, 0xffff0000, v81
	v_cvt_pk_bf16_f32 v42, v42, v43
	v_cvt_pk_bf16_f32 v43, v50, v51
	v_lshlrev_b32_e32 v50, 16, v82
	v_and_b32_e32 v51, 0xffff0000, v82
	v_pk_add_f32 v[38:39], v[38:39], v[46:47]
	v_pk_add_f32 v[36:37], v[36:37], v[44:45]
	v_lshlrev_b32_e32 v52, 16, v83
	v_and_b32_e32 v53, 0xffff0000, v83
	v_pk_add_f32 v[46:47], v[32:33], v[50:51]
	v_mul_f32_e32 v32, v37, v37
	v_mul_f32_e32 v33, v39, v39
	v_pk_add_f32 v[44:45], v[34:35], v[52:53]
	v_fmac_f32_e32 v32, v36, v36
	v_fmac_f32_e32 v33, v38, v38
	v_add_f32_e32 v32, v32, v33
	v_mul_f32_e32 v33, v47, v47
	v_mul_f32_e32 v34, v45, v45
	v_fmac_f32_e32 v33, v46, v46
	v_fmac_f32_e32 v34, v44, v44
	v_add_f32_e32 v33, v33, v34
	v_add_f32_e32 v32, v32, v33
	v_add_f32_e32 v35, v54, v32
	v_mov_b32_e32 v50, v35
	s_nop 1
	v_permlane16_swap_b32_e32 v35, v50
	s_waitcnt lgkmcnt(1)
	v_lshlrev_b64 v[48:49], 10, v[92:93]
	v_lshl_add_u64 v[32:33], v[48:49], 1, s[10:11]
	v_lshl_add_u64 v[48:49], v[168:169], 1, v[32:33]
	v_cvt_pk_bf16_f32 v34, v36, v37
	s_waitcnt lgkmcnt(0)
	v_add_f32_e32 v32, v35, v50
	v_mov_b32_e32 v33, v32
	s_nop 1
	v_permlane32_swap_b32_e32 v32, v33
	v_cvt_pk_bf16_f32 v35, v38, v39
	v_cvt_pk_bf16_f32 v36, v46, v47
	v_cvt_pk_bf16_f32 v37, v44, v45
	global_store_dwordx4 v[48:49], v[40:43], off
	global_store_dwordx4 v[48:49], v[34:37], off offset:256
	s_and_saveexec_b64 s[28:29], s[6:7]
	s_cbranch_execz .LBB0_870
	v_lshlrev_b64 v[34:35], 6, v[92:93]
	v_lshl_add_u64 v[34:35], s[12:13], 0, v[34:35]
	v_lshl_add_u64 v[34:35], s[26:27], 2, v[34:35]
	s_lshl_b32 s0, s43, 2
	v_lshl_add_u64 v[34:35], v[34:35], 0, s[0:1]
	s_waitcnt lgkmcnt(0)
	v_add_f32_e32 v32, v32, v33
	global_store_dword v[34:35], v32, off
; #define GAS_ __attribute__((address_space(1)))
; __device__ __forceinline__ unsigned pk2(float lo, float hi) { f32x2_t v = {lo, hi}; bf16x2_t b = __builtin_convertvector(v, bf16x2_t); return __builtin_bit_cast(unsigned, b); }
;     __device__ __forceinline__ void operator()(const f32x4 (&acc)[2][2][4][2], const Unit& u, int wr, int wc, int fr, int fq) const {
;     ...
;                 for (int bj = 0; bj < 2; ++bj) {
;                     f32x4 b0, b1;
;                     if (BASE_F32) { b0 = bs[m][bj][0]; b1 = bs[m][bj][1]; }
;                     else { const u32x4 h = bh[m][bj];
;                         b0 = (f32x4){__builtin_bit_cast(float, h.x << 16), __builtin_bit_cast(float, h.x & 0xffff0000u), __builtin_bit_cast(float, h.y << 16), __builtin_bit_cast(float, h.y & 0xffff0000u)};
;                         b1 = (f32x4){__builtin_bit_cast(float, h.z << 16), __builtin_bit_cast(float, h.z & 0xffff0000u), __builtin_bit_cast(float, h.w << 16), __builtin_bit_cast(float, h.w & 0xffff0000u)}; }
;                     const f32x4 v0 = b0 + acc[ai][bj][m][0], v1 = b1 + acc[ai][bj][m][1];
;                     ssq += ((v0[0] * v0[0] + v0[1] * v0[1]) + (v0[2] * v0[2] + v0[3] * v0[3])) + ((v1[0] * v1[0] + v1[1] * v1[1]) + (v1[2] * v1[2] + v1[3] * v1[3]));
;                     u32x4 w; w.x = pk2(v0[0], v0[1]); w.y = pk2(v0[2], v0[3]); w.z = pk2(v1[0], v1[1]); w.w = pk2(v1[2], v1[3]); *(GAS_ u32x4*)(XB + off + bj * 128) = w;
;                 }
;                 ssq += __shfl_xor(ssq, 16); ssq += __shfl_xor(ssq, 32);
;                 if (fq == 0) *(GAS_ float*)(SS + (size_t)(row0 + ai * 128 + m * 16) * 16 + u.pn * 4 + wc) = ssq;
.LBB0_870:
	s_or_b64 exec, exec, s[28:29]
	s_waitcnt vmcnt(7)
	v_lshlrev_b32_e32 v34, 16, v76
	v_and_b32_e32 v35, 0xffff0000, v76
	v_lshlrev_b32_e32 v36, 16, v77
	v_and_b32_e32 v37, 0xffff0000, v77
	v_lshlrev_b32_e32 v38, 16, v78
	v_and_b32_e32 v39, 0xffff0000, v78
	v_lshlrev_b32_e32 v40, 16, v79
	v_and_b32_e32 v41, 0xffff0000, v79
	v_pk_add_f32 v[30:31], v[30:31], v[36:37]
	v_pk_add_f32 v[28:29], v[28:29], v[34:35]
	v_pk_add_f32 v[34:35], v[26:27], v[40:41]
	v_pk_add_f32 v[26:27], v[24:25], v[38:39]
	v_mul_f32_e32 v24, v29, v29
	v_mul_f32_e32 v25, v31, v31
	v_fmac_f32_e32 v24, v28, v28
	v_fmac_f32_e32 v25, v30, v30
	v_add_f32_e32 v24, v24, v25
	v_mul_f32_e32 v25, v27, v27
	v_mul_f32_e32 v36, v35, v35
	v_fmac_f32_e32 v25, v26, v26
	v_fmac_f32_e32 v36, v34, v34
	v_add_f32_e32 v25, v25, v36
	v_add_f32_e32 v38, v24, v25
	v_cvt_pk_bf16_f32 v24, v28, v29
	v_cvt_pk_bf16_f32 v25, v30, v31
	s_waitcnt vmcnt(6)
	v_lshlrev_b32_e32 v28, 16, v72
	v_and_b32_e32 v29, 0xffff0000, v72
	v_lshlrev_b32_e32 v30, 16, v73
	v_and_b32_e32 v31, 0xffff0000, v73
	v_cvt_pk_bf16_f32 v26, v26, v27
	v_cvt_pk_bf16_f32 v27, v34, v35
	v_lshlrev_b32_e32 v34, 16, v74
	v_and_b32_e32 v35, 0xffff0000, v74
	v_pk_add_f32 v[22:23], v[22:23], v[30:31]
	v_pk_add_f32 v[20:21], v[20:21], v[28:29]
	v_lshlrev_b32_e32 v36, 16, v75
	v_and_b32_e32 v37, 0xffff0000, v75
	v_pk_add_f32 v[30:31], v[16:17], v[34:35]
	v_mul_f32_e32 v16, v21, v21
	v_mul_f32_e32 v17, v23, v23
	v_pk_add_f32 v[28:29], v[18:19], v[36:37]
	v_fmac_f32_e32 v16, v20, v20
	v_fmac_f32_e32 v17, v22, v22
	v_add_f32_e32 v16, v16, v17
	v_mul_f32_e32 v17, v31, v31
	v_mul_f32_e32 v18, v29, v29
	v_fmac_f32_e32 v17, v30, v30
	v_fmac_f32_e32 v18, v28, v28
	v_add_f32_e32 v17, v17, v18
	v_add_f32_e32 v16, v16, v17
	v_add_f32_e32 v19, v38, v16
	v_mov_b32_e32 v34, v19
	s_nop 1
	v_permlane16_swap_b32_e32 v19, v34
	s_waitcnt lgkmcnt(1)
	v_lshlrev_b64 v[32:33], 10, v[90:91]
	v_lshl_add_u64 v[16:17], v[32:33], 1, s[10:11]
	v_lshl_add_u64 v[32:33], v[168:169], 1, v[16:17]
	v_cvt_pk_bf16_f32 v18, v20, v21
	s_waitcnt lgkmcnt(0)
	v_add_f32_e32 v16, v19, v34
	v_mov_b32_e32 v17, v16
	s_nop 1
	v_permlane32_swap_b32_e32 v16, v17
	v_cvt_pk_bf16_f32 v19, v22, v23
	v_cvt_pk_bf16_f32 v20, v30, v31
	v_cvt_pk_bf16_f32 v21, v28, v29
	global_store_dwordx4 v[32:33], v[24:27], off
	global_store_dwordx4 v[32:33], v[18:21], off offset:256
	s_and_saveexec_b64 s[28:29], s[6:7]
	s_cbranch_execz .LBB0_872
	v_lshlrev_b64 v[18:19], 6, v[90:91]
	v_lshl_add_u64 v[18:19], s[12:13], 0, v[18:19]
	v_lshl_add_u64 v[18:19], s[26:27], 2, v[18:19]
	s_lshl_b32 s0, s43, 2
	v_lshl_add_u64 v[18:19], v[18:19], 0, s[0:1]
	s_waitcnt lgkmcnt(0)
	v_add_f32_e32 v16, v16, v17
	global_store_dword v[18:19], v16, off
.LBB0_872:
	s_or_b64 exec, exec, s[28:29]
	s_waitcnt vmcnt(7)
	v_lshlrev_b32_e32 v18, 16, v68
	v_and_b32_e32 v19, 0xffff0000, v68
	v_lshlrev_b32_e32 v20, 16, v69
	v_and_b32_e32 v21, 0xffff0000, v69
	v_lshlrev_b32_e32 v22, 16, v70
	v_and_b32_e32 v23, 0xffff0000, v70
	v_lshlrev_b32_e32 v24, 16, v71
	v_and_b32_e32 v25, 0xffff0000, v71
	v_pk_add_f32 v[14:15], v[14:15], v[20:21]
	v_pk_add_f32 v[12:13], v[12:13], v[18:19]
	v_pk_add_f32 v[18:19], v[10:11], v[24:25]
	v_pk_add_f32 v[10:11], v[8:9], v[22:23]
	v_mul_f32_e32 v8, v13, v13
	v_mul_f32_e32 v9, v15, v15
	v_fmac_f32_e32 v8, v12, v12
	v_fmac_f32_e32 v9, v14, v14
	v_add_f32_e32 v8, v8, v9
	v_mul_f32_e32 v9, v11, v11
	v_mul_f32_e32 v20, v19, v19
	v_fmac_f32_e32 v9, v10, v10
	v_fmac_f32_e32 v20, v18, v18
	v_add_f32_e32 v9, v9, v20
	v_add_f32_e32 v22, v8, v9
	v_cvt_pk_bf16_f32 v8, v12, v13
	v_cvt_pk_bf16_f32 v9, v14, v15
	s_waitcnt vmcnt(6)
	v_lshlrev_b32_e32 v12, 16, v64
	v_and_b32_e32 v13, 0xffff0000, v64
	v_lshlrev_b32_e32 v14, 16, v65
	v_and_b32_e32 v15, 0xffff0000, v65
	v_cvt_pk_bf16_f32 v10, v10, v11
	v_cvt_pk_bf16_f32 v11, v18, v19
	v_lshlrev_b32_e32 v18, 16, v66
	v_and_b32_e32 v19, 0xffff0000, v66
	v_pk_add_f32 v[6:7], v[6:7], v[14:15]
	v_pk_add_f32 v[4:5], v[4:5], v[12:13]
	v_lshlrev_b32_e32 v20, 16, v67
	v_and_b32_e32 v21, 0xffff0000, v67
	v_pk_add_f32 v[14:15], v[0:1], v[18:19]
	v_mul_f32_e32 v0, v5, v5
	v_mul_f32_e32 v1, v7, v7
	v_pk_add_f32 v[12:13], v[2:3], v[20:21]
	v_fmac_f32_e32 v0, v4, v4
	v_fmac_f32_e32 v1, v6, v6
	v_add_f32_e32 v0, v0, v1
	v_mul_f32_e32 v1, v15, v15
	v_mul_f32_e32 v2, v13, v13
	v_fmac_f32_e32 v1, v14, v14
	v_fmac_f32_e32 v2, v12, v12
	v_add_f32_e32 v1, v1, v2
	v_add_f32_e32 v0, v0, v1
	v_add_f32_e32 v3, v22, v0
	v_mov_b32_e32 v18, v3
	s_nop 1
	v_permlane16_swap_b32_e32 v3, v18
	s_waitcnt lgkmcnt(1)
	v_lshlrev_b64 v[16:17], 10, v[88:89]
	v_lshl_add_u64 v[0:1], v[16:17], 1, s[10:11]
	v_lshl_add_u64 v[16:17], v[168:169], 1, v[0:1]
	v_cvt_pk_bf16_f32 v2, v4, v5
	s_waitcnt lgkmcnt(0)
	v_add_f32_e32 v0, v3, v18
	v_mov_b32_e32 v1, v0
	s_nop 1
	v_permlane32_swap_b32_e32 v0, v1
	v_cvt_pk_bf16_f32 v3, v6, v7
	v_cvt_pk_bf16_f32 v4, v14, v15
	v_cvt_pk_bf16_f32 v5, v12, v13
	global_store_dwordx4 v[16:17], v[8:11], off
	global_store_dwordx4 v[16:17], v[2:5], off offset:256
	s_and_saveexec_b64 s[28:29], s[6:7]
	s_cbranch_execz .LBB0_874
	v_lshlrev_b64 v[2:3], 6, v[88:89]
	v_lshl_add_u64 v[2:3], s[12:13], 0, v[2:3]
	v_lshl_add_u64 v[2:3], s[26:27], 2, v[2:3]
	s_lshl_b32 s0, s43, 2
	v_lshl_add_u64 v[2:3], v[2:3], 0, s[0:1]
	s_waitcnt lgkmcnt(0)
	v_add_f32_e32 v0, v0, v1
	global_store_dword v[2:3], v0, off

; #define GAS_ __attribute__((address_space(1)))
; __device__ __forceinline__ unsigned pk2(float lo, float hi) { f32x2_t v = {lo, hi}; bf16x2_t b = __builtin_convertvector(v, bf16x2_t); return __builtin_bit_cast(unsigned, b); }
; __device__ __forceinline__ void rows_rstd(float (&rs)[2][4], const float* SS, int row0, int fq) {
;     ...
;         for (int m = 0; m < 4; ++m) { float s = (q[ai][m][0] + q[ai][m][1]) + (q[ai][m][2] + q[ai][m][3]); s += __shfl_xor(s, 16); s += __shfl_xor(s, 32);
;             rs[ai][m] = 1.0f / sqrtf(s * (1.0f / 1024.0f) + 1e-5f); }
;     __device__ __forceinline__ void operator()(const f32x4 (&acc)[2][2][4][2], const Unit& u, int wr, int wc, int fr, int fq) const {
;     ...
;                     const int h = u.pn * 2 + bj;
;                     if (HM == 0 && col0 + bj * 128 >= 2072) continue;
;                     const float sc = ((scaleMask >> h) & 1u) ? rs * C2 : rs;
;                     f32x4 v0 = acc[ai][bj][m][0] * sc, v1 = acc[ai][bj][m][1] * sc;
;                     int off = bj * bjstep;
;                     if ((dualMask >> h) & 1u) { u32x4 w; w.x = pk2(v0[0], v0[1]); w.y = pk2(v0[2], v0[3]); w.z = pk2(v1[0], v1[1]); w.w = pk2(v1[2], v1[3]); *(GAS_ u32x4*)(rowp + off) = w; off += dualOff; }
;                     if ((ropeMask >> h) & 1u) {
;                         f32x4 a, b2;
;                         a[0] = v0[0] * c4[0] - v0[1] * s4[0]; a[1] = v0[1] * c4[0] + v0[0] * s4[0];
;                         a[2] = v0[2] * c4[1] - v0[3] * s4[1]; a[3] = v0[3] * c4[1] + v0[2] * s4[1];
;                         b2[0] = v1[0] * c4[2] - v1[1] * s4[2]; b2[1] = v1[1] * c4[2] + v1[0] * s4[2];
;                         b2[2] = v1[2] * c4[3] - v1[3] * s4[3]; b2[3] = v1[3] * c4[3] + v1[2] * s4[3];
;                         v0 = a; v1 = b2;
.LBB0_944:
	v_add_f32_e32 v163, v208, v209
	v_fmamk_f32 v163, v163, 0x3a800000, v214
	v_rsq_f32_e32 v167, v163
	s_nop 0
	v_mul_f32_e32 v176, v163, v167
	v_fma_f32 v176, -v176, v167, 1.0
	v_mul_f32_e32 v209, 0.5, v167
	v_fma_f32 v163, v209, v176, v167
	s_nop 1
	s_lshl_b32 s4, 1, s11
	s_and_b32 s5, s4, 0x55
	s_cmp_eq_u32 s5, 0
	v_mul_f32_e32 v226, 0x3e38aa3b, v163
	s_cselect_b64 s[8:9], -1, 0
	s_and_b32 s12, s4, 0x5555
	v_cndmask_b32_e64 v176, v226, v163, s[8:9]
	s_cmp_lg_u32 s12, 0
	v_pk_mul_f32 v[210:211], v[174:175], v[176:177] op_sel_hi:[1,0]
	v_pk_mul_f32 v[172:173], v[172:173], v[176:177] op_sel_hi:[1,0]
	v_pk_mul_f32 v[208:209], v[170:171], v[176:177] op_sel_hi:[1,0]
	s_cselect_b64 s[4:5], -1, 0
	s_cmp_eq_u32 s12, 0
	v_pk_mul_f32 v[174:175], v[168:169], v[176:177] op_sel_hi:[1,0]
	s_cbranch_scc1 .LBB0_946
	v_pk_mul_f32 v[170:171], v[172:173], v[160:161] op_sel:[1,0] op_sel_hi:[0,0]
	v_pk_mul_f32 v[168:169], v[172:173], v[164:165]
	v_pk_fma_f32 v[172:173], v[172:173], v[164:165], v[170:171] op_sel_hi:[1,0,1]
	v_mov_b32_e32 v228, v165
	v_mov_b32_e32 v229, v161
	v_mul_f32_e32 v172, v211, v161
	v_pk_fma_f32 v[228:229], v[210:211], v[228:229], v[172:173] op_sel_hi:[1,1,0] neg_lo:[0,0,1] neg_hi:[0,0,1]
	v_mov_b32_e32 v230, v161
	v_mov_b32_e32 v231, v165
	v_mul_f32_e32 v172, v211, v165
	v_pk_fma_f32 v[230:231], v[210:211], v[230:231], v[172:173] op_sel_hi:[1,1,0]
	v_mov_b32_e32 v234, v205
	v_mov_b32_e32 v235, v204
	v_mul_f32_e32 v172, v209, v204
	v_mov_b32_e32 v167, v205
	v_pk_mul_f32 v[232:233], v[174:175], v[162:163] op_sel:[1,0] op_sel_hi:[0,0]
	v_pk_fma_f32 v[234:235], v[208:209], v[234:235], v[172:173] op_sel_hi:[1,1,0] neg_lo:[0,0,1] neg_hi:[0,0,1]
	v_mul_f32_e32 v172, v209, v205
	v_pk_mul_f32 v[210:211], v[174:175], v[166:167]
	v_pk_fma_f32 v[174:175], v[174:175], v[166:167], v[232:233] op_sel_hi:[1,0,1]
	v_pk_fma_f32 v[236:237], v[208:209], v[204:205], v[172:173] op_sel_hi:[1,1,0]
	v_sub_f32_e32 v172, v168, v170
	v_sub_f32_e32 v174, v210, v232
	v_mov_b32_e32 v210, v228
	v_mov_b32_e32 v211, v230
	v_mov_b32_e32 v208, v234
	v_mov_b32_e32 v209, v236

; #define GAS_ __attribute__((address_space(1)))
; __device__ __forceinline__ unsigned pk2(float lo, float hi) { f32x2_t v = {lo, hi}; bf16x2_t b = __builtin_convertvector(v, bf16x2_t); return __builtin_bit_cast(unsigned, b); }
; __device__ __forceinline__ void rows_rstd(float (&rs)[2][4], const float* SS, int row0, int fq) {
;     ...
;         for (int m = 0; m < 4; ++m) { float s = (q[ai][m][0] + q[ai][m][1]) + (q[ai][m][2] + q[ai][m][3]); s += __shfl_xor(s, 16); s += __shfl_xor(s, 32);
;             rs[ai][m] = 1.0f / sqrtf(s * (1.0f / 1024.0f) + 1e-5f); }
;     __device__ __forceinline__ void operator()(const f32x4 (&acc)[2][2][4][2], const Unit& u, int wr, int wc, int fr, int fq) const {
;     ...
;                     const float sc = ((scaleMask >> h) & 1u) ? rs * C2 : rs;
;                     f32x4 v0 = acc[ai][bj][m][0] * sc, v1 = acc[ai][bj][m][1] * sc;
;                     int off = bj * bjstep;
;                     if ((dualMask >> h) & 1u) { u32x4 w; w.x = pk2(v0[0], v0[1]); w.y = pk2(v0[2], v0[3]); w.z = pk2(v1[0], v1[1]); w.w = pk2(v1[2], v1[3]); *(GAS_ u32x4*)(rowp + off) = w; off += dualOff; }
;                     if ((ropeMask >> h) & 1u) {
;                         f32x4 a, b2;
;                         a[0] = v0[0] * c4[0] - v0[1] * s4[0]; a[1] = v0[1] * c4[0] + v0[0] * s4[0];
;                         a[2] = v0[2] * c4[1] - v0[3] * s4[1]; a[3] = v0[3] * c4[1] + v0[2] * s4[1];
;                         b2[0] = v1[0] * c4[2] - v1[1] * s4[2]; b2[1] = v1[1] * c4[2] + v1[0] * s4[2];
;                         b2[2] = v1[2] * c4[3] - v1[3] * s4[3]; b2[3] = v1[3] * c4[3] + v1[2] * s4[3];
;                         v0 = a; v1 = b2;
;                     }
;                     u32x4 w; w.x = pk2(v0[0], v0[1]); w.y = pk2(v0[2], v0[3]); w.z = pk2(v1[0], v1[1]); w.w = pk2(v1[2], v1[3]);
;                     *(GAS_ u32x4*)(rowp + off) = w;
.LBB0_948:
	v_add_f32_e32 v163, v224, v225
	v_fmamk_f32 v163, v163, 0x3a800000, v214
	v_rsq_f32_e32 v167, v163
	s_nop 0
	v_mul_f32_e32 v172, v163, v167
	v_fma_f32 v172, -v172, v167, 1.0
	v_mul_f32_e32 v174, 0.5, v167
	v_fma_f32 v163, v174, v172, v167
	v_cvt_pk_bf16_f32 v156, v156, v157
	v_cvt_pk_bf16_f32 v157, v158, v159
	v_cvt_pk_bf16_f32 v158, v152, v153
	v_cvt_pk_bf16_f32 v159, v154, v155
	v_add_co_u32_e32 v152, vcc, s69, v170
	s_nop 0
	s_nop 0
	v_addc_co_u32_e32 v153, vcc, 0, v171, vcc
	global_store_dwordx4 v[152:153], v[156:159], off
	v_mul_f32_e32 v152, 0x3e38aa3b, v163
	v_cndmask_b32_e64 v154, v152, v163, s[8:9]
	v_cndmask_b32_e64 v153, 0, 1, s[4:5]
	v_pk_mul_f32 v[150:151], v[150:151], v[154:155] op_sel_hi:[1,0]
	v_pk_mul_f32 v[148:149], v[148:149], v[154:155] op_sel_hi:[1,0]
	v_pk_mul_f32 v[146:147], v[146:147], v[154:155] op_sel_hi:[1,0]
	v_cmp_ne_u32_e64 s[14:15], 1, v153
	s_andn2_b64 vcc, exec, s[4:5]
	v_pk_mul_f32 v[144:145], v[144:145], v[154:155] op_sel_hi:[1,0]
	s_cbranch_vccnz .LBB0_950
	s_waitcnt vmcnt(6)
	v_pk_mul_f32 v[156:157], v[148:149], v[136:137] op_sel:[1,0] op_sel_hi:[0,0]
	v_pk_mul_f32 v[154:155], v[148:149], v[140:141]
	v_pk_fma_f32 v[148:149], v[148:149], v[140:141], v[156:157] op_sel_hi:[1,0,1]
	v_mov_b32_e32 v158, v141
	v_mov_b32_e32 v159, v137
	v_mul_f32_e32 v148, v151, v137
	v_pk_fma_f32 v[158:159], v[150:151], v[158:159], v[148:149] op_sel_hi:[1,1,0] neg_lo:[0,0,1] neg_hi:[0,0,1]
	v_mov_b32_e32 v172, v137
	v_mov_b32_e32 v173, v141
	v_mul_f32_e32 v148, v151, v141
	v_pk_mul_f32 v[174:175], v[144:145], v[138:139] op_sel:[1,0] op_sel_hi:[0,0]
	v_pk_fma_f32 v[172:173], v[150:151], v[172:173], v[148:149] op_sel_hi:[1,1,0]
	v_pk_mul_f32 v[150:151], v[144:145], v[142:143]
	v_pk_fma_f32 v[144:145], v[144:145], v[142:143], v[174:175] op_sel_hi:[1,0,1]
	v_mov_b32_e32 v208, v143
	v_mov_b32_e32 v209, v139
	v_mul_f32_e32 v144, v147, v139
	v_pk_fma_f32 v[208:209], v[146:147], v[208:209], v[144:145] op_sel_hi:[1,1,0] neg_lo:[0,0,1] neg_hi:[0,0,1]
	v_mov_b32_e32 v210, v139
	v_mov_b32_e32 v211, v143
	v_mul_f32_e32 v144, v147, v143
	v_pk_fma_f32 v[210:211], v[146:147], v[210:211], v[144:145] op_sel_hi:[1,1,0]
	v_sub_f32_e32 v148, v154, v156
	v_sub_f32_e32 v144, v150, v174
	v_mov_b32_e32 v150, v158
	v_mov_b32_e32 v151, v172
	v_mov_b32_e32 v146, v208
	v_mov_b32_e32 v147, v210

; #define GAS_ __attribute__((address_space(1)))
; __device__ __forceinline__ unsigned pk2(float lo, float hi) { f32x2_t v = {lo, hi}; bf16x2_t b = __builtin_convertvector(v, bf16x2_t); return __builtin_bit_cast(unsigned, b); }
; __device__ __forceinline__ void rows_rstd(float (&rs)[2][4], const float* SS, int row0, int fq) {
;     ...
;         for (int m = 0; m < 4; ++m) { float s = (q[ai][m][0] + q[ai][m][1]) + (q[ai][m][2] + q[ai][m][3]); s += __shfl_xor(s, 16); s += __shfl_xor(s, 32);
;             rs[ai][m] = 1.0f / sqrtf(s * (1.0f / 1024.0f) + 1e-5f); }
;     __device__ __forceinline__ void operator()(const f32x4 (&acc)[2][2][4][2], const Unit& u, int wr, int wc, int fr, int fq) const {
;     ...
;                     const float sc = ((scaleMask >> h) & 1u) ? rs * C2 : rs;
;                     f32x4 v0 = acc[ai][bj][m][0] * sc, v1 = acc[ai][bj][m][1] * sc;
;                     int off = bj * bjstep;
;                     if ((dualMask >> h) & 1u) { u32x4 w; w.x = pk2(v0[0], v0[1]); w.y = pk2(v0[2], v0[3]); w.z = pk2(v1[0], v1[1]); w.w = pk2(v1[2], v1[3]); *(GAS_ u32x4*)(rowp + off) = w; off += dualOff; }
;                     if ((ropeMask >> h) & 1u) {
;                         f32x4 a, b2;
;                         a[0] = v0[0] * c4[0] - v0[1] * s4[0]; a[1] = v0[1] * c4[0] + v0[0] * s4[0];
;                         a[2] = v0[2] * c4[1] - v0[3] * s4[1]; a[3] = v0[3] * c4[1] + v0[2] * s4[1];
;                         b2[0] = v1[0] * c4[2] - v1[1] * s4[2]; b2[1] = v1[1] * c4[2] + v1[0] * s4[2];
;                         b2[2] = v1[2] * c4[3] - v1[3] * s4[3]; b2[3] = v1[3] * c4[3] + v1[2] * s4[3];
;                         v0 = a; v1 = b2;
;                     }
;                     u32x4 w; w.x = pk2(v0[0], v0[1]); w.y = pk2(v0[2], v0[3]); w.z = pk2(v1[0], v1[1]); w.w = pk2(v1[2], v1[3]);
;                     *(GAS_ u32x4*)(rowp + off) = w;
.LBB0_952:
	v_add_f32_e32 v144, v222, v223
	v_fmamk_f32 v144, v144, 0x3a800000, v214
	v_rsq_f32_e32 v145, v144
	s_nop 0
	v_mul_f32_e32 v146, v144, v145
	v_fma_f32 v146, -v146, v145, 1.0
	v_mul_f32_e32 v148, 0.5, v145
	v_fma_f32 v144, v148, v146, v145
	v_cvt_pk_bf16_f32 v132, v132, v133
	v_cvt_pk_bf16_f32 v133, v134, v135
	v_cvt_pk_bf16_f32 v134, v128, v129
	v_cvt_pk_bf16_f32 v135, v130, v131
	v_lshl_add_u64 v[146:147], v[170:171], 0, s[72:73]
	s_nop 0
	v_add_co_u32_e32 v128, vcc, s69, v146
	s_nop 0
	s_nop 0
	v_addc_co_u32_e32 v129, vcc, 0, v147, vcc
	global_store_dwordx4 v[128:129], v[132:135], off
	v_mul_f32_e32 v130, 0x3e38aa3b, v144
	s_and_b64 vcc, exec, s[14:15]
	v_cndmask_b32_e64 v132, v130, v144, s[8:9]
	v_pk_mul_f32 v[128:129], v[126:127], v[132:133] op_sel_hi:[1,0]
	v_pk_mul_f32 v[124:125], v[124:125], v[132:133] op_sel_hi:[1,0]
	v_pk_mul_f32 v[126:127], v[122:123], v[132:133] op_sel_hi:[1,0]
	v_pk_mul_f32 v[122:123], v[120:121], v[132:133] op_sel_hi:[1,0]
	s_cbranch_vccnz .LBB0_954
	s_waitcnt vmcnt(6)
	v_pk_mul_f32 v[132:133], v[124:125], v[112:113] op_sel:[1,0] op_sel_hi:[0,0]
	v_pk_mul_f32 v[120:121], v[124:125], v[116:117]
	v_pk_fma_f32 v[124:125], v[124:125], v[116:117], v[132:133] op_sel_hi:[1,0,1]
	v_mov_b32_e32 v134, v117
	v_mov_b32_e32 v135, v113
	v_mul_f32_e32 v124, v129, v113
	v_pk_fma_f32 v[134:135], v[128:129], v[134:135], v[124:125] op_sel_hi:[1,1,0] neg_lo:[0,0,1] neg_hi:[0,0,1]
	v_mov_b32_e32 v146, v113
	v_mov_b32_e32 v147, v117
	v_mul_f32_e32 v124, v129, v117
	v_pk_mul_f32 v[148:149], v[122:123], v[114:115] op_sel:[1,0] op_sel_hi:[0,0]
	v_pk_fma_f32 v[146:147], v[128:129], v[146:147], v[124:125] op_sel_hi:[1,1,0]
	v_pk_mul_f32 v[128:129], v[122:123], v[118:119]
	v_pk_fma_f32 v[122:123], v[122:123], v[118:119], v[148:149] op_sel_hi:[1,0,1]
	v_mov_b32_e32 v150, v119
	v_mov_b32_e32 v151, v115
	v_mul_f32_e32 v122, v127, v115
	v_pk_fma_f32 v[150:151], v[126:127], v[150:151], v[122:123] op_sel_hi:[1,1,0] neg_lo:[0,0,1] neg_hi:[0,0,1]
	v_mov_b32_e32 v152, v115
	v_mov_b32_e32 v153, v119
	v_mul_f32_e32 v122, v127, v119
	v_pk_fma_f32 v[152:153], v[126:127], v[152:153], v[122:123] op_sel_hi:[1,1,0]
	v_sub_f32_e32 v124, v120, v132
	v_sub_f32_e32 v122, v128, v148
	v_mov_b32_e32 v128, v134
	v_mov_b32_e32 v129, v146
	v_mov_b32_e32 v126, v150
	v_mov_b32_e32 v127, v152

; #define GAS_ __attribute__((address_space(1)))
; __device__ __forceinline__ unsigned pk2(float lo, float hi) { f32x2_t v = {lo, hi}; bf16x2_t b = __builtin_convertvector(v, bf16x2_t); return __builtin_bit_cast(unsigned, b); }
; __device__ __forceinline__ void rows_rstd(float (&rs)[2][4], const float* SS, int row0, int fq) {
;     ...
;         for (int m = 0; m < 4; ++m) { float s = (q[ai][m][0] + q[ai][m][1]) + (q[ai][m][2] + q[ai][m][3]); s += __shfl_xor(s, 16); s += __shfl_xor(s, 32);
;             rs[ai][m] = 1.0f / sqrtf(s * (1.0f / 1024.0f) + 1e-5f); }
;     __device__ __forceinline__ void operator()(const f32x4 (&acc)[2][2][4][2], const Unit& u, int wr, int wc, int fr, int fq) const {
;     ...
;                     const float sc = ((scaleMask >> h) & 1u) ? rs * C2 : rs;
;                     f32x4 v0 = acc[ai][bj][m][0] * sc, v1 = acc[ai][bj][m][1] * sc;
;                     int off = bj * bjstep;
;                     if ((dualMask >> h) & 1u) { u32x4 w; w.x = pk2(v0[0], v0[1]); w.y = pk2(v0[2], v0[3]); w.z = pk2(v1[0], v1[1]); w.w = pk2(v1[2], v1[3]); *(GAS_ u32x4*)(rowp + off) = w; off += dualOff; }
;                     if ((ropeMask >> h) & 1u) {
;                         f32x4 a, b2;
;                         a[0] = v0[0] * c4[0] - v0[1] * s4[0]; a[1] = v0[1] * c4[0] + v0[0] * s4[0];
;                         a[2] = v0[2] * c4[1] - v0[3] * s4[1]; a[3] = v0[3] * c4[1] + v0[2] * s4[1];
;                         b2[0] = v1[0] * c4[2] - v1[1] * s4[2]; b2[1] = v1[1] * c4[2] + v1[0] * s4[2];
;                         b2[2] = v1[2] * c4[3] - v1[3] * s4[3]; b2[3] = v1[3] * c4[3] + v1[2] * s4[3];
;                         v0 = a; v1 = b2;
.LBB0_962:
	v_add_f32_e32 v82, v213, v215
	v_fmamk_f32 v82, v82, 0x3a800000, v214
	v_rsq_f32_e32 v83, v82
	s_nop 0
	v_mul_f32_e32 v84, v82, v83
	v_fma_f32 v84, -v84, v83, 1.0
	v_mul_f32_e32 v85, 0.5, v83
	v_fma_f32 v86, v85, v84, v83
	s_nop 1
	v_mul_f32_e32 v87, 0x3e38aa3b, v86
	v_cndmask_b32_e64 v96, v87, v86, s[8:9]
	v_pk_mul_f32 v[84:85], v[78:79], v[96:97] op_sel_hi:[1,0]
	v_pk_mul_f32 v[76:77], v[76:77], v[96:97] op_sel_hi:[1,0]
	v_pk_mul_f32 v[82:83], v[74:75], v[96:97] op_sel_hi:[1,0]
	s_and_b64 vcc, exec, s[14:15]
	v_pk_mul_f32 v[78:79], v[72:73], v[96:97] op_sel_hi:[1,0]
	s_cbranch_vccnz .LBB0_964
	v_pk_mul_f32 v[74:75], v[76:77], v[160:161] op_sel:[1,0] op_sel_hi:[0,0]
	v_pk_mul_f32 v[72:73], v[76:77], v[164:165] op_sel_hi:[1,0]
	v_pk_fma_f32 v[76:77], v[76:77], v[164:165], v[74:75] op_sel_hi:[1,0,1]
	v_pk_mul_f32 v[100:101], v[78:79], v[162:163] op_sel:[1,0] op_sel_hi:[0,0]
	v_mul_f32_e32 v76, v85, v80
	v_pk_fma_f32 v[96:97], v[84:85], v[80:81], v[76:77] op_sel:[0,1,0] op_sel_hi:[1,0,0] neg_lo:[0,0,1] neg_hi:[0,0,1]
	v_mul_f32_e32 v76, v85, v81
	v_pk_fma_f32 v[98:99], v[84:85], v[80:81], v[76:77] op_sel_hi:[1,1,0]
	v_mul_f32_e32 v76, v83, v204
	v_pk_fma_f32 v[102:103], v[82:83], v[204:205], v[76:77] op_sel:[0,1,0] op_sel_hi:[1,0,0] neg_lo:[0,0,1] neg_hi:[0,0,1]
	v_mul_f32_e32 v76, v83, v205
	v_pk_mul_f32 v[84:85], v[78:79], v[166:167] op_sel_hi:[1,0]
	v_pk_fma_f32 v[78:79], v[78:79], v[166:167], v[100:101] op_sel_hi:[1,0,1]
	v_pk_fma_f32 v[104:105], v[82:83], v[204:205], v[76:77] op_sel_hi:[1,1,0]
	v_sub_f32_e32 v76, v72, v74
	v_sub_f32_e32 v78, v84, v100
	v_mov_b32_e32 v84, v96
	v_mov_b32_e32 v85, v98
	v_mov_b32_e32 v82, v102
	v_mov_b32_e32 v83, v104

; #define GAS_ __attribute__((address_space(1)))
; __device__ __forceinline__ unsigned pk2(float lo, float hi) { f32x2_t v = {lo, hi}; bf16x2_t b = __builtin_convertvector(v, bf16x2_t); return __builtin_bit_cast(unsigned, b); }
; __device__ __forceinline__ void rows_rstd(float (&rs)[2][4], const float* SS, int row0, int fq) {
;     ...
;         for (int m = 0; m < 4; ++m) { float s = (q[ai][m][0] + q[ai][m][1]) + (q[ai][m][2] + q[ai][m][3]); s += __shfl_xor(s, 16); s += __shfl_xor(s, 32);
;             rs[ai][m] = 1.0f / sqrtf(s * (1.0f / 1024.0f) + 1e-5f); }
;     __device__ __forceinline__ void operator()(const f32x4 (&acc)[2][2][4][2], const Unit& u, int wr, int wc, int fr, int fq) const {
;     ...
;                     const float sc = ((scaleMask >> h) & 1u) ? rs * C2 : rs;
;                     f32x4 v0 = acc[ai][bj][m][0] * sc, v1 = acc[ai][bj][m][1] * sc;
;                     int off = bj * bjstep;
;                     if ((dualMask >> h) & 1u) { u32x4 w; w.x = pk2(v0[0], v0[1]); w.y = pk2(v0[2], v0[3]); w.z = pk2(v1[0], v1[1]); w.w = pk2(v1[2], v1[3]); *(GAS_ u32x4*)(rowp + off) = w; off += dualOff; }
;                     if ((ropeMask >> h) & 1u) {
;                         f32x4 a, b2;
;                         a[0] = v0[0] * c4[0] - v0[1] * s4[0]; a[1] = v0[1] * c4[0] + v0[0] * s4[0];
;                         a[2] = v0[2] * c4[1] - v0[3] * s4[1]; a[3] = v0[3] * c4[1] + v0[2] * s4[1];
;                         b2[0] = v1[0] * c4[2] - v1[1] * s4[2]; b2[1] = v1[1] * c4[2] + v1[0] * s4[2];
;                         b2[2] = v1[2] * c4[3] - v1[3] * s4[3]; b2[3] = v1[3] * c4[3] + v1[2] * s4[3];
;                         v0 = a; v1 = b2;
;                     }
;                     u32x4 w; w.x = pk2(v0[0], v0[1]); w.y = pk2(v0[2], v0[3]); w.z = pk2(v1[0], v1[1]); w.w = pk2(v1[2], v1[3]);
;                     *(GAS_ u32x4*)(rowp + off) = w;
.LBB0_966:
	v_add_f32_e32 v76, v180, v181
	v_fmamk_f32 v76, v76, 0x3a800000, v214
	v_rsq_f32_e32 v77, v76
	s_nop 0
	v_mul_f32_e32 v78, v76, v77
	v_fma_f32 v78, -v78, v77, 1.0
	v_mul_f32_e32 v80, 0.5, v77
	v_fma_f32 v76, v80, v78, v77
	v_cvt_pk_bf16_f32 v68, v68, v69
	v_cvt_pk_bf16_f32 v69, v70, v71
	v_cvt_pk_bf16_f32 v70, v64, v65
	v_cvt_pk_bf16_f32 v71, v66, v67
	v_add_co_u32_e32 v64, vcc, s69, v74
	s_nop 0
	s_nop 0
	v_addc_co_u32_e32 v65, vcc, 0, v75, vcc
	global_store_dwordx4 v[64:65], v[68:71], off
	v_mul_f32_e32 v64, 0x3e38aa3b, v76
	v_cndmask_b32_e64 v66, v64, v76, s[8:9]
	v_pk_mul_f32 v[62:63], v[62:63], v[66:67] op_sel_hi:[1,0]
	v_pk_mul_f32 v[60:61], v[60:61], v[66:67] op_sel_hi:[1,0]
	v_pk_mul_f32 v[58:59], v[58:59], v[66:67] op_sel_hi:[1,0]
	s_and_b64 vcc, exec, s[14:15]
	v_pk_mul_f32 v[56:57], v[56:57], v[66:67] op_sel_hi:[1,0]
	s_cbranch_vccnz .LBB0_968
	s_waitcnt vmcnt(6)
	v_pk_mul_f32 v[68:69], v[60:61], v[136:137] op_sel:[1,0] op_sel_hi:[0,0]
	v_pk_mul_f32 v[66:67], v[60:61], v[140:141]
	v_pk_fma_f32 v[60:61], v[60:61], v[140:141], v[68:69] op_sel_hi:[1,0,1]
	v_mov_b32_e32 v70, v141
	v_mov_b32_e32 v71, v137
	v_mul_f32_e32 v60, v63, v137
	v_pk_fma_f32 v[70:71], v[62:63], v[70:71], v[60:61] op_sel_hi:[1,1,0] neg_lo:[0,0,1] neg_hi:[0,0,1]
	v_mov_b32_e32 v78, v137
	v_mov_b32_e32 v79, v141
	v_mul_f32_e32 v60, v63, v141
	v_pk_mul_f32 v[80:81], v[56:57], v[138:139] op_sel:[1,0] op_sel_hi:[0,0]
	v_pk_fma_f32 v[78:79], v[62:63], v[78:79], v[60:61] op_sel_hi:[1,1,0]
	v_pk_mul_f32 v[62:63], v[56:57], v[142:143]
	v_pk_fma_f32 v[56:57], v[56:57], v[142:143], v[80:81] op_sel_hi:[1,0,1]
	v_mov_b32_e32 v82, v143
	v_mov_b32_e32 v83, v139
	v_mul_f32_e32 v56, v59, v139
	v_pk_fma_f32 v[82:83], v[58:59], v[82:83], v[56:57] op_sel_hi:[1,1,0] neg_lo:[0,0,1] neg_hi:[0,0,1]
	v_mov_b32_e32 v84, v139
	v_mov_b32_e32 v85, v143
	v_mul_f32_e32 v56, v59, v143
	v_pk_fma_f32 v[84:85], v[58:59], v[84:85], v[56:57] op_sel_hi:[1,1,0]
	v_sub_f32_e32 v60, v66, v68
	v_sub_f32_e32 v56, v62, v80
	v_mov_b32_e32 v62, v70
	v_mov_b32_e32 v63, v78
	v_mov_b32_e32 v58, v82
	v_mov_b32_e32 v59, v84

; #define GAS_ __attribute__((address_space(1)))
; __device__ __forceinline__ unsigned pk2(float lo, float hi) { f32x2_t v = {lo, hi}; bf16x2_t b = __builtin_convertvector(v, bf16x2_t); return __builtin_bit_cast(unsigned, b); }
; __device__ __forceinline__ void rows_rstd(float (&rs)[2][4], const float* SS, int row0, int fq) {
;     ...
;         for (int m = 0; m < 4; ++m) { float s = (q[ai][m][0] + q[ai][m][1]) + (q[ai][m][2] + q[ai][m][3]); s += __shfl_xor(s, 16); s += __shfl_xor(s, 32);
;             rs[ai][m] = 1.0f / sqrtf(s * (1.0f / 1024.0f) + 1e-5f); }
;     __device__ __forceinline__ void operator()(const f32x4 (&acc)[2][2][4][2], const Unit& u, int wr, int wc, int fr, int fq) const {
;     ...
;                     const float sc = ((scaleMask >> h) & 1u) ? rs * C2 : rs;
;                     f32x4 v0 = acc[ai][bj][m][0] * sc, v1 = acc[ai][bj][m][1] * sc;
;                     int off = bj * bjstep;
;                     if ((dualMask >> h) & 1u) { u32x4 w; w.x = pk2(v0[0], v0[1]); w.y = pk2(v0[2], v0[3]); w.z = pk2(v1[0], v1[1]); w.w = pk2(v1[2], v1[3]); *(GAS_ u32x4*)(rowp + off) = w; off += dualOff; }
;                     if ((ropeMask >> h) & 1u) {
;                         f32x4 a, b2;
;                         a[0] = v0[0] * c4[0] - v0[1] * s4[0]; a[1] = v0[1] * c4[0] + v0[0] * s4[0];
;                         a[2] = v0[2] * c4[1] - v0[3] * s4[1]; a[3] = v0[3] * c4[1] + v0[2] * s4[1];
;                         b2[0] = v1[0] * c4[2] - v1[1] * s4[2]; b2[1] = v1[1] * c4[2] + v1[0] * s4[2];
;                         b2[2] = v1[2] * c4[3] - v1[3] * s4[3]; b2[3] = v1[3] * c4[3] + v1[2] * s4[3];
;                         v0 = a; v1 = b2;
;                     }
;                     u32x4 w; w.x = pk2(v0[0], v0[1]); w.y = pk2(v0[2], v0[3]); w.z = pk2(v1[0], v1[1]); w.w = pk2(v1[2], v1[3]);
;                     *(GAS_ u32x4*)(rowp + off) = w;
.LBB0_970:
	s_waitcnt lgkmcnt(1)
	v_add_f32_e32 v56, v203, v207
	v_fmamk_f32 v56, v56, 0x3a800000, v214
	v_rsq_f32_e32 v57, v56
	s_nop 0
	v_mul_f32_e32 v58, v56, v57
	v_fma_f32 v58, -v58, v57, 1.0
	v_mul_f32_e32 v60, 0.5, v57
	v_fma_f32 v56, v60, v58, v57
	v_cvt_pk_bf16_f32 v52, v52, v53
	v_cvt_pk_bf16_f32 v53, v54, v55
	v_cvt_pk_bf16_f32 v54, v48, v49
	v_cvt_pk_bf16_f32 v55, v50, v51
	v_lshl_add_u64 v[58:59], v[74:75], 0, s[72:73]
	s_nop 0
	v_add_co_u32_e32 v48, vcc, s69, v58
	s_nop 0
	s_nop 0
	v_addc_co_u32_e32 v49, vcc, 0, v59, vcc
	global_store_dwordx4 v[48:49], v[52:55], off
	v_mul_f32_e32 v50, 0x3e38aa3b, v56
	s_and_b64 vcc, exec, s[14:15]
	v_cndmask_b32_e64 v52, v50, v56, s[8:9]
	v_pk_mul_f32 v[48:49], v[46:47], v[52:53] op_sel_hi:[1,0]
	v_pk_mul_f32 v[44:45], v[44:45], v[52:53] op_sel_hi:[1,0]
	v_pk_mul_f32 v[46:47], v[42:43], v[52:53] op_sel_hi:[1,0]
	v_pk_mul_f32 v[42:43], v[40:41], v[52:53] op_sel_hi:[1,0]
	s_cbranch_vccnz .LBB0_972
	s_waitcnt vmcnt(6)
	v_pk_mul_f32 v[52:53], v[44:45], v[112:113] op_sel:[1,0] op_sel_hi:[0,0]
	v_pk_mul_f32 v[40:41], v[44:45], v[116:117]
	v_pk_fma_f32 v[44:45], v[44:45], v[116:117], v[52:53] op_sel_hi:[1,0,1]
	v_mov_b32_e32 v54, v117
	v_mov_b32_e32 v55, v113
	v_mul_f32_e32 v44, v49, v113
	v_pk_fma_f32 v[54:55], v[48:49], v[54:55], v[44:45] op_sel_hi:[1,1,0] neg_lo:[0,0,1] neg_hi:[0,0,1]
	v_mov_b32_e32 v58, v113
	v_mov_b32_e32 v59, v117
	v_mul_f32_e32 v44, v49, v117
	v_pk_mul_f32 v[60:61], v[42:43], v[114:115] op_sel:[1,0] op_sel_hi:[0,0]
	v_pk_fma_f32 v[58:59], v[48:49], v[58:59], v[44:45] op_sel_hi:[1,1,0]
	v_pk_mul_f32 v[48:49], v[42:43], v[118:119]
	v_pk_fma_f32 v[42:43], v[42:43], v[118:119], v[60:61] op_sel_hi:[1,0,1]
	v_mov_b32_e32 v62, v119
	v_mov_b32_e32 v63, v115
	v_mul_f32_e32 v42, v47, v115
	v_pk_fma_f32 v[62:63], v[46:47], v[62:63], v[42:43] op_sel_hi:[1,1,0] neg_lo:[0,0,1] neg_hi:[0,0,1]
	v_mov_b32_e32 v64, v115
	v_mov_b32_e32 v65, v119
	v_mul_f32_e32 v42, v47, v119
	v_pk_fma_f32 v[64:65], v[46:47], v[64:65], v[42:43] op_sel_hi:[1,1,0]
	v_sub_f32_e32 v44, v40, v52
	v_sub_f32_e32 v42, v48, v60
	v_mov_b32_e32 v48, v54
	v_mov_b32_e32 v49, v58
	v_mov_b32_e32 v46, v62
	v_mov_b32_e32 v47, v64

; #define GAS_ __attribute__((address_space(1)))
;     __device__ __forceinline__ void operator()(const f32x4 (&acc)[2][2][4][2], const Unit& u, int wr, int wc, int fr, int fq) const {
;     ...
;         for (int ai = 0; ai < 2; ++ai) {
;             f32x4 bs[4][2][2]; u32x4 bh[4][2];
; #pragma unroll
;             for (int m = 0; m < 4; ++m) { const size_t off = (size_t)(row0 + ai * 128 + m * 16) * ldc + col0;
; #pragma unroll
;                 for (int bj = 0; bj < 2; ++bj) {
;                     if (BASE_F32) { bs[m][bj][0] = *(const GAS_ f32x4*)(basef + off + bj * 128); bs[m][bj][1] = *(const GAS_ f32x4*)(basef + off + bj * 128 + 4); }
;                     else bh[m][bj] = *(const GAS_ u32x4*)(XB + off + bj * 128); } }
;             asm volatile("" ::: "memory");
; #pragma unroll
;             for (int m = 0; m < 4; ++m) {
;                 const size_t off = (size_t)(row0 + ai * 128 + m * 16) * ldc + col0;
;                 float ssq = 0.f;
; #pragma unroll
;                 for (int bj = 0; bj < 2; ++bj) {
;                     f32x4 b0, b1;
;                     if (BASE_F32) { b0 = bs[m][bj][0]; b1 = bs[m][bj][1]; }
;                     else { const u32x4 h = bh[m][bj];
;                         b0 = (f32x4){__builtin_bit_cast(float, h.x << 16), __builtin_bit_cast(float, h.x & 0xffff0000u), __builtin_bit_cast(float, h.y << 16), __builtin_bit_cast(float, h.y & 0xffff0000u)};
;                         b1 = (f32x4){__builtin_bit_cast(float, h.z << 16), __builtin_bit_cast(float, h.z & 0xffff0000u), __builtin_bit_cast(float, h.w << 16), __builtin_bit_cast(float, h.w & 0xffff0000u)}; }
;                     const f32x4 v0 = b0 + acc[ai][bj][m][0], v1 = b1 + acc[ai][bj][m][1];
;                     ssq += ((v0[0] * v0[0] + v0[1] * v0[1]) + (v0[2] * v0[2] + v0[3] * v0[3])) + ((v1[0] * v1[0] + v1[1] * v1[1]) + (v1[2] * v1[2] + v1[3] * v1[3]));
;                     u32x4 w; w.x = pk2(v0[0], v0[1]); w.y = pk2(v0[2], v0[3]); w.z = pk2(v1[0], v1[1]); w.w = pk2(v1[2], v1[3]); *(GAS_ u32x4*)(XB + off + bj * 128) = w;
;                 }
;                 ssq += __shfl_xor(ssq, 16); ssq += __shfl_xor(ssq, 32);
;                 if (fq == 0) *(GAS_ float*)(SS + (size_t)(row0 + ai * 128 + m * 16) * 16 + u.pn * 4 + wc) = ssq;
;             }
.LBB0_1156:
	v_lshl_or_b32 v188, s41, 8, v202
	v_lshl_add_u32 v192, s42, 8, v200
	v_ashrrev_i32_e32 v189, 31, v188
	v_lshlrev_b64 v[180:181], 1, v[188:189]
	v_ashrrev_i32_e32 v193, 31, v192
	v_lshl_add_u64 v[190:191], s[12:13], 0, v[180:181]
	v_lshlrev_b64 v[208:209], 11, v[192:193]
	v_lshl_add_u64 v[144:145], v[190:191], 0, v[208:209]
	global_load_dwordx4 v[204:207], v[144:145], off
	global_load_dwordx4 v[168:171], v[144:145], off offset:256
	v_or_b32_e32 v198, 16, v192
	v_ashrrev_i32_e32 v199, 31, v198
	v_lshlrev_b64 v[144:145], 11, v[198:199]
	v_or_b32_e32 v196, 32, v192
	v_lshl_add_u64 v[144:145], v[190:191], 0, v[144:145]
	v_ashrrev_i32_e32 v197, 31, v196
	global_load_dwordx4 v[164:167], v[144:145], off
	global_load_dwordx4 v[160:163], v[144:145], off offset:256
	v_lshlrev_b64 v[144:145], 11, v[196:197]
	v_or_b32_e32 v194, 48, v192
	v_lshl_add_u64 v[144:145], v[190:191], 0, v[144:145]
	v_ashrrev_i32_e32 v195, 31, v194
	global_load_dwordx4 v[156:159], v[144:145], off
	global_load_dwordx4 v[152:155], v[144:145], off offset:256
	v_lshlrev_b64 v[144:145], 11, v[194:195]
	v_lshl_add_u64 v[144:145], v[190:191], 0, v[144:145]
	global_load_dwordx4 v[148:151], v[144:145], off
	s_nop 0
	global_load_dwordx4 v[144:147], v[144:145], off offset:256
	v_and_b32_e32 v179, 64, v212
	v_xor_b32_e32 v178, 16, v212
	v_add_u32_e32 v179, 64, v179
	v_cmp_lt_i32_e32 vcc, v178, v179
	v_xor_b32_e32 v210, 32, v212
	s_lshl_b32 s22, s41, 2
	v_cndmask_b32_e32 v178, v212, v178, vcc
	v_cmp_lt_i32_e32 vcc, v210, v179
	v_lshlrev_b32_e32 v178, 2, v178
	s_ashr_i32 s23, s22, 31
	v_cndmask_b32_e32 v179, v212, v210, vcc
	v_lshlrev_b32_e32 v179, 2, v179
	s_waitcnt vmcnt(0)
	v_lshlrev_b32_e32 v210, 16, v204
	v_and_b32_e32 v211, 0xffff0000, v204
	v_lshlrev_b32_e32 v204, 16, v205
	v_and_b32_e32 v205, 0xffff0000, v205
	v_lshlrev_b32_e32 v218, 16, v206
	v_and_b32_e32 v219, 0xffff0000, v206
	v_lshlrev_b32_e32 v206, 16, v207
	v_and_b32_e32 v207, 0xffff0000, v207
	v_pk_add_f32 v[142:143], v[142:143], v[204:205]
	v_pk_add_f32 v[140:141], v[140:141], v[210:211]
	v_pk_add_f32 v[204:205], v[138:139], v[206:207]
	v_mul_f32_e32 v138, v141, v141
	v_mul_f32_e32 v139, v143, v143
	v_pk_add_f32 v[136:137], v[136:137], v[218:219]
	v_fmac_f32_e32 v138, v140, v140
	v_fmac_f32_e32 v139, v142, v142
	v_add_f32_e32 v138, v138, v139
	v_mul_f32_e32 v139, v137, v137
	v_mul_f32_e32 v206, v205, v205
	v_fmac_f32_e32 v139, v136, v136
	v_fmac_f32_e32 v206, v204, v204
	v_add_f32_e32 v139, v139, v206
	v_add_f32_e32 v206, v138, v139
	v_cvt_pk_bf16_f32 v138, v140, v141
	v_cvt_pk_bf16_f32 v140, v136, v137
	v_lshl_add_u64 v[136:137], s[12:13], 0, v[208:209]
	v_cvt_pk_bf16_f32 v139, v142, v143
	v_cvt_pk_bf16_f32 v141, v204, v205
	v_lshl_add_u64 v[136:137], v[136:137], 0, v[180:181]
	global_store_dwordx4 v[136:137], v[138:141], off
	v_lshlrev_b32_e32 v142, 16, v170
	v_and_b32_e32 v143, 0xffff0000, v170
	v_lshlrev_b32_e32 v138, 16, v168
	v_and_b32_e32 v139, 0xffff0000, v168
	v_lshlrev_b32_e32 v140, 16, v169
	v_and_b32_e32 v141, 0xffff0000, v169
	v_lshlrev_b32_e32 v168, 16, v171
	v_and_b32_e32 v169, 0xffff0000, v171
	v_pk_add_f32 v[134:135], v[134:135], v[140:141]
	v_pk_add_f32 v[132:133], v[132:133], v[138:139]
	v_pk_add_f32 v[138:139], v[130:131], v[168:169]
	v_pk_add_f32 v[130:131], v[128:129], v[142:143]
	v_mul_f32_e32 v128, v133, v133
	v_mul_f32_e32 v129, v135, v135
	v_fmac_f32_e32 v128, v132, v132
	v_fmac_f32_e32 v129, v134, v134
	v_add_f32_e32 v128, v128, v129
	v_mul_f32_e32 v129, v131, v131
	v_mul_f32_e32 v140, v139, v139
	v_fmac_f32_e32 v129, v130, v130
	v_fmac_f32_e32 v140, v138, v138
	v_add_f32_e32 v129, v129, v140
	v_add_f32_e32 v128, v128, v129
	v_add_f32_e32 v140, v206, v128
	v_cvt_pk_bf16_f32 v128, v132, v133
	v_cvt_pk_bf16_f32 v129, v134, v135
	v_cvt_pk_bf16_f32 v130, v130, v131
	v_cvt_pk_bf16_f32 v131, v138, v139
	global_store_dwordx4 v[136:137], v[128:131], off offset:256
	s_nop 1
	v_mov_b32_e32 v128, v140
	s_nop 1
	v_permlane16_swap_b32_e32 v140, v128
	s_waitcnt lgkmcnt(0)
	v_add_f32_e32 v128, v140, v128
	v_mov_b32_e32 v129, v128
	s_nop 1
	v_permlane32_swap_b32_e32 v128, v129
	s_and_saveexec_b64 s[24:25], s[6:7]
	s_cbranch_execz .LBB0_1158
	v_readlane_b32 s44, v254, 18
	v_readlane_b32 s45, v254, 19
	v_lshlrev_b64 v[130:131], 6, v[192:193]
	s_mov_b32 s5, s45
	v_lshl_add_u64 v[130:131], s[14:15], 0, v[130:131]
	v_readlane_b32 s46, v254, 20
	v_readlane_b32 s47, v254, 21
	v_readlane_b32 s48, v254, 22
	v_readlane_b32 s49, v254, 23
	v_readlane_b32 s50, v254, 24
	v_readlane_b32 s51, v254, 25
	v_readlane_b32 s52, v254, 26
	v_readlane_b32 s53, v254, 27
	v_readlane_b32 s54, v254, 28
	v_readlane_b32 s55, v254, 29
	v_readlane_b32 s56, v254, 30
	v_readlane_b32 s57, v254, 31
	v_readlane_b32 s58, v254, 32
	v_readlane_b32 s59, v254, 33
	v_writelane_b32 v254, s4, 18
	v_lshl_add_u64 v[130:131], s[22:23], 2, v[130:131]
	s_lshl_b32 s44, s37, 2
	v_writelane_b32 v254, s5, 19
	v_writelane_b32 v254, s6, 20
	v_writelane_b32 v254, s7, 21
	v_writelane_b32 v254, s8, 22
	v_writelane_b32 v254, s9, 23
	v_writelane_b32 v254, s10, 24
	v_writelane_b32 v254, s11, 25
	v_writelane_b32 v254, s12, 26
	v_writelane_b32 v254, s13, 27
	v_writelane_b32 v254, s14, 28
	v_writelane_b32 v254, s15, 29
	v_writelane_b32 v254, s16, 30
	v_writelane_b32 v254, s17, 31
	v_writelane_b32 v254, s18, 32
	s_mov_b32 s52, 0xff800000
	v_writelane_b32 v254, s19, 33
	v_lshl_add_u64 v[130:131], v[130:131], 0, s[44:45]
	s_waitcnt lgkmcnt(0)
	v_add_f32_e32 v128, v128, v129
	global_store_dword v[130:131], v128, off
; #define GAS_ __attribute__((address_space(1)))
; __device__ __forceinline__ unsigned pk2(float lo, float hi) { f32x2_t v = {lo, hi}; bf16x2_t b = __builtin_convertvector(v, bf16x2_t); return __builtin_bit_cast(unsigned, b); }
;     __device__ __forceinline__ void operator()(const f32x4 (&acc)[2][2][4][2], const Unit& u, int wr, int wc, int fr, int fq) const {
;     ...
;             for (int m = 0; m < 4; ++m) {
;                 const size_t off = (size_t)(row0 + ai * 128 + m * 16) * ldc + col0;
;                 float ssq = 0.f;
; #pragma unroll
;                 for (int bj = 0; bj < 2; ++bj) {
;                     f32x4 b0, b1;
;                     if (BASE_F32) { b0 = bs[m][bj][0]; b1 = bs[m][bj][1]; }
;                     else { const u32x4 h = bh[m][bj];
;                         b0 = (f32x4){__builtin_bit_cast(float, h.x << 16), __builtin_bit_cast(float, h.x & 0xffff0000u), __builtin_bit_cast(float, h.y << 16), __builtin_bit_cast(float, h.y & 0xffff0000u)};
;                         b1 = (f32x4){__builtin_bit_cast(float, h.z << 16), __builtin_bit_cast(float, h.z & 0xffff0000u), __builtin_bit_cast(float, h.w << 16), __builtin_bit_cast(float, h.w & 0xffff0000u)}; }
;                     const f32x4 v0 = b0 + acc[ai][bj][m][0], v1 = b1 + acc[ai][bj][m][1];
;                     ssq += ((v0[0] * v0[0] + v0[1] * v0[1]) + (v0[2] * v0[2] + v0[3] * v0[3])) + ((v1[0] * v1[0] + v1[1] * v1[1]) + (v1[2] * v1[2] + v1[3] * v1[3]));
;                     u32x4 w; w.x = pk2(v0[0], v0[1]); w.y = pk2(v0[2], v0[3]); w.z = pk2(v1[0], v1[1]); w.w = pk2(v1[2], v1[3]); *(GAS_ u32x4*)(XB + off + bj * 128) = w;
;                 }
;                 ssq += __shfl_xor(ssq, 16); ssq += __shfl_xor(ssq, 32);
;                 if (fq == 0) *(GAS_ float*)(SS + (size_t)(row0 + ai * 128 + m * 16) * 16 + u.pn * 4 + wc) = ssq;
;             }
.LBB0_1158:
	s_or_b64 exec, exec, s[24:25]
	v_lshlrev_b32_e32 v130, 16, v164
	v_and_b32_e32 v131, 0xffff0000, v164
	v_lshlrev_b32_e32 v132, 16, v165
	v_and_b32_e32 v133, 0xffff0000, v165
	v_lshlrev_b32_e32 v134, 16, v166
	v_and_b32_e32 v135, 0xffff0000, v166
	v_lshlrev_b32_e32 v136, 16, v167
	v_and_b32_e32 v137, 0xffff0000, v167
	v_pk_add_f32 v[126:127], v[126:127], v[132:133]
	v_pk_add_f32 v[124:125], v[124:125], v[130:131]
	v_pk_add_f32 v[130:131], v[122:123], v[136:137]
	v_pk_add_f32 v[122:123], v[120:121], v[134:135]
	v_mul_f32_e32 v120, v125, v125
	v_mul_f32_e32 v121, v127, v127
	v_fmac_f32_e32 v120, v124, v124
	v_fmac_f32_e32 v121, v126, v126
	v_add_f32_e32 v120, v120, v121
	v_mul_f32_e32 v121, v123, v123
	v_mul_f32_e32 v132, v131, v131
	v_fmac_f32_e32 v121, v122, v122
	v_fmac_f32_e32 v132, v130, v130
	v_add_f32_e32 v121, v121, v132
	v_add_f32_e32 v134, v120, v121
	v_cvt_pk_bf16_f32 v120, v124, v125
	v_cvt_pk_bf16_f32 v121, v126, v127
	v_lshlrev_b32_e32 v124, 16, v160
	v_and_b32_e32 v125, 0xffff0000, v160
	v_lshlrev_b32_e32 v126, 16, v161
	v_and_b32_e32 v127, 0xffff0000, v161
	v_cvt_pk_bf16_f32 v122, v122, v123
	v_cvt_pk_bf16_f32 v123, v130, v131
	v_lshlrev_b32_e32 v130, 16, v162
	v_and_b32_e32 v131, 0xffff0000, v162
	v_pk_add_f32 v[118:119], v[118:119], v[126:127]
	v_pk_add_f32 v[116:117], v[116:117], v[124:125]
	v_lshlrev_b32_e32 v132, 16, v163
	v_and_b32_e32 v133, 0xffff0000, v163
	v_pk_add_f32 v[126:127], v[112:113], v[130:131]
	v_mul_f32_e32 v112, v117, v117
	v_mul_f32_e32 v113, v119, v119
	v_pk_add_f32 v[124:125], v[114:115], v[132:133]
	v_fmac_f32_e32 v112, v116, v116
	v_fmac_f32_e32 v113, v118, v118
	v_add_f32_e32 v112, v112, v113
	v_mul_f32_e32 v113, v127, v127
	v_mul_f32_e32 v114, v125, v125
	v_fmac_f32_e32 v113, v126, v126
	v_fmac_f32_e32 v114, v124, v124
	v_add_f32_e32 v113, v113, v114
	v_add_f32_e32 v112, v112, v113
	v_add_f32_e32 v115, v134, v112
	v_mov_b32_e32 v130, v115
	s_nop 1
	v_permlane16_swap_b32_e32 v115, v130
	s_waitcnt lgkmcnt(1)
	v_lshlrev_b64 v[128:129], 10, v[198:199]
	v_lshl_add_u64 v[112:113], v[128:129], 1, s[12:13]
	v_lshl_add_u64 v[128:129], v[188:189], 1, v[112:113]
	v_cvt_pk_bf16_f32 v114, v116, v117
	s_waitcnt lgkmcnt(0)
	v_add_f32_e32 v112, v115, v130
	v_mov_b32_e32 v113, v112
	s_nop 1
	v_permlane32_swap_b32_e32 v112, v113
	v_cvt_pk_bf16_f32 v115, v118, v119
	v_cvt_pk_bf16_f32 v116, v126, v127
	v_cvt_pk_bf16_f32 v117, v124, v125
	global_store_dwordx4 v[128:129], v[120:123], off
	global_store_dwordx4 v[128:129], v[114:117], off offset:256
	s_and_saveexec_b64 s[24:25], s[6:7]
	s_cbranch_execz .LBB0_1160
	v_readlane_b32 s44, v254, 18
	v_readlane_b32 s45, v254, 19
	v_lshlrev_b64 v[114:115], 6, v[198:199]
	s_mov_b32 s5, s45
	v_lshl_add_u64 v[114:115], s[14:15], 0, v[114:115]
	v_readlane_b32 s46, v254, 20
	v_readlane_b32 s47, v254, 21
	v_readlane_b32 s48, v254, 22
	v_readlane_b32 s49, v254, 23
	v_readlane_b32 s50, v254, 24
	v_readlane_b32 s51, v254, 25
	v_readlane_b32 s52, v254, 26
	v_readlane_b32 s53, v254, 27
	v_readlane_b32 s54, v254, 28
	v_readlane_b32 s55, v254, 29
	v_readlane_b32 s56, v254, 30
	v_readlane_b32 s57, v254, 31
	v_readlane_b32 s58, v254, 32
	v_readlane_b32 s59, v254, 33
	v_writelane_b32 v254, s4, 18
	v_lshl_add_u64 v[114:115], s[22:23], 2, v[114:115]
	s_lshl_b32 s44, s37, 2
	v_writelane_b32 v254, s5, 19
	v_writelane_b32 v254, s6, 20
	v_writelane_b32 v254, s7, 21
	v_writelane_b32 v254, s8, 22
	v_writelane_b32 v254, s9, 23
	v_writelane_b32 v254, s10, 24
	v_writelane_b32 v254, s11, 25
	v_writelane_b32 v254, s12, 26
	v_writelane_b32 v254, s13, 27
	v_writelane_b32 v254, s14, 28
	v_writelane_b32 v254, s15, 29
	v_writelane_b32 v254, s16, 30
	v_writelane_b32 v254, s17, 31
	v_writelane_b32 v254, s18, 32
	s_mov_b32 s52, 0xff800000
	v_writelane_b32 v254, s19, 33
	v_lshl_add_u64 v[114:115], v[114:115], 0, s[44:45]
	s_waitcnt lgkmcnt(0)
	v_add_f32_e32 v112, v112, v113
	global_store_dword v[114:115], v112, off
.LBB0_1160:
	s_or_b64 exec, exec, s[24:25]
	v_lshlrev_b32_e32 v114, 16, v156
	v_and_b32_e32 v115, 0xffff0000, v156
	v_lshlrev_b32_e32 v116, 16, v157
	v_and_b32_e32 v117, 0xffff0000, v157
	v_lshlrev_b32_e32 v118, 16, v158
	v_and_b32_e32 v119, 0xffff0000, v158
	v_lshlrev_b32_e32 v120, 16, v159
	v_and_b32_e32 v121, 0xffff0000, v159
	v_pk_add_f32 v[110:111], v[110:111], v[116:117]
	v_pk_add_f32 v[108:109], v[108:109], v[114:115]
	v_pk_add_f32 v[114:115], v[106:107], v[120:121]
	v_pk_add_f32 v[106:107], v[104:105], v[118:119]
	v_mul_f32_e32 v104, v109, v109
	v_mul_f32_e32 v105, v111, v111
	v_fmac_f32_e32 v104, v108, v108
	v_fmac_f32_e32 v105, v110, v110
	v_add_f32_e32 v104, v104, v105
	v_mul_f32_e32 v105, v107, v107
	v_mul_f32_e32 v116, v115, v115
	v_fmac_f32_e32 v105, v106, v106
	v_fmac_f32_e32 v116, v114, v114
	v_add_f32_e32 v105, v105, v116
	v_add_f32_e32 v118, v104, v105
	v_cvt_pk_bf16_f32 v104, v108, v109
	v_cvt_pk_bf16_f32 v105, v110, v111
	v_lshlrev_b32_e32 v108, 16, v152
	v_and_b32_e32 v109, 0xffff0000, v152
	v_lshlrev_b32_e32 v110, 16, v153
	v_and_b32_e32 v111, 0xffff0000, v153
	v_cvt_pk_bf16_f32 v106, v106, v107
	v_cvt_pk_bf16_f32 v107, v114, v115
	v_lshlrev_b32_e32 v114, 16, v154
	v_and_b32_e32 v115, 0xffff0000, v154
	v_pk_add_f32 v[102:103], v[102:103], v[110:111]
	v_pk_add_f32 v[100:101], v[100:101], v[108:109]
	v_lshlrev_b32_e32 v116, 16, v155
	v_and_b32_e32 v117, 0xffff0000, v155
	v_pk_add_f32 v[110:111], v[96:97], v[114:115]
	v_mul_f32_e32 v96, v101, v101
	v_mul_f32_e32 v97, v103, v103
	v_pk_add_f32 v[108:109], v[98:99], v[116:117]
	v_fmac_f32_e32 v96, v100, v100
	v_fmac_f32_e32 v97, v102, v102
	v_add_f32_e32 v96, v96, v97
	v_mul_f32_e32 v97, v111, v111
	v_mul_f32_e32 v98, v109, v109
	v_fmac_f32_e32 v97, v110, v110
	v_fmac_f32_e32 v98, v108, v108
	v_add_f32_e32 v97, v97, v98
	v_add_f32_e32 v96, v96, v97
	v_add_f32_e32 v99, v118, v96
	v_mov_b32_e32 v114, v99
	s_nop 1
	v_permlane16_swap_b32_e32 v99, v114
	s_waitcnt lgkmcnt(1)
	v_lshlrev_b64 v[112:113], 10, v[196:197]
	v_lshl_add_u64 v[96:97], v[112:113], 1, s[12:13]
	v_lshl_add_u64 v[112:113], v[188:189], 1, v[96:97]
	v_cvt_pk_bf16_f32 v98, v100, v101
	s_waitcnt lgkmcnt(0)
	v_add_f32_e32 v96, v99, v114
	v_mov_b32_e32 v97, v96
	s_nop 1
	v_permlane32_swap_b32_e32 v96, v97
	v_cvt_pk_bf16_f32 v99, v102, v103
	v_cvt_pk_bf16_f32 v100, v110, v111
	v_cvt_pk_bf16_f32 v101, v108, v109
	global_store_dwordx4 v[112:113], v[104:107], off
	global_store_dwordx4 v[112:113], v[98:101], off offset:256
	s_and_saveexec_b64 s[24:25], s[6:7]
	s_cbranch_execz .LBB0_1162
; #define GAS_ __attribute__((address_space(1)))
; __device__ __forceinline__ unsigned pk2(float lo, float hi) { f32x2_t v = {lo, hi}; bf16x2_t b = __builtin_convertvector(v, bf16x2_t); return __builtin_bit_cast(unsigned, b); }
;     __device__ __forceinline__ void operator()(const f32x4 (&acc)[2][2][4][2], const Unit& u, int wr, int wc, int fr, int fq) const {
;     ...
;             for (int m = 0; m < 4; ++m) {
;                 const size_t off = (size_t)(row0 + ai * 128 + m * 16) * ldc + col0;
;                 float ssq = 0.f;
; #pragma unroll
;                 for (int bj = 0; bj < 2; ++bj) {
;                     f32x4 b0, b1;
;                     if (BASE_F32) { b0 = bs[m][bj][0]; b1 = bs[m][bj][1]; }
;                     else { const u32x4 h = bh[m][bj];
;                         b0 = (f32x4){__builtin_bit_cast(float, h.x << 16), __builtin_bit_cast(float, h.x & 0xffff0000u), __builtin_bit_cast(float, h.y << 16), __builtin_bit_cast(float, h.y & 0xffff0000u)};
;                         b1 = (f32x4){__builtin_bit_cast(float, h.z << 16), __builtin_bit_cast(float, h.z & 0xffff0000u), __builtin_bit_cast(float, h.w << 16), __builtin_bit_cast(float, h.w & 0xffff0000u)}; }
;                     const f32x4 v0 = b0 + acc[ai][bj][m][0], v1 = b1 + acc[ai][bj][m][1];
;                     ssq += ((v0[0] * v0[0] + v0[1] * v0[1]) + (v0[2] * v0[2] + v0[3] * v0[3])) + ((v1[0] * v1[0] + v1[1] * v1[1]) + (v1[2] * v1[2] + v1[3] * v1[3]));
;                     u32x4 w; w.x = pk2(v0[0], v0[1]); w.y = pk2(v0[2], v0[3]); w.z = pk2(v1[0], v1[1]); w.w = pk2(v1[2], v1[3]); *(GAS_ u32x4*)(XB + off + bj * 128) = w;
;                 }
;                 ssq += __shfl_xor(ssq, 16); ssq += __shfl_xor(ssq, 32);
;                 if (fq == 0) *(GAS_ float*)(SS + (size_t)(row0 + ai * 128 + m * 16) * 16 + u.pn * 4 + wc) = ssq;
;             }
	v_readlane_b32 s44, v254, 18
	v_readlane_b32 s45, v254, 19
	v_lshlrev_b64 v[98:99], 6, v[196:197]
	s_mov_b32 s5, s45
	v_lshl_add_u64 v[98:99], s[14:15], 0, v[98:99]
	v_readlane_b32 s46, v254, 20
	v_readlane_b32 s47, v254, 21
	v_readlane_b32 s48, v254, 22
	v_readlane_b32 s49, v254, 23
	v_readlane_b32 s50, v254, 24
	v_readlane_b32 s51, v254, 25
	v_readlane_b32 s52, v254, 26
	v_readlane_b32 s53, v254, 27
	v_readlane_b32 s54, v254, 28
	v_readlane_b32 s55, v254, 29
	v_readlane_b32 s56, v254, 30
	v_readlane_b32 s57, v254, 31
	v_readlane_b32 s58, v254, 32
	v_readlane_b32 s59, v254, 33
	v_writelane_b32 v254, s4, 18
	v_lshl_add_u64 v[98:99], s[22:23], 2, v[98:99]
	s_lshl_b32 s44, s37, 2
	v_writelane_b32 v254, s5, 19
	v_writelane_b32 v254, s6, 20
	v_writelane_b32 v254, s7, 21
	v_writelane_b32 v254, s8, 22
	v_writelane_b32 v254, s9, 23
	v_writelane_b32 v254, s10, 24
	v_writelane_b32 v254, s11, 25
	v_writelane_b32 v254, s12, 26
	v_writelane_b32 v254, s13, 27
	v_writelane_b32 v254, s14, 28
	v_writelane_b32 v254, s15, 29
	v_writelane_b32 v254, s16, 30
	v_writelane_b32 v254, s17, 31
	v_writelane_b32 v254, s18, 32
	s_mov_b32 s52, 0xff800000
	v_writelane_b32 v254, s19, 33
	v_lshl_add_u64 v[98:99], v[98:99], 0, s[44:45]
	s_waitcnt lgkmcnt(0)
	v_add_f32_e32 v96, v96, v97
	global_store_dword v[98:99], v96, off
.LBB0_1162:
	s_or_b64 exec, exec, s[24:25]
	v_lshlrev_b32_e32 v98, 16, v148
	v_and_b32_e32 v99, 0xffff0000, v148
	v_lshlrev_b32_e32 v100, 16, v149
	v_and_b32_e32 v101, 0xffff0000, v149
	v_lshlrev_b32_e32 v102, 16, v150
	v_and_b32_e32 v103, 0xffff0000, v150
	v_lshlrev_b32_e32 v104, 16, v151
	v_and_b32_e32 v105, 0xffff0000, v151
	v_pk_add_f32 v[94:95], v[94:95], v[100:101]
	v_pk_add_f32 v[92:93], v[92:93], v[98:99]
	v_pk_add_f32 v[98:99], v[90:91], v[104:105]
	v_pk_add_f32 v[90:91], v[88:89], v[102:103]
	v_mul_f32_e32 v88, v93, v93
	v_mul_f32_e32 v89, v95, v95
	v_fmac_f32_e32 v88, v92, v92
	v_fmac_f32_e32 v89, v94, v94
	v_add_f32_e32 v88, v88, v89
	v_mul_f32_e32 v89, v91, v91
	v_mul_f32_e32 v100, v99, v99
	v_fmac_f32_e32 v89, v90, v90
	v_fmac_f32_e32 v100, v98, v98
	v_add_f32_e32 v89, v89, v100
	v_add_f32_e32 v102, v88, v89
	v_cvt_pk_bf16_f32 v88, v92, v93
	v_cvt_pk_bf16_f32 v89, v94, v95
	v_lshlrev_b32_e32 v92, 16, v144
	v_and_b32_e32 v93, 0xffff0000, v144
	v_lshlrev_b32_e32 v94, 16, v145
	v_and_b32_e32 v95, 0xffff0000, v145
	v_cvt_pk_bf16_f32 v90, v90, v91
	v_cvt_pk_bf16_f32 v91, v98, v99
	v_lshlrev_b32_e32 v98, 16, v146
	v_and_b32_e32 v99, 0xffff0000, v146
	v_pk_add_f32 v[86:87], v[86:87], v[94:95]
	v_pk_add_f32 v[84:85], v[84:85], v[92:93]
	v_lshlrev_b32_e32 v100, 16, v147
	v_and_b32_e32 v101, 0xffff0000, v147
	v_pk_add_f32 v[94:95], v[80:81], v[98:99]
	v_mul_f32_e32 v80, v85, v85
	v_mul_f32_e32 v81, v87, v87
	v_pk_add_f32 v[92:93], v[82:83], v[100:101]
	v_fmac_f32_e32 v80, v84, v84
	v_fmac_f32_e32 v81, v86, v86
	v_add_f32_e32 v80, v80, v81
	v_mul_f32_e32 v81, v95, v95
	v_mul_f32_e32 v82, v93, v93
	v_fmac_f32_e32 v81, v94, v94
	v_fmac_f32_e32 v82, v92, v92
	v_add_f32_e32 v81, v81, v82
	v_add_f32_e32 v80, v80, v81
	v_add_f32_e32 v83, v102, v80
	v_mov_b32_e32 v98, v83
	s_nop 1
	v_permlane16_swap_b32_e32 v83, v98
	s_waitcnt lgkmcnt(1)
	v_lshlrev_b64 v[96:97], 10, v[194:195]
	v_lshl_add_u64 v[80:81], v[96:97], 1, s[12:13]
	v_lshl_add_u64 v[96:97], v[188:189], 1, v[80:81]
	v_cvt_pk_bf16_f32 v82, v84, v85
	s_waitcnt lgkmcnt(0)
	v_add_f32_e32 v80, v83, v98
	v_mov_b32_e32 v81, v80
	s_nop 1
	v_permlane32_swap_b32_e32 v80, v81
	v_cvt_pk_bf16_f32 v83, v86, v87
	v_cvt_pk_bf16_f32 v84, v94, v95
	v_cvt_pk_bf16_f32 v85, v92, v93
	global_store_dwordx4 v[96:97], v[88:91], off
	global_store_dwordx4 v[96:97], v[82:85], off offset:256
	s_and_saveexec_b64 s[24:25], s[6:7]
	s_cbranch_execz .LBB0_1164
	v_readlane_b32 s44, v254, 18
	v_readlane_b32 s45, v254, 19
	v_lshlrev_b64 v[82:83], 6, v[194:195]
	s_mov_b32 s5, s45
	v_lshl_add_u64 v[82:83], s[14:15], 0, v[82:83]
	v_readlane_b32 s46, v254, 20
	v_readlane_b32 s47, v254, 21
	v_readlane_b32 s48, v254, 22
	v_readlane_b32 s49, v254, 23
	v_readlane_b32 s50, v254, 24
	v_readlane_b32 s51, v254, 25
	v_readlane_b32 s52, v254, 26
	v_readlane_b32 s53, v254, 27
	v_readlane_b32 s54, v254, 28
	v_readlane_b32 s55, v254, 29
	v_readlane_b32 s56, v254, 30
	v_readlane_b32 s57, v254, 31
	v_readlane_b32 s58, v254, 32
	v_readlane_b32 s59, v254, 33
	v_writelane_b32 v254, s4, 18
	v_lshl_add_u64 v[82:83], s[22:23], 2, v[82:83]
	s_lshl_b32 s44, s37, 2
	v_writelane_b32 v254, s5, 19
	v_writelane_b32 v254, s6, 20
	v_writelane_b32 v254, s7, 21
	v_writelane_b32 v254, s8, 22
	v_writelane_b32 v254, s9, 23
	v_writelane_b32 v254, s10, 24
	v_writelane_b32 v254, s11, 25
	v_writelane_b32 v254, s12, 26
	v_writelane_b32 v254, s13, 27
	v_writelane_b32 v254, s14, 28
	v_writelane_b32 v254, s15, 29
	v_writelane_b32 v254, s16, 30
	v_writelane_b32 v254, s17, 31
	v_writelane_b32 v254, s18, 32
	s_mov_b32 s52, 0xff800000
	v_writelane_b32 v254, s19, 33
	v_lshl_add_u64 v[82:83], v[82:83], 0, s[44:45]
	s_waitcnt lgkmcnt(0)
	v_add_f32_e32 v80, v80, v81
	global_store_dword v[82:83], v80, off
; #define GAS_ __attribute__((address_space(1)))
;     __device__ __forceinline__ void operator()(const f32x4 (&acc)[2][2][4][2], const Unit& u, int wr, int wc, int fr, int fq) const {
;     ...
;         for (int ai = 0; ai < 2; ++ai) {
;             f32x4 bs[4][2][2]; u32x4 bh[4][2];
; #pragma unroll
;             for (int m = 0; m < 4; ++m) { const size_t off = (size_t)(row0 + ai * 128 + m * 16) * ldc + col0;
; #pragma unroll
;                 for (int bj = 0; bj < 2; ++bj) {
;                     if (BASE_F32) { bs[m][bj][0] = *(const GAS_ f32x4*)(basef + off + bj * 128); bs[m][bj][1] = *(const GAS_ f32x4*)(basef + off + bj * 128 + 4); }
;                     else bh[m][bj] = *(const GAS_ u32x4*)(XB + off + bj * 128); } }
;             asm volatile("" ::: "memory");
; #pragma unroll
;             for (int m = 0; m < 4; ++m) {
;                 const size_t off = (size_t)(row0 + ai * 128 + m * 16) * ldc + col0;
;                 float ssq = 0.f;
; #pragma unroll
;                 for (int bj = 0; bj < 2; ++bj) {
;                     f32x4 b0, b1;
;                     if (BASE_F32) { b0 = bs[m][bj][0]; b1 = bs[m][bj][1]; }
;                     else { const u32x4 h = bh[m][bj];
;                         b0 = (f32x4){__builtin_bit_cast(float, h.x << 16), __builtin_bit_cast(float, h.x & 0xffff0000u), __builtin_bit_cast(float, h.y << 16), __builtin_bit_cast(float, h.y & 0xffff0000u)};
;                         b1 = (f32x4){__builtin_bit_cast(float, h.z << 16), __builtin_bit_cast(float, h.z & 0xffff0000u), __builtin_bit_cast(float, h.w << 16), __builtin_bit_cast(float, h.w & 0xffff0000u)}; }
;                     const f32x4 v0 = b0 + acc[ai][bj][m][0], v1 = b1 + acc[ai][bj][m][1];
;                     ssq += ((v0[0] * v0[0] + v0[1] * v0[1]) + (v0[2] * v0[2] + v0[3] * v0[3])) + ((v1[0] * v1[0] + v1[1] * v1[1]) + (v1[2] * v1[2] + v1[3] * v1[3]));
;                     u32x4 w; w.x = pk2(v0[0], v0[1]); w.y = pk2(v0[2], v0[3]); w.z = pk2(v1[0], v1[1]); w.w = pk2(v1[2], v1[3]); *(GAS_ u32x4*)(XB + off + bj * 128) = w;
;                 }
;                 ssq += __shfl_xor(ssq, 16); ssq += __shfl_xor(ssq, 32);
;                 if (fq == 0) *(GAS_ float*)(SS + (size_t)(row0 + ai * 128 + m * 16) * 16 + u.pn * 4 + wc) = ssq;
;             }
.LBB0_1164:
	s_or_b64 exec, exec, s[24:25]
	v_add_u32_e32 v110, 0x80, v192
	v_ashrrev_i32_e32 v111, 31, v110
	v_lshlrev_b64 v[120:121], 11, v[110:111]
	s_waitcnt lgkmcnt(0)
	v_lshl_add_u64 v[80:81], v[190:191], 0, v[120:121]
	global_load_dwordx4 v[112:115], v[80:81], off
	global_load_dwordx4 v[116:119], v[80:81], off offset:256
	v_add_u32_e32 v108, 0x90, v192
	v_ashrrev_i32_e32 v109, 31, v108
	v_lshlrev_b64 v[80:81], 11, v[108:109]
	v_add_u32_e32 v106, 0xa0, v192
	v_lshl_add_u64 v[80:81], v[190:191], 0, v[80:81]
	v_ashrrev_i32_e32 v107, 31, v106
	global_load_dwordx4 v[100:103], v[80:81], off
	global_load_dwordx4 v[96:99], v[80:81], off offset:256
	v_lshlrev_b64 v[80:81], 11, v[106:107]
	v_add_u32_e32 v104, 0xb0, v192
	v_lshl_add_u64 v[80:81], v[190:191], 0, v[80:81]
	v_ashrrev_i32_e32 v105, 31, v104
	global_load_dwordx4 v[92:95], v[80:81], off
	global_load_dwordx4 v[88:91], v[80:81], off offset:256
	v_lshlrev_b64 v[80:81], 11, v[104:105]
	v_lshl_add_u64 v[80:81], v[190:191], 0, v[80:81]
	global_load_dwordx4 v[84:87], v[80:81], off
	s_nop 0
	global_load_dwordx4 v[80:83], v[80:81], off offset:256
	s_waitcnt vmcnt(7)
	v_lshlrev_b32_e32 v122, 16, v112
	v_and_b32_e32 v123, 0xffff0000, v112
	v_lshlrev_b32_e32 v112, 16, v113
	v_and_b32_e32 v113, 0xffff0000, v113
	v_lshlrev_b32_e32 v124, 16, v114
	v_and_b32_e32 v125, 0xffff0000, v114
	v_lshlrev_b32_e32 v114, 16, v115
	v_and_b32_e32 v115, 0xffff0000, v115
	v_pk_add_f32 v[78:79], v[78:79], v[112:113]
	v_pk_add_f32 v[76:77], v[76:77], v[122:123]
	v_pk_add_f32 v[112:113], v[74:75], v[114:115]
	v_mul_f32_e32 v74, v77, v77
	v_mul_f32_e32 v75, v79, v79
	v_pk_add_f32 v[72:73], v[72:73], v[124:125]
	v_fmac_f32_e32 v74, v76, v76
	v_fmac_f32_e32 v75, v78, v78
	v_add_f32_e32 v74, v74, v75
	v_mul_f32_e32 v75, v73, v73
	v_mul_f32_e32 v114, v113, v113
	v_fmac_f32_e32 v75, v72, v72
	v_fmac_f32_e32 v114, v112, v112
	v_add_f32_e32 v75, v75, v114
	v_add_f32_e32 v114, v74, v75
	v_cvt_pk_bf16_f32 v74, v76, v77
	v_cvt_pk_bf16_f32 v76, v72, v73
	v_lshl_add_u64 v[72:73], s[12:13], 0, v[120:121]
	v_cvt_pk_bf16_f32 v75, v78, v79
	v_cvt_pk_bf16_f32 v77, v112, v113
	v_lshl_add_u64 v[72:73], v[188:189], 1, v[72:73]
	global_store_dwordx4 v[72:73], v[74:77], off
	s_waitcnt vmcnt(7)
	v_lshlrev_b32_e32 v78, 16, v118
	v_and_b32_e32 v79, 0xffff0000, v118
	v_lshlrev_b32_e32 v74, 16, v116
	v_and_b32_e32 v75, 0xffff0000, v116
	v_lshlrev_b32_e32 v76, 16, v117
	v_and_b32_e32 v77, 0xffff0000, v117
	v_lshlrev_b32_e32 v112, 16, v119
	v_and_b32_e32 v113, 0xffff0000, v119
	v_pk_add_f32 v[70:71], v[70:71], v[76:77]
	v_pk_add_f32 v[68:69], v[68:69], v[74:75]
	v_pk_add_f32 v[74:75], v[66:67], v[112:113]
	v_pk_add_f32 v[66:67], v[64:65], v[78:79]
	v_mul_f32_e32 v64, v69, v69
	v_mul_f32_e32 v65, v71, v71
	v_fmac_f32_e32 v64, v68, v68
	v_fmac_f32_e32 v65, v70, v70
	v_add_f32_e32 v64, v64, v65
	v_mul_f32_e32 v65, v67, v67
	v_mul_f32_e32 v76, v75, v75
	v_fmac_f32_e32 v65, v66, v66
	v_fmac_f32_e32 v76, v74, v74
	v_add_f32_e32 v65, v65, v76
	v_add_f32_e32 v64, v64, v65
	v_add_f32_e32 v76, v114, v64
	v_cvt_pk_bf16_f32 v64, v68, v69
	v_cvt_pk_bf16_f32 v65, v70, v71
	v_cvt_pk_bf16_f32 v66, v66, v67
	v_cvt_pk_bf16_f32 v67, v74, v75
	global_store_dwordx4 v[72:73], v[64:67], off offset:256
	s_nop 1
	v_mov_b32_e32 v64, v76
	s_nop 1
	v_permlane16_swap_b32_e32 v76, v64
	s_waitcnt lgkmcnt(0)
	v_add_f32_e32 v64, v76, v64
	v_mov_b32_e32 v65, v64
	s_nop 1
	v_permlane32_swap_b32_e32 v64, v65
	s_and_saveexec_b64 s[24:25], s[6:7]
	s_cbranch_execz .LBB0_1166
	v_readlane_b32 s44, v254, 18
	v_readlane_b32 s45, v254, 19
	v_lshlrev_b64 v[66:67], 6, v[110:111]
	s_mov_b32 s5, s45
	v_lshl_add_u64 v[66:67], s[14:15], 0, v[66:67]
	v_readlane_b32 s46, v254, 20
	v_readlane_b32 s47, v254, 21
	v_readlane_b32 s48, v254, 22
	v_readlane_b32 s49, v254, 23
	v_readlane_b32 s50, v254, 24
	v_readlane_b32 s51, v254, 25
	v_readlane_b32 s52, v254, 26
	v_readlane_b32 s53, v254, 27
	v_readlane_b32 s54, v254, 28
	v_readlane_b32 s55, v254, 29
	v_readlane_b32 s56, v254, 30
	v_readlane_b32 s57, v254, 31
	v_readlane_b32 s58, v254, 32
	v_readlane_b32 s59, v254, 33
	v_writelane_b32 v254, s4, 18
	v_lshl_add_u64 v[66:67], s[22:23], 2, v[66:67]
	s_lshl_b32 s44, s37, 2
	v_writelane_b32 v254, s5, 19
	v_writelane_b32 v254, s6, 20
	v_writelane_b32 v254, s7, 21
	v_writelane_b32 v254, s8, 22
	v_writelane_b32 v254, s9, 23
	v_writelane_b32 v254, s10, 24
	v_writelane_b32 v254, s11, 25
	v_writelane_b32 v254, s12, 26
	v_writelane_b32 v254, s13, 27
	v_writelane_b32 v254, s14, 28
	v_writelane_b32 v254, s15, 29
	v_writelane_b32 v254, s16, 30
	v_writelane_b32 v254, s17, 31
	v_writelane_b32 v254, s18, 32
	s_mov_b32 s52, 0xff800000
	v_writelane_b32 v254, s19, 33
	v_lshl_add_u64 v[66:67], v[66:67], 0, s[44:45]
	s_waitcnt lgkmcnt(0)
	v_add_f32_e32 v64, v64, v65
	global_store_dword v[66:67], v64, off
; #define GAS_ __attribute__((address_space(1)))
; __device__ __forceinline__ unsigned pk2(float lo, float hi) { f32x2_t v = {lo, hi}; bf16x2_t b = __builtin_convertvector(v, bf16x2_t); return __builtin_bit_cast(unsigned, b); }
;     __device__ __forceinline__ void operator()(const f32x4 (&acc)[2][2][4][2], const Unit& u, int wr, int wc, int fr, int fq) const {
;     ...
;             for (int m = 0; m < 4; ++m) {
;                 const size_t off = (size_t)(row0 + ai * 128 + m * 16) * ldc + col0;
;                 float ssq = 0.f;
; #pragma unroll
;                 for (int bj = 0; bj < 2; ++bj) {
;                     f32x4 b0, b1;
;                     if (BASE_F32) { b0 = bs[m][bj][0]; b1 = bs[m][bj][1]; }
;                     else { const u32x4 h = bh[m][bj];
;                         b0 = (f32x4){__builtin_bit_cast(float, h.x << 16), __builtin_bit_cast(float, h.x & 0xffff0000u), __builtin_bit_cast(float, h.y << 16), __builtin_bit_cast(float, h.y & 0xffff0000u)};
;                         b1 = (f32x4){__builtin_bit_cast(float, h.z << 16), __builtin_bit_cast(float, h.z & 0xffff0000u), __builtin_bit_cast(float, h.w << 16), __builtin_bit_cast(float, h.w & 0xffff0000u)}; }
;                     const f32x4 v0 = b0 + acc[ai][bj][m][0], v1 = b1 + acc[ai][bj][m][1];
;                     ssq += ((v0[0] * v0[0] + v0[1] * v0[1]) + (v0[2] * v0[2] + v0[3] * v0[3])) + ((v1[0] * v1[0] + v1[1] * v1[1]) + (v1[2] * v1[2] + v1[3] * v1[3]));
;                     u32x4 w; w.x = pk2(v0[0], v0[1]); w.y = pk2(v0[2], v0[3]); w.z = pk2(v1[0], v1[1]); w.w = pk2(v1[2], v1[3]); *(GAS_ u32x4*)(XB + off + bj * 128) = w;
;                 }
;                 ssq += __shfl_xor(ssq, 16); ssq += __shfl_xor(ssq, 32);
;                 if (fq == 0) *(GAS_ float*)(SS + (size_t)(row0 + ai * 128 + m * 16) * 16 + u.pn * 4 + wc) = ssq;
;             }
.LBB0_1166:
	s_or_b64 exec, exec, s[24:25]
	s_waitcnt vmcnt(7)
	v_lshlrev_b32_e32 v66, 16, v100
	v_and_b32_e32 v67, 0xffff0000, v100
	v_lshlrev_b32_e32 v68, 16, v101
	v_and_b32_e32 v69, 0xffff0000, v101
	v_lshlrev_b32_e32 v70, 16, v102
	v_and_b32_e32 v71, 0xffff0000, v102
	v_lshlrev_b32_e32 v72, 16, v103
	v_and_b32_e32 v73, 0xffff0000, v103
	v_pk_add_f32 v[62:63], v[62:63], v[68:69]
	v_pk_add_f32 v[60:61], v[60:61], v[66:67]
	v_pk_add_f32 v[66:67], v[58:59], v[72:73]
	v_pk_add_f32 v[58:59], v[56:57], v[70:71]
	v_mul_f32_e32 v56, v61, v61
	v_mul_f32_e32 v57, v63, v63
	v_fmac_f32_e32 v56, v60, v60
	v_fmac_f32_e32 v57, v62, v62
	v_add_f32_e32 v56, v56, v57
	v_mul_f32_e32 v57, v59, v59
	v_mul_f32_e32 v68, v67, v67
	v_fmac_f32_e32 v57, v58, v58
	v_fmac_f32_e32 v68, v66, v66
	v_add_f32_e32 v57, v57, v68
	v_add_f32_e32 v70, v56, v57
	v_cvt_pk_bf16_f32 v56, v60, v61
	v_cvt_pk_bf16_f32 v57, v62, v63
	s_waitcnt vmcnt(6)
	v_lshlrev_b32_e32 v60, 16, v96
	v_and_b32_e32 v61, 0xffff0000, v96
	v_lshlrev_b32_e32 v62, 16, v97
	v_and_b32_e32 v63, 0xffff0000, v97
	v_cvt_pk_bf16_f32 v58, v58, v59
	v_cvt_pk_bf16_f32 v59, v66, v67
	v_lshlrev_b32_e32 v66, 16, v98
	v_and_b32_e32 v67, 0xffff0000, v98
	v_pk_add_f32 v[54:55], v[54:55], v[62:63]
	v_pk_add_f32 v[52:53], v[52:53], v[60:61]
	v_lshlrev_b32_e32 v68, 16, v99
	v_and_b32_e32 v69, 0xffff0000, v99
	v_pk_add_f32 v[62:63], v[48:49], v[66:67]
	v_mul_f32_e32 v48, v53, v53
	v_mul_f32_e32 v49, v55, v55
	v_pk_add_f32 v[60:61], v[50:51], v[68:69]
	v_fmac_f32_e32 v48, v52, v52
	v_fmac_f32_e32 v49, v54, v54
	v_add_f32_e32 v48, v48, v49
	v_mul_f32_e32 v49, v63, v63
	v_mul_f32_e32 v50, v61, v61
	v_fmac_f32_e32 v49, v62, v62
	v_fmac_f32_e32 v50, v60, v60
	v_add_f32_e32 v49, v49, v50
	v_add_f32_e32 v48, v48, v49
	v_add_f32_e32 v51, v70, v48
	v_mov_b32_e32 v66, v51
	s_nop 1
	v_permlane16_swap_b32_e32 v51, v66
	s_waitcnt lgkmcnt(1)
	v_lshlrev_b64 v[64:65], 10, v[108:109]
	v_lshl_add_u64 v[48:49], v[64:65], 1, s[12:13]
	v_lshl_add_u64 v[64:65], v[188:189], 1, v[48:49]
	v_cvt_pk_bf16_f32 v50, v52, v53
	s_waitcnt lgkmcnt(0)
	v_add_f32_e32 v48, v51, v66
	v_mov_b32_e32 v49, v48
	s_nop 1
	v_permlane32_swap_b32_e32 v48, v49
	v_cvt_pk_bf16_f32 v51, v54, v55
	v_cvt_pk_bf16_f32 v52, v62, v63
	v_cvt_pk_bf16_f32 v53, v60, v61
	global_store_dwordx4 v[64:65], v[56:59], off
	global_store_dwordx4 v[64:65], v[50:53], off offset:256
	s_and_saveexec_b64 s[24:25], s[6:7]
	s_cbranch_execz .LBB0_1168
	v_readlane_b32 s44, v254, 18
	v_readlane_b32 s45, v254, 19
	v_lshlrev_b64 v[50:51], 6, v[108:109]
	s_mov_b32 s5, s45
	v_lshl_add_u64 v[50:51], s[14:15], 0, v[50:51]
	v_readlane_b32 s46, v254, 20
	v_readlane_b32 s47, v254, 21
	v_readlane_b32 s48, v254, 22
	v_readlane_b32 s49, v254, 23
	v_readlane_b32 s50, v254, 24
	v_readlane_b32 s51, v254, 25
	v_readlane_b32 s52, v254, 26
	v_readlane_b32 s53, v254, 27
	v_readlane_b32 s54, v254, 28
	v_readlane_b32 s55, v254, 29
	v_readlane_b32 s56, v254, 30
	v_readlane_b32 s57, v254, 31
	v_readlane_b32 s58, v254, 32
	v_readlane_b32 s59, v254, 33
	v_writelane_b32 v254, s4, 18
	v_lshl_add_u64 v[50:51], s[22:23], 2, v[50:51]
	s_lshl_b32 s44, s37, 2
	v_writelane_b32 v254, s5, 19
	v_writelane_b32 v254, s6, 20
	v_writelane_b32 v254, s7, 21
	v_writelane_b32 v254, s8, 22
	v_writelane_b32 v254, s9, 23
	v_writelane_b32 v254, s10, 24
	v_writelane_b32 v254, s11, 25
	v_writelane_b32 v254, s12, 26
	v_writelane_b32 v254, s13, 27
	v_writelane_b32 v254, s14, 28
	v_writelane_b32 v254, s15, 29
	v_writelane_b32 v254, s16, 30
	v_writelane_b32 v254, s17, 31
	v_writelane_b32 v254, s18, 32
	s_mov_b32 s52, 0xff800000
	v_writelane_b32 v254, s19, 33
	v_lshl_add_u64 v[50:51], v[50:51], 0, s[44:45]
	s_waitcnt lgkmcnt(0)
	v_add_f32_e32 v48, v48, v49
	global_store_dword v[50:51], v48, off
.LBB0_1168:
	s_or_b64 exec, exec, s[24:25]
	s_waitcnt vmcnt(7)
	v_lshlrev_b32_e32 v50, 16, v92
	v_and_b32_e32 v51, 0xffff0000, v92
	v_lshlrev_b32_e32 v52, 16, v93
	v_and_b32_e32 v53, 0xffff0000, v93
	v_lshlrev_b32_e32 v54, 16, v94
	v_and_b32_e32 v55, 0xffff0000, v94
	v_lshlrev_b32_e32 v56, 16, v95
	v_and_b32_e32 v57, 0xffff0000, v95
	v_pk_add_f32 v[46:47], v[46:47], v[52:53]
	v_pk_add_f32 v[44:45], v[44:45], v[50:51]
	v_pk_add_f32 v[50:51], v[42:43], v[56:57]
	v_pk_add_f32 v[42:43], v[40:41], v[54:55]
	v_mul_f32_e32 v40, v45, v45
	v_mul_f32_e32 v41, v47, v47
	v_fmac_f32_e32 v40, v44, v44
	v_fmac_f32_e32 v41, v46, v46
	v_add_f32_e32 v40, v40, v41
	v_mul_f32_e32 v41, v43, v43
	v_mul_f32_e32 v52, v51, v51
	v_fmac_f32_e32 v41, v42, v42
	v_fmac_f32_e32 v52, v50, v50
	v_add_f32_e32 v41, v41, v52
	v_add_f32_e32 v54, v40, v41
	v_cvt_pk_bf16_f32 v40, v44, v45
	v_cvt_pk_bf16_f32 v41, v46, v47
	s_waitcnt vmcnt(6)
	v_lshlrev_b32_e32 v44, 16, v88
	v_and_b32_e32 v45, 0xffff0000, v88
	v_lshlrev_b32_e32 v46, 16, v89
	v_and_b32_e32 v47, 0xffff0000, v89
	v_cvt_pk_bf16_f32 v42, v42, v43
	v_cvt_pk_bf16_f32 v43, v50, v51
	v_lshlrev_b32_e32 v50, 16, v90
	v_and_b32_e32 v51, 0xffff0000, v90
	v_pk_add_f32 v[38:39], v[38:39], v[46:47]
	v_pk_add_f32 v[36:37], v[36:37], v[44:45]
	v_lshlrev_b32_e32 v52, 16, v91
	v_and_b32_e32 v53, 0xffff0000, v91
	v_pk_add_f32 v[46:47], v[32:33], v[50:51]
	v_mul_f32_e32 v32, v37, v37
	v_mul_f32_e32 v33, v39, v39
	v_pk_add_f32 v[44:45], v[34:35], v[52:53]
	v_fmac_f32_e32 v32, v36, v36
	v_fmac_f32_e32 v33, v38, v38
	v_add_f32_e32 v32, v32, v33
	v_mul_f32_e32 v33, v47, v47
	v_mul_f32_e32 v34, v45, v45
	v_fmac_f32_e32 v33, v46, v46
	v_fmac_f32_e32 v34, v44, v44
	v_add_f32_e32 v33, v33, v34
	v_add_f32_e32 v32, v32, v33
	v_add_f32_e32 v35, v54, v32
	v_mov_b32_e32 v50, v35
	s_nop 1
	v_permlane16_swap_b32_e32 v35, v50
	s_waitcnt lgkmcnt(1)
	v_lshlrev_b64 v[48:49], 10, v[106:107]
	v_lshl_add_u64 v[32:33], v[48:49], 1, s[12:13]
	v_lshl_add_u64 v[48:49], v[188:189], 1, v[32:33]
	v_cvt_pk_bf16_f32 v34, v36, v37
	s_waitcnt lgkmcnt(0)
	v_add_f32_e32 v32, v35, v50
	v_mov_b32_e32 v33, v32
	s_nop 1
	v_permlane32_swap_b32_e32 v32, v33
	v_cvt_pk_bf16_f32 v35, v38, v39
	v_cvt_pk_bf16_f32 v36, v46, v47
	v_cvt_pk_bf16_f32 v37, v44, v45
	global_store_dwordx4 v[48:49], v[40:43], off
	global_store_dwordx4 v[48:49], v[34:37], off offset:256
	s_and_saveexec_b64 s[24:25], s[6:7]
	s_cbranch_execz .LBB0_1170
; #define GAS_ __attribute__((address_space(1)))
; __device__ __forceinline__ unsigned pk2(float lo, float hi) { f32x2_t v = {lo, hi}; bf16x2_t b = __builtin_convertvector(v, bf16x2_t); return __builtin_bit_cast(unsigned, b); }
;     __device__ __forceinline__ void operator()(const f32x4 (&acc)[2][2][4][2], const Unit& u, int wr, int wc, int fr, int fq) const {
;     ...
;             for (int m = 0; m < 4; ++m) {
;                 const size_t off = (size_t)(row0 + ai * 128 + m * 16) * ldc + col0;
;                 float ssq = 0.f;
; #pragma unroll
;                 for (int bj = 0; bj < 2; ++bj) {
;                     f32x4 b0, b1;
;                     if (BASE_F32) { b0 = bs[m][bj][0]; b1 = bs[m][bj][1]; }
;                     else { const u32x4 h = bh[m][bj];
;                         b0 = (f32x4){__builtin_bit_cast(float, h.x << 16), __builtin_bit_cast(float, h.x & 0xffff0000u), __builtin_bit_cast(float, h.y << 16), __builtin_bit_cast(float, h.y & 0xffff0000u)};
;                         b1 = (f32x4){__builtin_bit_cast(float, h.z << 16), __builtin_bit_cast(float, h.z & 0xffff0000u), __builtin_bit_cast(float, h.w << 16), __builtin_bit_cast(float, h.w & 0xffff0000u)}; }
;                     const f32x4 v0 = b0 + acc[ai][bj][m][0], v1 = b1 + acc[ai][bj][m][1];
;                     ssq += ((v0[0] * v0[0] + v0[1] * v0[1]) + (v0[2] * v0[2] + v0[3] * v0[3])) + ((v1[0] * v1[0] + v1[1] * v1[1]) + (v1[2] * v1[2] + v1[3] * v1[3]));
;                     u32x4 w; w.x = pk2(v0[0], v0[1]); w.y = pk2(v0[2], v0[3]); w.z = pk2(v1[0], v1[1]); w.w = pk2(v1[2], v1[3]); *(GAS_ u32x4*)(XB + off + bj * 128) = w;
;                 }
;                 ssq += __shfl_xor(ssq, 16); ssq += __shfl_xor(ssq, 32);
;                 if (fq == 0) *(GAS_ float*)(SS + (size_t)(row0 + ai * 128 + m * 16) * 16 + u.pn * 4 + wc) = ssq;
;             }
	v_readlane_b32 s44, v254, 18
	v_readlane_b32 s45, v254, 19
	v_lshlrev_b64 v[34:35], 6, v[106:107]
	s_mov_b32 s5, s45
	v_lshl_add_u64 v[34:35], s[14:15], 0, v[34:35]
	v_readlane_b32 s46, v254, 20
	v_readlane_b32 s47, v254, 21
	v_readlane_b32 s48, v254, 22
	v_readlane_b32 s49, v254, 23
	v_readlane_b32 s50, v254, 24
	v_readlane_b32 s51, v254, 25
	v_readlane_b32 s52, v254, 26
	v_readlane_b32 s53, v254, 27
	v_readlane_b32 s54, v254, 28
	v_readlane_b32 s55, v254, 29
	v_readlane_b32 s56, v254, 30
	v_readlane_b32 s57, v254, 31
	v_readlane_b32 s58, v254, 32
	v_readlane_b32 s59, v254, 33
	v_writelane_b32 v254, s4, 18
	v_lshl_add_u64 v[34:35], s[22:23], 2, v[34:35]
	s_lshl_b32 s44, s37, 2
	v_writelane_b32 v254, s5, 19
	v_writelane_b32 v254, s6, 20
	v_writelane_b32 v254, s7, 21
	v_writelane_b32 v254, s8, 22
	v_writelane_b32 v254, s9, 23
	v_writelane_b32 v254, s10, 24
	v_writelane_b32 v254, s11, 25
	v_writelane_b32 v254, s12, 26
	v_writelane_b32 v254, s13, 27
	v_writelane_b32 v254, s14, 28
	v_writelane_b32 v254, s15, 29
	v_writelane_b32 v254, s16, 30
	v_writelane_b32 v254, s17, 31
	v_writelane_b32 v254, s18, 32
	s_mov_b32 s52, 0xff800000
	v_writelane_b32 v254, s19, 33
	v_lshl_add_u64 v[34:35], v[34:35], 0, s[44:45]
	s_waitcnt lgkmcnt(0)
	v_add_f32_e32 v32, v32, v33
	global_store_dword v[34:35], v32, off
.LBB0_1170:
	s_or_b64 exec, exec, s[24:25]
	s_waitcnt vmcnt(7)
	v_lshlrev_b32_e32 v34, 16, v84
	v_and_b32_e32 v35, 0xffff0000, v84
	v_lshlrev_b32_e32 v36, 16, v85
	v_and_b32_e32 v37, 0xffff0000, v85
	v_lshlrev_b32_e32 v38, 16, v86
	v_and_b32_e32 v39, 0xffff0000, v86
	v_lshlrev_b32_e32 v40, 16, v87
	v_and_b32_e32 v41, 0xffff0000, v87
	v_pk_add_f32 v[30:31], v[30:31], v[36:37]
	v_pk_add_f32 v[28:29], v[28:29], v[34:35]
	v_pk_add_f32 v[34:35], v[26:27], v[40:41]
	v_pk_add_f32 v[26:27], v[24:25], v[38:39]
	v_mul_f32_e32 v24, v29, v29
	v_mul_f32_e32 v25, v31, v31
	v_fmac_f32_e32 v24, v28, v28
	v_fmac_f32_e32 v25, v30, v30
	v_add_f32_e32 v24, v24, v25
	v_mul_f32_e32 v25, v27, v27
	v_mul_f32_e32 v36, v35, v35
	v_fmac_f32_e32 v25, v26, v26
	v_fmac_f32_e32 v36, v34, v34
	v_add_f32_e32 v25, v25, v36
	v_add_f32_e32 v38, v24, v25
	v_cvt_pk_bf16_f32 v24, v28, v29
	v_cvt_pk_bf16_f32 v25, v30, v31
	s_waitcnt vmcnt(6)
	v_lshlrev_b32_e32 v28, 16, v80
	v_and_b32_e32 v29, 0xffff0000, v80
	v_lshlrev_b32_e32 v30, 16, v81
	v_and_b32_e32 v31, 0xffff0000, v81
	v_cvt_pk_bf16_f32 v26, v26, v27
	v_cvt_pk_bf16_f32 v27, v34, v35
	v_lshlrev_b32_e32 v34, 16, v82
	v_and_b32_e32 v35, 0xffff0000, v82
	v_pk_add_f32 v[22:23], v[22:23], v[30:31]
	v_pk_add_f32 v[20:21], v[20:21], v[28:29]
	v_lshlrev_b32_e32 v36, 16, v83
	v_and_b32_e32 v37, 0xffff0000, v83
	v_pk_add_f32 v[30:31], v[16:17], v[34:35]
	v_mul_f32_e32 v16, v21, v21
	v_mul_f32_e32 v17, v23, v23
	v_pk_add_f32 v[28:29], v[18:19], v[36:37]
	v_fmac_f32_e32 v16, v20, v20
	v_fmac_f32_e32 v17, v22, v22
	v_add_f32_e32 v16, v16, v17
	v_mul_f32_e32 v17, v31, v31
	v_mul_f32_e32 v18, v29, v29
	v_fmac_f32_e32 v17, v30, v30
	v_fmac_f32_e32 v18, v28, v28
	v_add_f32_e32 v17, v17, v18
	v_add_f32_e32 v16, v16, v17
	v_add_f32_e32 v19, v38, v16
	v_mov_b32_e32 v34, v19
	s_nop 1
	v_permlane16_swap_b32_e32 v19, v34
	s_waitcnt lgkmcnt(1)
	v_lshlrev_b64 v[32:33], 10, v[104:105]
	v_lshl_add_u64 v[16:17], v[32:33], 1, s[12:13]
	v_lshl_add_u64 v[32:33], v[188:189], 1, v[16:17]
	v_cvt_pk_bf16_f32 v18, v20, v21
	s_waitcnt lgkmcnt(0)
	v_add_f32_e32 v16, v19, v34
	v_mov_b32_e32 v17, v16
	s_nop 1
	v_permlane32_swap_b32_e32 v16, v17
	v_cvt_pk_bf16_f32 v19, v22, v23
	v_cvt_pk_bf16_f32 v20, v30, v31
	v_cvt_pk_bf16_f32 v21, v28, v29
	global_store_dwordx4 v[32:33], v[24:27], off
	global_store_dwordx4 v[32:33], v[18:21], off offset:256
	s_and_saveexec_b64 s[24:25], s[6:7]
	s_cbranch_execz .LBB0_1172
	v_readlane_b32 s44, v254, 18
	v_readlane_b32 s45, v254, 19
	v_lshlrev_b64 v[18:19], 6, v[104:105]
	s_mov_b32 s5, s45
	v_lshl_add_u64 v[18:19], s[14:15], 0, v[18:19]
	v_readlane_b32 s46, v254, 20
	v_readlane_b32 s47, v254, 21
	v_readlane_b32 s48, v254, 22
	v_readlane_b32 s49, v254, 23
	v_readlane_b32 s50, v254, 24
	v_readlane_b32 s51, v254, 25
	v_readlane_b32 s52, v254, 26
	v_readlane_b32 s53, v254, 27
	v_readlane_b32 s54, v254, 28
	v_readlane_b32 s55, v254, 29
	v_readlane_b32 s56, v254, 30
	v_readlane_b32 s57, v254, 31
	v_readlane_b32 s58, v254, 32
	v_readlane_b32 s59, v254, 33
	v_writelane_b32 v254, s4, 18
	v_lshl_add_u64 v[18:19], s[22:23], 2, v[18:19]
	s_lshl_b32 s44, s37, 2
	v_writelane_b32 v254, s5, 19
	v_writelane_b32 v254, s6, 20
	v_writelane_b32 v254, s7, 21
	v_writelane_b32 v254, s8, 22
	v_writelane_b32 v254, s9, 23
	v_writelane_b32 v254, s10, 24
	v_writelane_b32 v254, s11, 25
	v_writelane_b32 v254, s12, 26
	v_writelane_b32 v254, s13, 27
	v_writelane_b32 v254, s14, 28
	v_writelane_b32 v254, s15, 29
	v_writelane_b32 v254, s16, 30
	v_writelane_b32 v254, s17, 31
	v_writelane_b32 v254, s18, 32
	s_mov_b32 s52, 0xff800000
	v_writelane_b32 v254, s19, 33
	v_lshl_add_u64 v[18:19], v[18:19], 0, s[44:45]
	s_waitcnt lgkmcnt(0)
	v_add_f32_e32 v16, v16, v17
	global_store_dword v[18:19], v16, off

; #define PG8_STAGE(bufoff, gbase, voff) do { _Pragma("unroll") for (int _i = 0; _i < 2; ++_i) \
;         __builtin_amdgcn_global_load_lds((const unsigned*)((const char*)(gbase) + (voff)[_i]), (PG8_LAS unsigned*)(lds + (bufoff) + ldsw + _i * 8192), 16, 0, 0); } while (0)
; #define PG8_WAIT_V(n) asm volatile("s_waitcnt vmcnt(" #n ")" ::: "memory")
; #define PG8_BAR __builtin_amdgcn_s_barrier()
; #define GAS_ __attribute__((address_space(1)))
; template <class Epi, class Sched, bool ALIGN_EPI = false, bool SP2 = false>
; __device__ __forceinline__ void gemm_phase(PG8_LAS unsigned char* lds, const Gemm g, const Sched& S, const Epi& E, int wave0) {
;     ...
;         PG8_STAGE(PG8_SB(0, 0), cB, voffB); PG8_STAGE(PG8_SB(0, 1), cB + hstep, voffB); PG8_STAGE(PG8_SA(0, 0), cA, voffA); PG8_STAGE(PG8_SA(0, 1), cA + hstepA, voffA);
;         if (wr == 1) PG8_BAR;
;         PG8_WAIT_V(2); PG8_BAR;
;         PG8_STAGE(PG8_SB(1, 0), cB + kstep, voffB); PG8_STAGE(PG8_SA(1, 0), cA + kstepA, voffA); PG8_STAGE(PG8_SB(1, 1), cB + hstep + kstep, voffB);
;         PG8_WAIT_V(6); PG8_BAR;
; __device__ __forceinline__ void rows_rstd(float (&rs)[2][4], const float* SS, int row0, int fq) {
;     ...
;     for (int ai = 0; ai < 2; ++ai)
; #pragma unroll
;         for (int m = 0; m < 4; ++m) q[ai][m] = *(const GAS_ f32x4*)(SS + (size_t)(row0 + ai * 128 + m * 16) * 16 + fq * 4);
.LBB0_1226:
	s_add_u32 s12, s6, 0xc800000
	s_addc_u32 s13, s7, 0
	v_bfe_u32 v31, v30, 4, 2
	s_lshl_b32 s8, s8, 5
	v_and_b32_e32 v33, 15, v30
	v_lshlrev_b32_e32 v32, 4, v31
	v_lshlrev_b32_e32 v30, 2, v30
	s_and_b32 s16, s8, 0x60
	s_add_i32 m0, s29, 0x18000
	v_lshl_add_u64 v[22:23], v[22:23], 0, s[70:71]
	v_lshl_or_b32 v217, s9, 6, v33
	v_lshl_or_b32 v33, v33, 6, v32
	s_lshl_b32 s9, s9, 13
	v_and_b32_e32 v30, 32, v30
	s_lshl_b32 s8, s16, 7
	s_waitcnt vmcnt(2)
	s_barrier
	global_load_lds_dwordx4 v[22:23], off
	v_lshl_add_u64 v[20:21], v[20:21], 0, s[70:71]
	s_add_i32 m0, s29, 0x1a000
	s_add_i32 s35, s29, 0x8000
	s_add_i32 s36, s29, 0xa000
	v_bitop3_b32 v218, v33, s8, v30 bitop3:0xde
	global_load_lds_dwordx4 v[20:21], off
	v_lshl_add_u64 v[16:17], v[16:17], 0, s[70:71]
	s_mov_b32 m0, s35
	s_add_u32 s8, s0, 0x40080
	v_bitop3_b32 v34, v33, s9, v30 bitop3:0xde
	global_load_lds_dwordx4 v[16:17], off
	v_lshl_add_u64 v[16:17], v[18:19], 0, s[70:71]
	s_mov_b32 m0, s36
	s_addc_u32 s9, s1, 0
	global_load_lds_dwordx4 v[16:17], off
	s_add_i32 m0, s29, 0x1c000
	v_lshl_add_u64 v[16:17], s[8:9], 0, v[176:177]
	global_load_lds_dwordx4 v[16:17], off
	v_lshl_add_u64 v[16:17], s[8:9], 0, v[182:183]
	s_add_i32 m0, s29, 0x1e000
	v_mov_b32_e32 v33, v177
	global_load_lds_dwordx4 v[16:17], off
	v_lshl_add_u64 v[16:17], s[6:7], 0, v[32:33]
	s_mov_b64 s[6:7], 0x2d000000
	v_lshl_add_u64 v[188:189], v[16:17], 0, s[6:7]
	v_lshlrev_b32_e32 v16, 14, v24
	v_and_b32_e32 v16, 0xffff8000, v16
	v_lshl_add_u32 v16, v25, 11, v16
	v_and_b32_e32 v17, 1, v24
	v_lshl_or_b32 v16, v17, 6, v16
	v_lshl_add_u32 v190, v26, 1, v16
	v_lshlrev_b32_e32 v16, 14, v28
	v_and_b32_e32 v16, 0xffff8000, v16
	s_waitcnt vmcnt(6)
	v_lshl_add_u32 v16, v27, 11, v16
	v_and_b32_e32 v17, 1, v28
	s_cmpk_lt_u32 s2, 0x100
	v_lshl_or_b32 v16, v17, 6, v16
	v_readlane_b32 s6, v254, 51
	s_cselect_b64 s[14:15], -1, 0
	v_lshl_or_b32 v219, v31, 3, s16
	s_waitcnt vmcnt(0)
	v_mov_b32_e32 v191, v177
	v_lshl_add_u32 v192, v29, 1, v16
	v_mov_b32_e32 v193, v177
	s_mov_b32 s37, 0
	v_add_u32_e32 v220, 0, v34
	v_readlane_b32 s2, v254, 50
	s_cmp_eq_u64 s[10:11], 0
	s_cbranch_scc1 .Lgu_ss_skip0
	v_readlane_b32 s100, v219, 0
	s_nop 1
	s_lshr_b32 s100, s100, 5
	s_and_b32 s101, s100, 1
	s_lshl_b32 s101, s101, 7
	s_lshr_b32 m0, s100, 1
	s_lshl_b32 m0, m0, 6
	s_add_i32 s101, s101, m0
	s_lshl_b32 m0, s6, 8
	s_add_i32 s101, s101, m0
	v_and_b32_e32 v16, 15, v217
	v_add_u32_e32 v16, s101, v16
	v_lshlrev_b32_e32 v16, 6, v16
	v_mov_b32_e32 v17, 0
	v_lshl_add_u64 v[16:17], v[188:189], 0, v[16:17]
	s_lshl_b32 s100, s100, 12
	s_add_i32 m0, s100, 0x24000
	s_nop 0
	global_load_lds_dwordx4 v[16:17], off
	global_load_lds_dwordx4 v[16:17], off offset:1024
	global_load_lds_dwordx4 v[16:17], off offset:2048
	global_load_lds_dwordx4 v[16:17], off offset:3072

; #define GAS_ __attribute__((address_space(1)))
; __device__ __forceinline__ void rows_rstd(float (&rs)[2][4], const float* SS, int row0, int fq) {
;     f32x4 q[2][4];
; #pragma unroll
;     for (int ai = 0; ai < 2; ++ai)
; #pragma unroll
;         for (int m = 0; m < 4; ++m) q[ai][m] = *(const GAS_ f32x4*)(SS + (size_t)(row0 + ai * 128 + m * 16) * 16 + fq * 4);
; #pragma unroll
;     for (int ai = 0; ai < 2; ++ai)
; #pragma unroll
;         for (int m = 0; m < 4; ++m) { float s = (q[ai][m][0] + q[ai][m][1]) + (q[ai][m][2] + q[ai][m][3]); s += __shfl_xor(s, 16); s += __shfl_xor(s, 32);
;             rs[ai][m] = 1.0f / sqrtf(s * (1.0f / 1024.0f) + 1e-5f); }
;     __device__ __forceinline__ void operator()(const f32x4 (&acc)[2][2][4][2], const Unit& u, int wr, int wc, int fr, int fq) const {
;         const int row0 = u.pm * 256 + wr * 64 + fr, hc0 = u.pn * 128 + wc * 32 + 8 * fq;
;         float rsv[2][4];
;         rows_rstd(rsv, SS, row0, fq);
; #pragma unroll
;         for (int ai = 0; ai < 2; ++ai)
; #pragma unroll
;             for (int m = 0; m < 4; ++m) {
;                 bf16_t* rowp = H + (size_t)(row0 + ai * 128 + m * 16) * ldh + hc0;
;                 const float rs = rsv[ai][m];
;                 const f32x4 g0 = acc[ai][0][m][0] * rs, g1 = acc[ai][0][m][1] * rs, u0 = acc[ai][1][m][0] * rs, u1 = acc[ai][1][m][1] * rs;
.LBB0_1235:
	v_and_b32_e32 v144, 64, v217
	v_lshlrev_b32_e32 v144, 7, v144
	v_lshl_add_u32 v144, v212, 4, v144
	v_add_u32_e32 v144, 0x24000, v144
	ds_read_b128 v[172:175], v144
	ds_read_b128 v[168:171], v144 offset:1024
	ds_read_b128 v[164:167], v144 offset:2048
	ds_read_b128 v[160:163], v144 offset:3072
	ds_read_b128 v[156:159], v144 offset:4096
	ds_read_b128 v[152:155], v144 offset:5120
	ds_read_b128 v[148:151], v144 offset:6144
	ds_read_b128 v[144:147], v144 offset:7168
	v_lshl_add_u32 v208, s33, 8, v217
	v_ashrrev_i32_e32 v209, 31, v208
	v_or_b32_e32 v206, 16, v208
	v_ashrrev_i32_e32 v207, 31, v206
	v_and_b32_e32 v179, 64, v212
	v_xor_b32_e32 v178, 16, v212
	v_add_u32_e32 v179, 64, v179
	v_cmp_lt_i32_e32 vcc, v178, v179
	v_xor_b32_e32 v180, 32, v212
	v_or_b32_e32 v204, 32, v208
	v_cndmask_b32_e32 v178, v212, v178, vcc
	v_cmp_lt_i32_e32 vcc, v180, v179
	v_ashrrev_i32_e32 v205, 31, v204
	v_cndmask_b32_e32 v179, v212, v180, vcc
	v_lshlrev_b32_e32 v178, 2, v178
	v_lshlrev_b32_e32 v179, 2, v179
	v_or_b32_e32 v202, 48, v208
	v_ashrrev_i32_e32 v203, 31, v202
	v_add_u32_e32 v200, 0x80, v208
	v_ashrrev_i32_e32 v201, 31, v200
	v_add_u32_e32 v198, 0x90, v208
	v_ashrrev_i32_e32 v199, 31, v198
	v_add_u32_e32 v196, 0xa0, v208
	v_ashrrev_i32_e32 v197, 31, v196
	v_add_u32_e32 v194, 0xb0, v208
	v_ashrrev_i32_e32 v195, 31, v194
	v_lshl_or_b32 v210, s2, 7, v219
	v_ashrrev_i32_e32 v211, 31, v210
	s_waitcnt lgkmcnt(0)
	v_mov_b32_e32 v180, v173
	v_mov_b32_e32 v181, v174
	v_mov_b32_e32 v173, v175
	v_pk_add_f32 v[172:173], v[180:181], v[172:173]
	s_nop 0
	v_add_f32_e32 v172, v172, v173
	v_mov_b32_e32 v173, v172
	s_nop 1
	v_permlane16_swap_b32_e32 v172, v173
	s_waitcnt lgkmcnt(0)
	v_add_f32_e32 v172, v172, v173
	v_mov_b32_e32 v173, v172
	s_nop 1
	v_permlane32_swap_b32_e32 v172, v173
	s_waitcnt lgkmcnt(0)
	v_add_f32_e32 v172, v172, v173
	v_fmamk_f32 v172, v172, 0x3a800000, v214
	v_rsq_f32_e32 v173, v172
	s_nop 0
	v_mul_f32_e32 v174, v172, v173
	v_fma_f32 v174, -v174, v173, 1.0
	v_mul_f32_e32 v175, 0.5, v173
	v_fma_f32 v172, v175, v174, v173
	v_mov_b32_e32 v174, v169
	v_mov_b32_e32 v175, v170
	v_mov_b32_e32 v169, v171
	v_pk_add_f32 v[168:169], v[174:175], v[168:169]
	v_add_f32_e32 v168, v168, v169
	v_mov_b32_e32 v169, v168
	s_nop 1
	v_permlane16_swap_b32_e32 v168, v169
	s_waitcnt lgkmcnt(0)
	v_add_f32_e32 v168, v168, v169
	v_mov_b32_e32 v169, v168
	s_nop 1
	v_permlane32_swap_b32_e32 v168, v169
	s_waitcnt lgkmcnt(0)
	v_add_f32_e32 v168, v168, v169
	v_fmamk_f32 v168, v168, 0x3a800000, v214
	v_rsq_f32_e32 v169, v168
	s_nop 0
	v_mul_f32_e32 v170, v168, v169
	v_fma_f32 v170, -v170, v169, 1.0
	v_mul_f32_e32 v171, 0.5, v169
	v_fma_f32 v168, v171, v170, v169
	v_mov_b32_e32 v170, v165
	v_mov_b32_e32 v171, v166
	v_mov_b32_e32 v165, v167
	v_pk_add_f32 v[164:165], v[170:171], v[164:165]
	v_add_f32_e32 v164, v164, v165
	v_mov_b32_e32 v165, v164
	s_nop 1
	v_permlane16_swap_b32_e32 v164, v165
	v_pk_mul_f32 v[140:141], v[140:141], v[172:173] op_sel_hi:[1,0]
	v_pk_mul_f32 v[132:133], v[132:133], v[172:173] op_sel_hi:[1,0]
	v_pk_mul_f32 v[142:143], v[142:143], v[172:173] op_sel_hi:[1,0]
	v_pk_mul_f32 v[134:135], v[134:135], v[172:173] op_sel_hi:[1,0]
	s_waitcnt lgkmcnt(0)
	v_add_f32_e32 v164, v164, v165
	v_mov_b32_e32 v165, v164
	s_nop 1
	v_permlane32_swap_b32_e32 v164, v165
	v_pk_mul_f32 v[136:137], v[136:137], v[172:173] op_sel_hi:[1,0]
	v_pk_mul_f32 v[138:139], v[138:139], v[172:173] op_sel_hi:[1,0]
	s_waitcnt lgkmcnt(0)
	v_add_f32_e32 v164, v164, v165
	v_fmamk_f32 v164, v164, 0x3a800000, v214
	v_rsq_f32_e32 v165, v164
	s_nop 0
	v_mul_f32_e32 v166, v164, v165
	v_fma_f32 v166, -v166, v165, 1.0
	v_mul_f32_e32 v167, 0.5, v165
	v_fma_f32 v164, v167, v166, v165
	v_mov_b32_e32 v166, v161
	v_mov_b32_e32 v167, v162
	v_mov_b32_e32 v161, v163
	v_pk_add_f32 v[160:161], v[166:167], v[160:161]
	v_add_f32_e32 v160, v160, v161
	v_mov_b32_e32 v161, v160
	s_nop 1
	v_permlane16_swap_b32_e32 v160, v161
	v_pk_mul_f32 v[124:125], v[124:125], v[168:169] op_sel_hi:[1,0]
	v_pk_mul_f32 v[116:117], v[116:117], v[168:169] op_sel_hi:[1,0]
	v_pk_mul_f32 v[126:127], v[126:127], v[168:169] op_sel_hi:[1,0]
	v_pk_mul_f32 v[118:119], v[118:119], v[168:169] op_sel_hi:[1,0]
	s_waitcnt lgkmcnt(0)
	v_add_f32_e32 v160, v160, v161
	v_mov_b32_e32 v161, v160
	s_nop 1
	v_permlane32_swap_b32_e32 v160, v161
	v_pk_mul_f32 v[120:121], v[120:121], v[168:169] op_sel_hi:[1,0]
	v_pk_mul_f32 v[122:123], v[122:123], v[168:169] op_sel_hi:[1,0]
	s_waitcnt lgkmcnt(0)
	v_add_f32_e32 v160, v160, v161
	v_fmamk_f32 v160, v160, 0x3a800000, v214
	v_rsq_f32_e32 v161, v160
	s_nop 0
	v_mul_f32_e32 v162, v160, v161
	v_fma_f32 v162, -v162, v161, 1.0
	v_mul_f32_e32 v163, 0.5, v161
	v_fma_f32 v160, v163, v162, v161
	v_mov_b32_e32 v162, v157
	v_mov_b32_e32 v163, v158
	v_mov_b32_e32 v157, v159
	v_pk_add_f32 v[156:157], v[162:163], v[156:157]
	v_add_f32_e32 v156, v156, v157
	v_mov_b32_e32 v157, v156
	s_nop 1
	v_permlane16_swap_b32_e32 v156, v157
	v_pk_mul_f32 v[108:109], v[108:109], v[164:165] op_sel_hi:[1,0]
	v_pk_mul_f32 v[100:101], v[100:101], v[164:165] op_sel_hi:[1,0]
	v_pk_mul_f32 v[110:111], v[110:111], v[164:165] op_sel_hi:[1,0]
	v_pk_mul_f32 v[102:103], v[102:103], v[164:165] op_sel_hi:[1,0]
	s_waitcnt lgkmcnt(0)
	v_add_f32_e32 v156, v156, v157
	v_mov_b32_e32 v157, v156
	s_nop 1
	v_permlane32_swap_b32_e32 v156, v157
	v_pk_mul_f32 v[104:105], v[104:105], v[164:165] op_sel_hi:[1,0]
	v_pk_mul_f32 v[106:107], v[106:107], v[164:165] op_sel_hi:[1,0]
	s_waitcnt lgkmcnt(0)
; #define GAS_ __attribute__((address_space(1)))
; __device__ __forceinline__ unsigned pk2(float lo, float hi) { f32x2_t v = {lo, hi}; bf16x2_t b = __builtin_convertvector(v, bf16x2_t); return __builtin_bit_cast(unsigned, b); }
; __device__ __forceinline__ float silu_f(float g) { return g * __builtin_amdgcn_rcpf(1.0f + __expf(-g)); }
; __device__ __forceinline__ void rows_rstd(float (&rs)[2][4], const float* SS, int row0, int fq) {
;     ...
;         for (int m = 0; m < 4; ++m) { float s = (q[ai][m][0] + q[ai][m][1]) + (q[ai][m][2] + q[ai][m][3]); s += __shfl_xor(s, 16); s += __shfl_xor(s, 32);
;             rs[ai][m] = 1.0f / sqrtf(s * (1.0f / 1024.0f) + 1e-5f); }
;     __device__ __forceinline__ void operator()(const f32x4 (&acc)[2][2][4][2], const Unit& u, int wr, int wc, int fr, int fq) const {
;     ...
;             for (int m = 0; m < 4; ++m) {
;                 bf16_t* rowp = H + (size_t)(row0 + ai * 128 + m * 16) * ldh + hc0;
;                 const float rs = rsv[ai][m];
;                 const f32x4 g0 = acc[ai][0][m][0] * rs, g1 = acc[ai][0][m][1] * rs, u0 = acc[ai][1][m][0] * rs, u1 = acc[ai][1][m][1] * rs;
;                 u32x4 w; w.x = pk2(silu_f(g0[0]) * u0[0], silu_f(g0[1]) * u0[1]); w.y = pk2(silu_f(g0[2]) * u0[2], silu_f(g0[3]) * u0[3]);
;                 w.z = pk2(silu_f(g1[0]) * u1[0], silu_f(g1[1]) * u1[1]); w.w = pk2(silu_f(g1[2]) * u1[2], silu_f(g1[3]) * u1[3]);
;                 *(GAS_ u32x4*)rowp = w;
	v_add_f32_e32 v156, v156, v157
	v_fmamk_f32 v156, v156, 0x3a800000, v214
	v_rsq_f32_e32 v157, v156
	s_nop 0
	v_mul_f32_e32 v158, v156, v157
	v_fma_f32 v158, -v158, v157, 1.0
	v_mul_f32_e32 v159, 0.5, v157
	v_fma_f32 v156, v159, v158, v157
	v_mov_b32_e32 v158, v153
	v_mov_b32_e32 v159, v154
	v_mov_b32_e32 v153, v155
	v_pk_add_f32 v[152:153], v[158:159], v[152:153]
	v_add_f32_e32 v152, v152, v153
	v_mov_b32_e32 v153, v152
	s_nop 1
	v_permlane16_swap_b32_e32 v152, v153
	v_pk_mul_f32 v[92:93], v[92:93], v[160:161] op_sel_hi:[1,0]
	v_pk_mul_f32 v[84:85], v[84:85], v[160:161] op_sel_hi:[1,0]
	v_pk_mul_f32 v[94:95], v[94:95], v[160:161] op_sel_hi:[1,0]
	v_pk_mul_f32 v[86:87], v[86:87], v[160:161] op_sel_hi:[1,0]
	s_waitcnt lgkmcnt(0)
	v_add_f32_e32 v152, v152, v153
	v_mov_b32_e32 v153, v152
	s_nop 1
	v_permlane32_swap_b32_e32 v152, v153
	v_pk_mul_f32 v[88:89], v[88:89], v[160:161] op_sel_hi:[1,0]
	v_pk_mul_f32 v[90:91], v[90:91], v[160:161] op_sel_hi:[1,0]
	s_waitcnt lgkmcnt(0)
	v_add_f32_e32 v152, v152, v153
	v_fmamk_f32 v152, v152, 0x3a800000, v214
	v_rsq_f32_e32 v153, v152
	s_nop 0
	v_mul_f32_e32 v154, v152, v153
	v_fma_f32 v154, -v154, v153, 1.0
	v_mul_f32_e32 v155, 0.5, v153
	v_fma_f32 v152, v155, v154, v153
	v_mov_b32_e32 v154, v149
	v_mov_b32_e32 v155, v150
	v_mov_b32_e32 v149, v151
	v_pk_add_f32 v[148:149], v[154:155], v[148:149]
	v_pk_mul_f32 v[158:159], v[130:131], v[172:173] op_sel_hi:[1,0]
	v_add_f32_e32 v148, v148, v149
	v_mov_b32_e32 v149, v148
	s_nop 1
	v_permlane16_swap_b32_e32 v148, v149
	v_pk_mul_f32 v[130:131], v[128:129], v[172:173] op_sel_hi:[1,0]
	v_mul_f32_e32 v128, 0xbfb8aa3b, v140
	v_mul_f32_e32 v129, 0xbfb8aa3b, v141
	v_exp_f32_e32 v128, v128
	s_waitcnt lgkmcnt(0)
	v_add_f32_e32 v148, v148, v149
	v_mov_b32_e32 v149, v148
	s_nop 1
	v_permlane32_swap_b32_e32 v148, v149
	v_exp_f32_e32 v129, v129
	v_add_f32_e32 v128, 1.0, v128
	v_rcp_f32_e32 v128, v128
	s_waitcnt lgkmcnt(0)
	v_add_f32_e32 v148, v148, v149
	v_fmamk_f32 v148, v148, 0x3a800000, v214
	v_rsq_f32_e32 v149, v148
	s_nop 0
	v_mul_f32_e32 v151, v148, v149
	v_fma_f32 v151, -v151, v149, 1.0
	v_mul_f32_e32 v153, 0.5, v149
	v_fma_f32 v150, v153, v151, v149
	v_add_f32_e32 v129, 1.0, v129
	v_rcp_f32_e32 v129, v129
	v_pk_mul_f32 v[76:77], v[76:77], v[156:157] op_sel_hi:[1,0]
	v_pk_mul_f32 v[68:69], v[68:69], v[156:157] op_sel_hi:[1,0]
	v_pk_mul_f32 v[128:129], v[140:141], v[128:129]
	v_pk_mul_f32 v[128:129], v[132:133], v[128:129]
	v_pk_mul_f32 v[78:79], v[78:79], v[156:157] op_sel_hi:[1,0]
	v_cvt_pk_bf16_f32 v128, v128, v129
	v_mul_f32_e32 v129, 0xbfb8aa3b, v142
	v_exp_f32_e32 v129, v129
	v_pk_mul_f32 v[70:71], v[70:71], v[156:157] op_sel_hi:[1,0]
	v_pk_mul_f32 v[72:73], v[72:73], v[156:157] op_sel_hi:[1,0]
	v_mov_b32_e32 v148, v145
	v_mov_b32_e32 v149, v146
	v_mov_b32_e32 v145, v147
	v_pk_add_f32 v[144:145], v[148:149], v[144:145]
	v_add_f32_e32 v129, 1.0, v129
	v_add_f32_e32 v144, v144, v145
	v_rcp_f32_e32 v132, v129
	v_mul_f32_e32 v129, 0xbfb8aa3b, v143
	v_mov_b32_e32 v145, v144
	s_nop 1
	v_permlane16_swap_b32_e32 v144, v145
	v_exp_f32_e32 v129, v129
	v_pk_mul_f32 v[74:75], v[74:75], v[156:157] op_sel_hi:[1,0]
	v_pk_mul_f32 v[60:61], v[60:61], v[152:153] op_sel_hi:[1,0]
	v_pk_mul_f32 v[52:53], v[52:53], v[152:153] op_sel_hi:[1,0]
	v_add_f32_e32 v129, 1.0, v129
	s_waitcnt lgkmcnt(0)
	v_add_f32_e32 v144, v144, v145
	v_rcp_f32_e32 v133, v129
	v_mov_b32_e32 v145, v144
	s_nop 1
	v_permlane32_swap_b32_e32 v144, v145
	v_pk_mul_f32 v[62:63], v[62:63], v[152:153] op_sel_hi:[1,0]
	v_pk_mul_f32 v[54:55], v[54:55], v[152:153] op_sel_hi:[1,0]
	v_pk_mul_f32 v[132:133], v[142:143], v[132:133]
	v_pk_mul_f32 v[56:57], v[56:57], v[152:153] op_sel_hi:[1,0]
	v_pk_mul_f32 v[132:133], v[134:135], v[132:133]
	s_waitcnt lgkmcnt(0)
	v_add_f32_e32 v144, v144, v145
	v_cvt_pk_bf16_f32 v129, v132, v133
	v_mul_f32_e32 v132, 0xbfb8aa3b, v136
	v_mul_f32_e32 v133, 0xbfb8aa3b, v137
	v_fmamk_f32 v144, v144, 0x3a800000, v214
	v_rsq_f32_e32 v145, v144
	s_nop 0
	v_mul_f32_e32 v146, v144, v145
	v_fma_f32 v146, -v146, v145, 1.0
	v_mul_f32_e32 v147, 0.5, v145
	v_fma_f32 v144, v147, v146, v145
	v_exp_f32_e32 v132, v132
	v_exp_f32_e32 v133, v133
	v_add_f32_e32 v132, 1.0, v132
	v_add_f32_e32 v133, 1.0, v133
	v_rcp_f32_e32 v132, v132
	v_rcp_f32_e32 v133, v133
	s_nop 0
	v_pk_mul_f32 v[132:133], v[136:137], v[132:133]
	v_pk_mul_f32 v[130:131], v[130:131], v[132:133]
	v_cvt_pk_bf16_f32 v130, v130, v131
	v_mul_f32_e32 v131, 0xbfb8aa3b, v138
	v_exp_f32_e32 v131, v131
	s_nop 0
	v_add_f32_e32 v131, 1.0, v131
	v_rcp_f32_e32 v132, v131
	v_mul_f32_e32 v131, 0xbfb8aa3b, v139
	v_exp_f32_e32 v131, v131
	v_pk_mul_f32 v[58:59], v[58:59], v[152:153] op_sel_hi:[1,0]
	v_add_f32_e32 v131, 1.0, v131
	v_rcp_f32_e32 v133, v131
	v_mov_b64_e32 v[146:147], s[12:13]
	v_pk_mul_f32 v[132:133], v[138:139], v[132:133]
	v_mad_i64_i32 v[154:155], s[0:1], v208, s62, v[146:147]
	v_lshlrev_b64 v[148:149], 1, v[210:211]
	v_pk_mul_f32 v[132:133], v[158:159], v[132:133]
	v_lshl_add_u64 v[154:155], v[154:155], 0, v[148:149]
	v_cvt_pk_bf16_f32 v131, v132, v133
	global_store_dwordx4 v[154:155], v[128:131], off
	v_pk_mul_f32 v[44:45], v[44:45], v[150:151] op_sel_hi:[1,0]
	v_pk_mul_f32 v[36:37], v[36:37], v[150:151] op_sel_hi:[1,0]
	v_pk_mul_f32 v[130:131], v[114:115], v[168:169] op_sel_hi:[1,0]
	v_pk_mul_f32 v[114:115], v[112:113], v[168:169] op_sel_hi:[1,0]
	v_mul_f32_e32 v112, 0xbfb8aa3b, v124
	v_mul_f32_e32 v113, 0xbfb8aa3b, v125
	v_exp_f32_e32 v112, v112
	v_exp_f32_e32 v113, v113
	v_mad_i64_i32 v[128:129], s[0:1], v206, s62, v[146:147]
	v_add_f32_e32 v112, 1.0, v112
	v_add_f32_e32 v113, 1.0, v113
	v_rcp_f32_e32 v112, v112
	v_rcp_f32_e32 v113, v113
; #define GAS_ __attribute__((address_space(1)))
; __device__ __forceinline__ unsigned pk2(float lo, float hi) { f32x2_t v = {lo, hi}; bf16x2_t b = __builtin_convertvector(v, bf16x2_t); return __builtin_bit_cast(unsigned, b); }
; __device__ __forceinline__ float silu_f(float g) { return g * __builtin_amdgcn_rcpf(1.0f + __expf(-g)); }
;     __device__ __forceinline__ void operator()(const f32x4 (&acc)[2][2][4][2], const Unit& u, int wr, int wc, int fr, int fq) const {
;     ...
;             for (int m = 0; m < 4; ++m) {
;                 bf16_t* rowp = H + (size_t)(row0 + ai * 128 + m * 16) * ldh + hc0;
;                 const float rs = rsv[ai][m];
;                 const f32x4 g0 = acc[ai][0][m][0] * rs, g1 = acc[ai][0][m][1] * rs, u0 = acc[ai][1][m][0] * rs, u1 = acc[ai][1][m][1] * rs;
;                 u32x4 w; w.x = pk2(silu_f(g0[0]) * u0[0], silu_f(g0[1]) * u0[1]); w.y = pk2(silu_f(g0[2]) * u0[2], silu_f(g0[3]) * u0[3]);
;                 w.z = pk2(silu_f(g1[0]) * u1[0], silu_f(g1[1]) * u1[1]); w.w = pk2(silu_f(g1[2]) * u1[2], silu_f(g1[3]) * u1[3]);
;                 *(GAS_ u32x4*)rowp = w;
	v_lshl_add_u64 v[128:129], v[128:129], 0, v[148:149]
	v_pk_mul_f32 v[46:47], v[46:47], v[150:151] op_sel_hi:[1,0]
	v_pk_mul_f32 v[38:39], v[38:39], v[150:151] op_sel_hi:[1,0]
	v_pk_mul_f32 v[112:113], v[124:125], v[112:113]
	v_pk_mul_f32 v[40:41], v[40:41], v[150:151] op_sel_hi:[1,0]
	v_pk_mul_f32 v[112:113], v[116:117], v[112:113]
	v_pk_mul_f32 v[42:43], v[42:43], v[150:151] op_sel_hi:[1,0]
	v_cvt_pk_bf16_f32 v112, v112, v113
	v_mul_f32_e32 v113, 0xbfb8aa3b, v126
	v_exp_f32_e32 v113, v113
	v_pk_mul_f32 v[28:29], v[28:29], v[144:145] op_sel_hi:[1,0]
	v_pk_mul_f32 v[20:21], v[20:21], v[144:145] op_sel_hi:[1,0]
	v_add_f32_e32 v113, 1.0, v113
	v_rcp_f32_e32 v116, v113
	v_mul_f32_e32 v113, 0xbfb8aa3b, v127
	v_exp_f32_e32 v113, v113
	v_pk_mul_f32 v[30:31], v[30:31], v[144:145] op_sel_hi:[1,0]
	v_pk_mul_f32 v[22:23], v[22:23], v[144:145] op_sel_hi:[1,0]
	v_pk_mul_f32 v[24:25], v[24:25], v[144:145] op_sel_hi:[1,0]
	v_add_f32_e32 v113, 1.0, v113
	v_rcp_f32_e32 v117, v113
	v_pk_mul_f32 v[26:27], v[26:27], v[144:145] op_sel_hi:[1,0]
	s_andn2_b64 vcc, exec, s[6:7]
	v_pk_mul_f32 v[116:117], v[126:127], v[116:117]
	s_nop 0
	v_pk_mul_f32 v[116:117], v[118:119], v[116:117]
	s_nop 0
	v_cvt_pk_bf16_f32 v113, v116, v117
	v_mul_f32_e32 v116, 0xbfb8aa3b, v120
	v_mul_f32_e32 v117, 0xbfb8aa3b, v121
	v_exp_f32_e32 v116, v116
	v_exp_f32_e32 v117, v117
	v_add_f32_e32 v116, 1.0, v116
	v_add_f32_e32 v117, 1.0, v117
	v_rcp_f32_e32 v116, v116
	v_rcp_f32_e32 v117, v117
	s_nop 0
	v_pk_mul_f32 v[116:117], v[120:121], v[116:117]
	s_nop 0
	v_pk_mul_f32 v[114:115], v[114:115], v[116:117]
	s_nop 0
	v_cvt_pk_bf16_f32 v114, v114, v115
	v_mul_f32_e32 v115, 0xbfb8aa3b, v122
	v_exp_f32_e32 v115, v115
	s_nop 0
	v_add_f32_e32 v115, 1.0, v115
	v_rcp_f32_e32 v116, v115
	v_mul_f32_e32 v115, 0xbfb8aa3b, v123
	v_exp_f32_e32 v115, v115
	s_nop 0
	v_add_f32_e32 v115, 1.0, v115
	v_rcp_f32_e32 v117, v115
	s_nop 0
	v_pk_mul_f32 v[116:117], v[122:123], v[116:117]
	s_nop 0
	v_pk_mul_f32 v[116:117], v[130:131], v[116:117]
	s_nop 0
	v_cvt_pk_bf16_f32 v115, v116, v117
	global_store_dwordx4 v[128:129], v[112:115], off
	s_nop 1
	v_pk_mul_f32 v[114:115], v[98:99], v[164:165] op_sel_hi:[1,0]
	v_pk_mul_f32 v[98:99], v[96:97], v[164:165] op_sel_hi:[1,0]
	v_mul_f32_e32 v96, 0xbfb8aa3b, v108
	v_mul_f32_e32 v97, 0xbfb8aa3b, v109
	v_exp_f32_e32 v96, v96
	v_exp_f32_e32 v97, v97
	v_mad_i64_i32 v[112:113], s[0:1], v204, s62, v[146:147]
	v_add_f32_e32 v96, 1.0, v96
	v_add_f32_e32 v97, 1.0, v97
	v_rcp_f32_e32 v96, v96
	v_rcp_f32_e32 v97, v97
	v_lshl_add_u64 v[112:113], v[112:113], 0, v[148:149]
	v_pk_mul_f32 v[96:97], v[108:109], v[96:97]
	s_nop 0
	v_pk_mul_f32 v[96:97], v[100:101], v[96:97]
	s_nop 0
	v_cvt_pk_bf16_f32 v96, v96, v97
	v_mul_f32_e32 v97, 0xbfb8aa3b, v110
	v_exp_f32_e32 v97, v97
	s_nop 0
	v_add_f32_e32 v97, 1.0, v97
	v_rcp_f32_e32 v100, v97
	v_mul_f32_e32 v97, 0xbfb8aa3b, v111
	v_exp_f32_e32 v97, v97
	s_nop 0
	v_add_f32_e32 v97, 1.0, v97
	v_rcp_f32_e32 v101, v97
	s_nop 0
	v_pk_mul_f32 v[100:101], v[110:111], v[100:101]
	s_nop 0
	v_pk_mul_f32 v[100:101], v[102:103], v[100:101]
	s_nop 0
	v_cvt_pk_bf16_f32 v97, v100, v101
	v_mul_f32_e32 v100, 0xbfb8aa3b, v104
	v_mul_f32_e32 v101, 0xbfb8aa3b, v105
	v_exp_f32_e32 v100, v100
	v_exp_f32_e32 v101, v101
	v_add_f32_e32 v100, 1.0, v100
	v_add_f32_e32 v101, 1.0, v101
	v_rcp_f32_e32 v100, v100
	v_rcp_f32_e32 v101, v101
	s_nop 0
	v_pk_mul_f32 v[100:101], v[104:105], v[100:101]
	s_nop 0
	v_pk_mul_f32 v[98:99], v[98:99], v[100:101]
	s_nop 0
	v_cvt_pk_bf16_f32 v98, v98, v99
	v_mul_f32_e32 v99, 0xbfb8aa3b, v106
	v_exp_f32_e32 v99, v99
	s_nop 0
	v_add_f32_e32 v99, 1.0, v99
	v_rcp_f32_e32 v100, v99
	v_mul_f32_e32 v99, 0xbfb8aa3b, v107
	v_exp_f32_e32 v99, v99
	s_nop 0
	v_add_f32_e32 v99, 1.0, v99
	v_rcp_f32_e32 v101, v99
	s_nop 0
	v_pk_mul_f32 v[100:101], v[106:107], v[100:101]
	s_nop 0
	v_pk_mul_f32 v[100:101], v[114:115], v[100:101]
	s_nop 0
	v_cvt_pk_bf16_f32 v99, v100, v101
	global_store_dwordx4 v[112:113], v[96:99], off
	s_nop 1
	v_pk_mul_f32 v[98:99], v[82:83], v[160:161] op_sel_hi:[1,0]
	v_pk_mul_f32 v[82:83], v[80:81], v[160:161] op_sel_hi:[1,0]
	v_mul_f32_e32 v80, 0xbfb8aa3b, v92
	v_mul_f32_e32 v81, 0xbfb8aa3b, v93
	v_exp_f32_e32 v80, v80
	v_exp_f32_e32 v81, v81
	v_mad_i64_i32 v[96:97], s[0:1], v202, s62, v[146:147]
	v_add_f32_e32 v80, 1.0, v80
	v_add_f32_e32 v81, 1.0, v81
	v_rcp_f32_e32 v80, v80
	v_rcp_f32_e32 v81, v81
	v_lshl_add_u64 v[96:97], v[96:97], 0, v[148:149]
	v_pk_mul_f32 v[80:81], v[92:93], v[80:81]
	s_nop 0
	v_pk_mul_f32 v[80:81], v[84:85], v[80:81]
	s_nop 0
	v_cvt_pk_bf16_f32 v80, v80, v81
	v_mul_f32_e32 v81, 0xbfb8aa3b, v94
	v_exp_f32_e32 v81, v81
	s_nop 0
	v_add_f32_e32 v81, 1.0, v81
	v_rcp_f32_e32 v84, v81
	v_mul_f32_e32 v81, 0xbfb8aa3b, v95
	v_exp_f32_e32 v81, v81
	s_nop 0
	v_add_f32_e32 v81, 1.0, v81
	v_rcp_f32_e32 v85, v81
	s_nop 0
	v_pk_mul_f32 v[84:85], v[94:95], v[84:85]
	s_nop 0
	v_pk_mul_f32 v[84:85], v[86:87], v[84:85]
	s_nop 0
	v_cvt_pk_bf16_f32 v81, v84, v85
	v_mul_f32_e32 v84, 0xbfb8aa3b, v88
	v_mul_f32_e32 v85, 0xbfb8aa3b, v89
	v_exp_f32_e32 v84, v84
	v_exp_f32_e32 v85, v85
	v_add_f32_e32 v84, 1.0, v84
	v_add_f32_e32 v85, 1.0, v85
	v_rcp_f32_e32 v84, v84
	v_rcp_f32_e32 v85, v85
	s_nop 0
	v_pk_mul_f32 v[84:85], v[88:89], v[84:85]
	s_nop 0
	v_pk_mul_f32 v[82:83], v[82:83], v[84:85]
	s_nop 0
	v_cvt_pk_bf16_f32 v82, v82, v83
	v_mul_f32_e32 v83, 0xbfb8aa3b, v90
	v_exp_f32_e32 v83, v83
	s_nop 0
	v_add_f32_e32 v83, 1.0, v83
	v_rcp_f32_e32 v84, v83
	v_mul_f32_e32 v83, 0xbfb8aa3b, v91
	v_exp_f32_e32 v83, v83
	s_nop 0
	v_add_f32_e32 v83, 1.0, v83
	v_rcp_f32_e32 v85, v83
	s_nop 0
	v_pk_mul_f32 v[84:85], v[90:91], v[84:85]
	s_nop 0
; #define GAS_ __attribute__((address_space(1)))
; __device__ __forceinline__ unsigned pk2(float lo, float hi) { f32x2_t v = {lo, hi}; bf16x2_t b = __builtin_convertvector(v, bf16x2_t); return __builtin_bit_cast(unsigned, b); }
; __device__ __forceinline__ float silu_f(float g) { return g * __builtin_amdgcn_rcpf(1.0f + __expf(-g)); }
;     __device__ __forceinline__ void operator()(const f32x4 (&acc)[2][2][4][2], const Unit& u, int wr, int wc, int fr, int fq) const {
;     ...
;             for (int m = 0; m < 4; ++m) {
;                 bf16_t* rowp = H + (size_t)(row0 + ai * 128 + m * 16) * ldh + hc0;
;                 const float rs = rsv[ai][m];
;                 const f32x4 g0 = acc[ai][0][m][0] * rs, g1 = acc[ai][0][m][1] * rs, u0 = acc[ai][1][m][0] * rs, u1 = acc[ai][1][m][1] * rs;
;                 u32x4 w; w.x = pk2(silu_f(g0[0]) * u0[0], silu_f(g0[1]) * u0[1]); w.y = pk2(silu_f(g0[2]) * u0[2], silu_f(g0[3]) * u0[3]);
;                 w.z = pk2(silu_f(g1[0]) * u1[0], silu_f(g1[1]) * u1[1]); w.w = pk2(silu_f(g1[2]) * u1[2], silu_f(g1[3]) * u1[3]);
;                 *(GAS_ u32x4*)rowp = w;
	v_pk_mul_f32 v[84:85], v[98:99], v[84:85]
	s_nop 0
	v_cvt_pk_bf16_f32 v83, v84, v85
	global_store_dwordx4 v[96:97], v[80:83], off
	s_nop 1
	v_pk_mul_f32 v[82:83], v[66:67], v[156:157] op_sel_hi:[1,0]
	v_pk_mul_f32 v[66:67], v[64:65], v[156:157] op_sel_hi:[1,0]
	v_mul_f32_e32 v64, 0xbfb8aa3b, v76
	v_mul_f32_e32 v65, 0xbfb8aa3b, v77
	v_exp_f32_e32 v64, v64
	v_exp_f32_e32 v65, v65
	v_mad_i64_i32 v[80:81], s[0:1], v200, s62, v[146:147]
	v_add_f32_e32 v64, 1.0, v64
	v_add_f32_e32 v65, 1.0, v65
	v_rcp_f32_e32 v64, v64
	v_rcp_f32_e32 v65, v65
	v_lshl_add_u64 v[80:81], v[80:81], 0, v[148:149]
	v_pk_mul_f32 v[64:65], v[76:77], v[64:65]
	s_nop 0
	v_pk_mul_f32 v[64:65], v[68:69], v[64:65]
	s_nop 0
	v_cvt_pk_bf16_f32 v64, v64, v65
	v_mul_f32_e32 v65, 0xbfb8aa3b, v78
	v_exp_f32_e32 v65, v65
	s_nop 0
	v_add_f32_e32 v65, 1.0, v65
	v_rcp_f32_e32 v68, v65
	v_mul_f32_e32 v65, 0xbfb8aa3b, v79
	v_exp_f32_e32 v65, v65
	s_nop 0
	v_add_f32_e32 v65, 1.0, v65
	v_rcp_f32_e32 v69, v65
	s_nop 0
	v_pk_mul_f32 v[68:69], v[78:79], v[68:69]
	s_nop 0
	v_pk_mul_f32 v[68:69], v[70:71], v[68:69]
	s_nop 0
	v_cvt_pk_bf16_f32 v65, v68, v69
	v_mul_f32_e32 v68, 0xbfb8aa3b, v72
	v_mul_f32_e32 v69, 0xbfb8aa3b, v73
	v_exp_f32_e32 v68, v68
	v_exp_f32_e32 v69, v69
	v_add_f32_e32 v68, 1.0, v68
	v_add_f32_e32 v69, 1.0, v69
	v_rcp_f32_e32 v68, v68
	v_rcp_f32_e32 v69, v69
	s_nop 0
	v_pk_mul_f32 v[68:69], v[72:73], v[68:69]
	s_nop 0
	v_pk_mul_f32 v[66:67], v[66:67], v[68:69]
	s_nop 0
	v_cvt_pk_bf16_f32 v66, v66, v67
	v_mul_f32_e32 v67, 0xbfb8aa3b, v74
	v_exp_f32_e32 v67, v67
	s_nop 0
	v_add_f32_e32 v67, 1.0, v67
	v_rcp_f32_e32 v68, v67
	v_mul_f32_e32 v67, 0xbfb8aa3b, v75
	v_exp_f32_e32 v67, v67
	s_nop 0
	v_add_f32_e32 v67, 1.0, v67
	v_rcp_f32_e32 v69, v67
	s_nop 0
	v_pk_mul_f32 v[68:69], v[74:75], v[68:69]
	s_nop 0
	v_pk_mul_f32 v[68:69], v[82:83], v[68:69]
	s_nop 0
	v_cvt_pk_bf16_f32 v67, v68, v69
	global_store_dwordx4 v[80:81], v[64:67], off
	s_nop 1
	v_pk_mul_f32 v[66:67], v[50:51], v[152:153] op_sel_hi:[1,0]
	v_pk_mul_f32 v[50:51], v[48:49], v[152:153] op_sel_hi:[1,0]
	v_mul_f32_e32 v48, 0xbfb8aa3b, v60
	v_mul_f32_e32 v49, 0xbfb8aa3b, v61
	v_exp_f32_e32 v48, v48
	v_exp_f32_e32 v49, v49
	v_mad_i64_i32 v[64:65], s[0:1], v198, s62, v[146:147]
	v_add_f32_e32 v48, 1.0, v48
	v_add_f32_e32 v49, 1.0, v49
	v_rcp_f32_e32 v48, v48
	v_rcp_f32_e32 v49, v49
	v_lshl_add_u64 v[64:65], v[64:65], 0, v[148:149]
	v_pk_mul_f32 v[48:49], v[60:61], v[48:49]
	s_nop 0
	v_pk_mul_f32 v[48:49], v[52:53], v[48:49]
	s_nop 0
	v_cvt_pk_bf16_f32 v48, v48, v49
	v_mul_f32_e32 v49, 0xbfb8aa3b, v62
	v_exp_f32_e32 v49, v49
	s_nop 0
	v_add_f32_e32 v49, 1.0, v49
	v_rcp_f32_e32 v52, v49
	v_mul_f32_e32 v49, 0xbfb8aa3b, v63
	v_exp_f32_e32 v49, v49
	s_nop 0
	v_add_f32_e32 v49, 1.0, v49
	v_rcp_f32_e32 v53, v49
	s_nop 0
	v_pk_mul_f32 v[52:53], v[62:63], v[52:53]
	s_nop 0
	v_pk_mul_f32 v[52:53], v[54:55], v[52:53]
	s_nop 0
	v_cvt_pk_bf16_f32 v49, v52, v53
	v_mul_f32_e32 v52, 0xbfb8aa3b, v56
	v_mul_f32_e32 v53, 0xbfb8aa3b, v57
	v_exp_f32_e32 v52, v52
	v_exp_f32_e32 v53, v53
	v_add_f32_e32 v52, 1.0, v52
	v_add_f32_e32 v53, 1.0, v53
	v_rcp_f32_e32 v52, v52
	v_rcp_f32_e32 v53, v53
	s_nop 0
	v_pk_mul_f32 v[52:53], v[56:57], v[52:53]
	s_nop 0
	v_pk_mul_f32 v[50:51], v[50:51], v[52:53]
	s_nop 0
	v_cvt_pk_bf16_f32 v50, v50, v51
	v_mul_f32_e32 v51, 0xbfb8aa3b, v58
	v_exp_f32_e32 v51, v51
	s_nop 0
	v_add_f32_e32 v51, 1.0, v51
	v_rcp_f32_e32 v52, v51
	v_mul_f32_e32 v51, 0xbfb8aa3b, v59
	v_exp_f32_e32 v51, v51
	s_nop 0
	v_add_f32_e32 v51, 1.0, v51
	v_rcp_f32_e32 v53, v51
	s_nop 0
	v_pk_mul_f32 v[52:53], v[58:59], v[52:53]
	s_nop 0
	v_pk_mul_f32 v[52:53], v[66:67], v[52:53]
	s_nop 0
	v_cvt_pk_bf16_f32 v51, v52, v53
	global_store_dwordx4 v[64:65], v[48:51], off
	s_nop 1
	v_pk_mul_f32 v[50:51], v[34:35], v[150:151] op_sel_hi:[1,0]
	v_pk_mul_f32 v[34:35], v[32:33], v[150:151] op_sel_hi:[1,0]
	v_mul_f32_e32 v32, 0xbfb8aa3b, v44
	v_mul_f32_e32 v33, 0xbfb8aa3b, v45
	v_exp_f32_e32 v32, v32
	v_exp_f32_e32 v33, v33
	v_mad_i64_i32 v[48:49], s[0:1], v196, s62, v[146:147]
	v_add_f32_e32 v32, 1.0, v32
; #define PG8_BAR __builtin_amdgcn_s_barrier()
; #define GAS_ __attribute__((address_space(1)))
; __device__ __forceinline__ unsigned pk2(float lo, float hi) { f32x2_t v = {lo, hi}; bf16x2_t b = __builtin_convertvector(v, bf16x2_t); return __builtin_bit_cast(unsigned, b); }
; __device__ __forceinline__ float silu_f(float g) { return g * __builtin_amdgcn_rcpf(1.0f + __expf(-g)); }
; template <class Epi, class Sched, bool ALIGN_EPI = false, bool SP2 = false>
; __device__ __forceinline__ void gemm_phase(PG8_LAS unsigned char* lds, const Gemm g, const Sched& S, const Epi& E, int wave0) {
;     ...
;         if constexpr (!Epi::AFTER_DRAIN) { E(acc, cur, wr, wc, fr, fq); S.done(cur); }
;         if (!has_next) break;
; #pragma unroll
;         for (int a = 0; a < 2; ++a)
; #pragma unroll
;             for (int b = 0; b < 2; ++b)
; #pragma unroll
;                 for (int m = 0; m < 4; ++m)
; #pragma unroll
;                     for (int n = 0; n < 2; ++n) acc[a][b][m][n] = (f32x4){0.f, 0.f, 0.f, 0.f};
;         cur = nxt; cA = nA; cB = nB; ++ui;
;         if constexpr (ALIGN_EPI) { if (wr == 1) PG8_BAR; }
;     }
;     __device__ __forceinline__ void operator()(const f32x4 (&acc)[2][2][4][2], const Unit& u, int wr, int wc, int fr, int fq) const {
;     ...
;             for (int m = 0; m < 4; ++m) {
;                 bf16_t* rowp = H + (size_t)(row0 + ai * 128 + m * 16) * ldh + hc0;
;                 const float rs = rsv[ai][m];
;                 const f32x4 g0 = acc[ai][0][m][0] * rs, g1 = acc[ai][0][m][1] * rs, u0 = acc[ai][1][m][0] * rs, u1 = acc[ai][1][m][1] * rs;
;                 u32x4 w; w.x = pk2(silu_f(g0[0]) * u0[0], silu_f(g0[1]) * u0[1]); w.y = pk2(silu_f(g0[2]) * u0[2], silu_f(g0[3]) * u0[3]);
;                 w.z = pk2(silu_f(g1[0]) * u1[0], silu_f(g1[1]) * u1[1]); w.w = pk2(silu_f(g1[2]) * u1[2], silu_f(g1[3]) * u1[3]);
;                 *(GAS_ u32x4*)rowp = w;
	v_add_f32_e32 v33, 1.0, v33
	v_rcp_f32_e32 v32, v32
	v_rcp_f32_e32 v33, v33
	v_lshl_add_u64 v[48:49], v[48:49], 0, v[148:149]
	v_pk_mul_f32 v[32:33], v[44:45], v[32:33]
	s_nop 0
	v_pk_mul_f32 v[32:33], v[36:37], v[32:33]
	s_nop 0
	v_cvt_pk_bf16_f32 v32, v32, v33
	v_mul_f32_e32 v33, 0xbfb8aa3b, v46
	v_exp_f32_e32 v33, v33
	s_nop 0
	v_add_f32_e32 v33, 1.0, v33
	v_rcp_f32_e32 v36, v33
	v_mul_f32_e32 v33, 0xbfb8aa3b, v47
	v_exp_f32_e32 v33, v33
	s_nop 0
	v_add_f32_e32 v33, 1.0, v33
	v_rcp_f32_e32 v37, v33
	s_nop 0
	v_pk_mul_f32 v[36:37], v[46:47], v[36:37]
	s_nop 0
	v_pk_mul_f32 v[36:37], v[38:39], v[36:37]
	s_nop 0
	v_cvt_pk_bf16_f32 v33, v36, v37
	v_mul_f32_e32 v36, 0xbfb8aa3b, v40
	v_mul_f32_e32 v37, 0xbfb8aa3b, v41
	v_exp_f32_e32 v36, v36
	v_exp_f32_e32 v37, v37
	v_add_f32_e32 v36, 1.0, v36
	v_add_f32_e32 v37, 1.0, v37
	v_rcp_f32_e32 v36, v36
	v_rcp_f32_e32 v37, v37
	s_nop 0
	v_pk_mul_f32 v[36:37], v[40:41], v[36:37]
	s_nop 0
	v_pk_mul_f32 v[34:35], v[34:35], v[36:37]
	s_nop 0
	v_cvt_pk_bf16_f32 v34, v34, v35
	v_mul_f32_e32 v35, 0xbfb8aa3b, v42
	v_exp_f32_e32 v35, v35
	s_nop 0
	v_add_f32_e32 v35, 1.0, v35
	v_rcp_f32_e32 v36, v35
	v_mul_f32_e32 v35, 0xbfb8aa3b, v43
	v_exp_f32_e32 v35, v35
	s_nop 0
	v_add_f32_e32 v35, 1.0, v35
	v_rcp_f32_e32 v37, v35
	s_nop 0
	v_pk_mul_f32 v[36:37], v[42:43], v[36:37]
	s_nop 0
	v_pk_mul_f32 v[36:37], v[50:51], v[36:37]
	s_nop 0
	v_cvt_pk_bf16_f32 v35, v36, v37
	global_store_dwordx4 v[48:49], v[32:35], off
	s_nop 1
	v_pk_mul_f32 v[34:35], v[18:19], v[144:145] op_sel_hi:[1,0]
	v_pk_mul_f32 v[18:19], v[16:17], v[144:145] op_sel_hi:[1,0]
	v_mul_f32_e32 v16, 0xbfb8aa3b, v28
	v_mul_f32_e32 v17, 0xbfb8aa3b, v29
	v_exp_f32_e32 v16, v16
	v_exp_f32_e32 v17, v17
	v_mad_i64_i32 v[32:33], s[0:1], v194, s62, v[146:147]
	v_add_f32_e32 v16, 1.0, v16
	v_add_f32_e32 v17, 1.0, v17
	v_rcp_f32_e32 v16, v16
	v_rcp_f32_e32 v17, v17
	v_lshl_add_u64 v[32:33], v[32:33], 0, v[148:149]
	s_mov_b64 s[0:1], -1
	v_pk_mul_f32 v[16:17], v[28:29], v[16:17]
	s_nop 0
	v_pk_mul_f32 v[16:17], v[20:21], v[16:17]
	s_nop 0
	v_cvt_pk_bf16_f32 v16, v16, v17
	v_mul_f32_e32 v17, 0xbfb8aa3b, v30
	v_exp_f32_e32 v17, v17
	s_nop 0
	v_add_f32_e32 v17, 1.0, v17
	v_rcp_f32_e32 v20, v17
	v_mul_f32_e32 v17, 0xbfb8aa3b, v31
	v_exp_f32_e32 v17, v17
	s_nop 0
	v_add_f32_e32 v17, 1.0, v17
	v_rcp_f32_e32 v21, v17
	s_nop 0
	v_pk_mul_f32 v[20:21], v[30:31], v[20:21]
	s_nop 0
	v_pk_mul_f32 v[20:21], v[22:23], v[20:21]
	s_nop 0
	v_cvt_pk_bf16_f32 v17, v20, v21
	v_mul_f32_e32 v20, 0xbfb8aa3b, v24
	v_mul_f32_e32 v21, 0xbfb8aa3b, v25
	v_exp_f32_e32 v20, v20
	v_exp_f32_e32 v21, v21
	v_add_f32_e32 v20, 1.0, v20
	v_add_f32_e32 v21, 1.0, v21
	v_rcp_f32_e32 v20, v20
	v_rcp_f32_e32 v21, v21
	s_nop 0
	v_pk_mul_f32 v[20:21], v[24:25], v[20:21]
	s_nop 0
	v_pk_mul_f32 v[18:19], v[18:19], v[20:21]
	s_nop 0
	v_cvt_pk_bf16_f32 v18, v18, v19
	v_mul_f32_e32 v19, 0xbfb8aa3b, v26
	v_exp_f32_e32 v19, v19
	s_nop 0
	v_add_f32_e32 v19, 1.0, v19
	v_rcp_f32_e32 v20, v19
	v_mul_f32_e32 v19, 0xbfb8aa3b, v27
	v_exp_f32_e32 v19, v19
	s_nop 0
	v_add_f32_e32 v19, 1.0, v19
	v_rcp_f32_e32 v21, v19
	s_nop 0
	v_pk_mul_f32 v[20:21], v[26:27], v[20:21]
	s_nop 0
	v_pk_mul_f32 v[20:21], v[34:35], v[20:21]
	s_nop 0
	v_cvt_pk_bf16_f32 v19, v20, v21
	global_store_dwordx4 v[32:33], v[16:19], off
	s_cbranch_vccnz .LBB0_1228
	s_andn2_b64 vcc, exec, s[10:11]
	s_cbranch_vccnz .LBB0_1227
	s_barrier
	v_readlane_b32 s100, v219, 0
	s_nop 1
	s_lshr_b32 s100, s100, 5
	s_and_b32 s101, s100, 1
	s_lshl_b32 s101, s101, 7
	s_lshr_b32 m0, s100, 1
	s_lshl_b32 m0, m0, 6
	s_add_i32 s101, s101, m0
	s_lshl_b32 m0, s18, 8
	s_add_i32 s101, s101, m0
	v_and_b32_e32 v16, 15, v217
	v_add_u32_e32 v16, s101, v16
	v_lshlrev_b32_e32 v16, 6, v16
	v_mov_b32_e32 v17, 0
	v_lshl_add_u64 v[16:17], v[188:189], 0, v[16:17]
	s_lshl_b32 s100, s100, 12
	s_add_i32 m0, s100, 0x24000
	s_nop 0
	global_load_lds_dwordx4 v[16:17], off
	global_load_lds_dwordx4 v[16:17], off offset:1024
	global_load_lds_dwordx4 v[16:17], off offset:2048
	global_load_lds_dwordx4 v[16:17], off offset:3072
	s_branch .LBB0_1227

; #define GAS_ __attribute__((address_space(1)))
;     __device__ __forceinline__ void operator()(const f32x4 (&acc)[2][2][4][2], const Unit& u, int wr, int wc, int fr, int fq) const {
;     ...
;         for (int ai = 0; ai < 2; ++ai) {
;             f32x4 bs[4][2][2]; u32x4 bh[4][2];
; #pragma unroll
;             for (int m = 0; m < 4; ++m) { const size_t off = (size_t)(row0 + ai * 128 + m * 16) * ldc + col0;
; #pragma unroll
;                 for (int bj = 0; bj < 2; ++bj) {
;                     if (BASE_F32) { bs[m][bj][0] = *(const GAS_ f32x4*)(basef + off + bj * 128); bs[m][bj][1] = *(const GAS_ f32x4*)(basef + off + bj * 128 + 4); }
;                     else bh[m][bj] = *(const GAS_ u32x4*)(XB + off + bj * 128); } }
;             asm volatile("" ::: "memory");
; #pragma unroll
;             for (int m = 0; m < 4; ++m) {
;                 const size_t off = (size_t)(row0 + ai * 128 + m * 16) * ldc + col0;
;                 float ssq = 0.f;
; #pragma unroll
;                 for (int bj = 0; bj < 2; ++bj) {
;                     f32x4 b0, b1;
;                     if (BASE_F32) { b0 = bs[m][bj][0]; b1 = bs[m][bj][1]; }
;                     else { const u32x4 h = bh[m][bj];
;                         b0 = (f32x4){__builtin_bit_cast(float, h.x << 16), __builtin_bit_cast(float, h.x & 0xffff0000u), __builtin_bit_cast(float, h.y << 16), __builtin_bit_cast(float, h.y & 0xffff0000u)};
;                         b1 = (f32x4){__builtin_bit_cast(float, h.z << 16), __builtin_bit_cast(float, h.z & 0xffff0000u), __builtin_bit_cast(float, h.w << 16), __builtin_bit_cast(float, h.w & 0xffff0000u)}; }
;                     const f32x4 v0 = b0 + acc[ai][bj][m][0], v1 = b1 + acc[ai][bj][m][1];
;                     ssq += ((v0[0] * v0[0] + v0[1] * v0[1]) + (v0[2] * v0[2] + v0[3] * v0[3])) + ((v1[0] * v1[0] + v1[1] * v1[1]) + (v1[2] * v1[2] + v1[3] * v1[3]));
;                     u32x4 w; w.x = pk2(v0[0], v0[1]); w.y = pk2(v0[2], v0[3]); w.z = pk2(v1[0], v1[1]); w.w = pk2(v1[2], v1[3]); *(GAS_ u32x4*)(XB + off + bj * 128) = w;
;                 }
;                 ssq += __shfl_xor(ssq, 16); ssq += __shfl_xor(ssq, 32);
;                 if (fq == 0) *(GAS_ float*)(SS + (size_t)(row0 + ai * 128 + m * 16) * 16 + u.pn * 4 + wc) = ssq;
;             }
.LBB0_1305:
	v_lshl_or_b32 v188, s43, 8, v202
	v_lshl_add_u32 v192, s44, 8, v200
	v_ashrrev_i32_e32 v189, 31, v188
	v_lshlrev_b64 v[180:181], 1, v[188:189]
	v_ashrrev_i32_e32 v193, 31, v192
	v_lshl_add_u64 v[190:191], s[4:5], 0, v[180:181]
	v_lshlrev_b64 v[208:209], 11, v[192:193]
	v_lshl_add_u64 v[144:145], v[190:191], 0, v[208:209]
	global_load_dwordx4 v[204:207], v[144:145], off
	global_load_dwordx4 v[168:171], v[144:145], off offset:256
	v_or_b32_e32 v198, 16, v192
	v_ashrrev_i32_e32 v199, 31, v198
	v_lshlrev_b64 v[144:145], 11, v[198:199]
	v_or_b32_e32 v196, 32, v192
	v_lshl_add_u64 v[144:145], v[190:191], 0, v[144:145]
	v_ashrrev_i32_e32 v197, 31, v196
	global_load_dwordx4 v[164:167], v[144:145], off
	global_load_dwordx4 v[160:163], v[144:145], off offset:256
	v_lshlrev_b64 v[144:145], 11, v[196:197]
	v_or_b32_e32 v194, 48, v192
	v_lshl_add_u64 v[144:145], v[190:191], 0, v[144:145]
	v_ashrrev_i32_e32 v195, 31, v194
	global_load_dwordx4 v[156:159], v[144:145], off
	global_load_dwordx4 v[152:155], v[144:145], off offset:256
	v_lshlrev_b64 v[144:145], 11, v[194:195]
	v_lshl_add_u64 v[144:145], v[190:191], 0, v[144:145]
	global_load_dwordx4 v[148:151], v[144:145], off
	s_nop 0
	global_load_dwordx4 v[144:147], v[144:145], off offset:256
	v_and_b32_e32 v179, 64, v212
	v_xor_b32_e32 v178, 16, v212
	v_add_u32_e32 v179, 64, v179
	v_cmp_lt_i32_e32 vcc, v178, v179
	v_xor_b32_e32 v210, 32, v212
	s_lshl_b32 s18, s43, 2
	v_cndmask_b32_e32 v178, v212, v178, vcc
	v_cmp_lt_i32_e32 vcc, v210, v179
	v_lshlrev_b32_e32 v178, 2, v178
	s_ashr_i32 s19, s18, 31
	v_cndmask_b32_e32 v179, v212, v210, vcc
	v_lshlrev_b32_e32 v179, 2, v179
	s_waitcnt vmcnt(0)
	v_lshlrev_b32_e32 v210, 16, v204
	v_and_b32_e32 v211, 0xffff0000, v204
	v_lshlrev_b32_e32 v204, 16, v205
	v_and_b32_e32 v205, 0xffff0000, v205
	v_lshlrev_b32_e32 v218, 16, v206
	v_and_b32_e32 v219, 0xffff0000, v206
	v_lshlrev_b32_e32 v206, 16, v207
	v_and_b32_e32 v207, 0xffff0000, v207
	v_pk_add_f32 v[142:143], v[142:143], v[204:205]
	v_pk_add_f32 v[140:141], v[140:141], v[210:211]
	v_pk_add_f32 v[204:205], v[138:139], v[206:207]
	v_mul_f32_e32 v138, v141, v141
	v_mul_f32_e32 v139, v143, v143
	v_pk_add_f32 v[136:137], v[136:137], v[218:219]
	v_fmac_f32_e32 v138, v140, v140
	v_fmac_f32_e32 v139, v142, v142
	v_add_f32_e32 v138, v138, v139
	v_mul_f32_e32 v139, v137, v137
	v_mul_f32_e32 v206, v205, v205
	v_fmac_f32_e32 v139, v136, v136
	v_fmac_f32_e32 v206, v204, v204
	v_add_f32_e32 v139, v139, v206
	v_add_f32_e32 v206, v138, v139
	v_cvt_pk_bf16_f32 v138, v140, v141
	v_cvt_pk_bf16_f32 v140, v136, v137
	v_lshl_add_u64 v[136:137], s[4:5], 0, v[208:209]
	v_cvt_pk_bf16_f32 v139, v142, v143
	v_cvt_pk_bf16_f32 v141, v204, v205
	v_lshl_add_u64 v[136:137], v[136:137], 0, v[180:181]
	global_store_dwordx4 v[136:137], v[138:141], off
	v_lshlrev_b32_e32 v142, 16, v170
	v_and_b32_e32 v143, 0xffff0000, v170
	v_lshlrev_b32_e32 v138, 16, v168
	v_and_b32_e32 v139, 0xffff0000, v168
	v_lshlrev_b32_e32 v140, 16, v169
	v_and_b32_e32 v141, 0xffff0000, v169
	v_lshlrev_b32_e32 v168, 16, v171
	v_and_b32_e32 v169, 0xffff0000, v171
	v_pk_add_f32 v[134:135], v[134:135], v[140:141]
	v_pk_add_f32 v[132:133], v[132:133], v[138:139]
	v_pk_add_f32 v[138:139], v[130:131], v[168:169]
	v_pk_add_f32 v[130:131], v[128:129], v[142:143]
	v_mul_f32_e32 v128, v133, v133
	v_mul_f32_e32 v129, v135, v135
	v_fmac_f32_e32 v128, v132, v132
	v_fmac_f32_e32 v129, v134, v134
	v_add_f32_e32 v128, v128, v129
	v_mul_f32_e32 v129, v131, v131
	v_mul_f32_e32 v140, v139, v139
	v_fmac_f32_e32 v129, v130, v130
	v_fmac_f32_e32 v140, v138, v138
	v_add_f32_e32 v129, v129, v140
	v_add_f32_e32 v128, v128, v129
	v_add_f32_e32 v140, v206, v128
	v_cvt_pk_bf16_f32 v128, v132, v133
	v_cvt_pk_bf16_f32 v129, v134, v135
	v_cvt_pk_bf16_f32 v130, v130, v131
	v_cvt_pk_bf16_f32 v131, v138, v139
	global_store_dwordx4 v[136:137], v[128:131], off offset:256
	s_nop 1
	v_mov_b32_e32 v128, v140
	s_nop 1
	v_permlane16_swap_b32_e32 v140, v128
	s_waitcnt lgkmcnt(0)
	v_add_f32_e32 v128, v140, v128
	v_mov_b32_e32 v129, v128
	s_nop 1
	v_permlane32_swap_b32_e32 v128, v129
	s_and_saveexec_b64 s[20:21], s[6:7]
	s_cbranch_execz .LBB0_1307
	v_readlane_b32 s44, v254, 18
	v_readlane_b32 s45, v254, 19
	v_readlane_b32 s49, v254, 23
	v_readlane_b32 s52, v254, 26
	v_readlane_b32 s48, v254, 22
	v_readlane_b32 s50, v254, 24
	v_readlane_b32 s51, v254, 25
	v_readlane_b32 s53, v254, 27
	v_readlane_b32 s54, v254, 28
	v_readlane_b32 s55, v254, 29
	v_readlane_b32 s56, v254, 30
	v_readlane_b32 s57, v254, 31
	v_readlane_b32 s58, v254, 32
	v_readlane_b32 s59, v254, 33
	s_mov_b32 s52, 0xff800000
	s_mov_b32 s49, s45
	v_readlane_b32 s46, v254, 20
	v_readlane_b32 s47, v254, 21
	v_writelane_b32 v254, s48, 18
	v_lshlrev_b64 v[130:131], 6, v[192:193]
	v_lshl_add_u64 v[130:131], s[12:13], 0, v[130:131]
	v_writelane_b32 v254, s49, 19
	v_writelane_b32 v254, s50, 20
	v_writelane_b32 v254, s51, 21
	v_writelane_b32 v254, s52, 22
	v_writelane_b32 v254, s53, 23
	v_writelane_b32 v254, s54, 24
	v_writelane_b32 v254, s55, 25
	v_writelane_b32 v254, s56, 26
	v_writelane_b32 v254, s57, 27
	v_writelane_b32 v254, s58, 28
	v_writelane_b32 v254, s59, 29
	v_writelane_b32 v254, s60, 30
	v_writelane_b32 v254, s61, 31
	v_lshl_add_u64 v[130:131], s[18:19], 2, v[130:131]
	s_lshl_b32 s44, s35, 2
	v_writelane_b32 v254, s62, 32
	v_writelane_b32 v254, s63, 33
	v_lshl_add_u64 v[130:131], v[130:131], 0, s[44:45]
	s_waitcnt lgkmcnt(0)
	v_add_f32_e32 v128, v128, v129
	global_store_dword v[130:131], v128, off
; #define GAS_ __attribute__((address_space(1)))
; __device__ __forceinline__ unsigned pk2(float lo, float hi) { f32x2_t v = {lo, hi}; bf16x2_t b = __builtin_convertvector(v, bf16x2_t); return __builtin_bit_cast(unsigned, b); }
;     __device__ __forceinline__ void operator()(const f32x4 (&acc)[2][2][4][2], const Unit& u, int wr, int wc, int fr, int fq) const {
;     ...
;             for (int m = 0; m < 4; ++m) {
;                 const size_t off = (size_t)(row0 + ai * 128 + m * 16) * ldc + col0;
;                 float ssq = 0.f;
; #pragma unroll
;                 for (int bj = 0; bj < 2; ++bj) {
;                     f32x4 b0, b1;
;                     if (BASE_F32) { b0 = bs[m][bj][0]; b1 = bs[m][bj][1]; }
;                     else { const u32x4 h = bh[m][bj];
;                         b0 = (f32x4){__builtin_bit_cast(float, h.x << 16), __builtin_bit_cast(float, h.x & 0xffff0000u), __builtin_bit_cast(float, h.y << 16), __builtin_bit_cast(float, h.y & 0xffff0000u)};
;                         b1 = (f32x4){__builtin_bit_cast(float, h.z << 16), __builtin_bit_cast(float, h.z & 0xffff0000u), __builtin_bit_cast(float, h.w << 16), __builtin_bit_cast(float, h.w & 0xffff0000u)}; }
;                     const f32x4 v0 = b0 + acc[ai][bj][m][0], v1 = b1 + acc[ai][bj][m][1];
;                     ssq += ((v0[0] * v0[0] + v0[1] * v0[1]) + (v0[2] * v0[2] + v0[3] * v0[3])) + ((v1[0] * v1[0] + v1[1] * v1[1]) + (v1[2] * v1[2] + v1[3] * v1[3]));
;                     u32x4 w; w.x = pk2(v0[0], v0[1]); w.y = pk2(v0[2], v0[3]); w.z = pk2(v1[0], v1[1]); w.w = pk2(v1[2], v1[3]); *(GAS_ u32x4*)(XB + off + bj * 128) = w;
;                 }
;                 ssq += __shfl_xor(ssq, 16); ssq += __shfl_xor(ssq, 32);
;                 if (fq == 0) *(GAS_ float*)(SS + (size_t)(row0 + ai * 128 + m * 16) * 16 + u.pn * 4 + wc) = ssq;
;             }
.LBB0_1307:
	s_or_b64 exec, exec, s[20:21]
	v_lshlrev_b32_e32 v130, 16, v164
	v_and_b32_e32 v131, 0xffff0000, v164
	v_lshlrev_b32_e32 v132, 16, v165
	v_and_b32_e32 v133, 0xffff0000, v165
	v_lshlrev_b32_e32 v134, 16, v166
	v_and_b32_e32 v135, 0xffff0000, v166
	v_lshlrev_b32_e32 v136, 16, v167
	v_and_b32_e32 v137, 0xffff0000, v167
	v_pk_add_f32 v[126:127], v[126:127], v[132:133]
	v_pk_add_f32 v[124:125], v[124:125], v[130:131]
	v_pk_add_f32 v[130:131], v[122:123], v[136:137]
	v_pk_add_f32 v[122:123], v[120:121], v[134:135]
	v_mul_f32_e32 v120, v125, v125
	v_mul_f32_e32 v121, v127, v127
	v_fmac_f32_e32 v120, v124, v124
	v_fmac_f32_e32 v121, v126, v126
	v_add_f32_e32 v120, v120, v121
	v_mul_f32_e32 v121, v123, v123
	v_mul_f32_e32 v132, v131, v131
	v_fmac_f32_e32 v121, v122, v122
	v_fmac_f32_e32 v132, v130, v130
	v_add_f32_e32 v121, v121, v132
	v_add_f32_e32 v134, v120, v121
	v_cvt_pk_bf16_f32 v120, v124, v125
	v_cvt_pk_bf16_f32 v121, v126, v127
	v_lshlrev_b32_e32 v124, 16, v160
	v_and_b32_e32 v125, 0xffff0000, v160
	v_lshlrev_b32_e32 v126, 16, v161
	v_and_b32_e32 v127, 0xffff0000, v161
	v_cvt_pk_bf16_f32 v122, v122, v123
	v_cvt_pk_bf16_f32 v123, v130, v131
	v_lshlrev_b32_e32 v130, 16, v162
	v_and_b32_e32 v131, 0xffff0000, v162
	v_pk_add_f32 v[118:119], v[118:119], v[126:127]
	v_pk_add_f32 v[116:117], v[116:117], v[124:125]
	v_lshlrev_b32_e32 v132, 16, v163
	v_and_b32_e32 v133, 0xffff0000, v163
	v_pk_add_f32 v[126:127], v[112:113], v[130:131]
	v_mul_f32_e32 v112, v117, v117
	v_mul_f32_e32 v113, v119, v119
	v_pk_add_f32 v[124:125], v[114:115], v[132:133]
	v_fmac_f32_e32 v112, v116, v116
	v_fmac_f32_e32 v113, v118, v118
	v_add_f32_e32 v112, v112, v113
	v_mul_f32_e32 v113, v127, v127
	v_mul_f32_e32 v114, v125, v125
	v_fmac_f32_e32 v113, v126, v126
	v_fmac_f32_e32 v114, v124, v124
	v_add_f32_e32 v113, v113, v114
	v_add_f32_e32 v112, v112, v113
	v_add_f32_e32 v115, v134, v112
	v_mov_b32_e32 v130, v115
	s_nop 1
	v_permlane16_swap_b32_e32 v115, v130
	s_waitcnt lgkmcnt(1)
	v_lshlrev_b64 v[128:129], 10, v[198:199]
	v_lshl_add_u64 v[112:113], v[128:129], 1, s[4:5]
	v_lshl_add_u64 v[128:129], v[188:189], 1, v[112:113]
	v_cvt_pk_bf16_f32 v114, v116, v117
	s_waitcnt lgkmcnt(0)
	v_add_f32_e32 v112, v115, v130
	v_mov_b32_e32 v113, v112
	s_nop 1
	v_permlane32_swap_b32_e32 v112, v113
	v_cvt_pk_bf16_f32 v115, v118, v119
	v_cvt_pk_bf16_f32 v116, v126, v127
	v_cvt_pk_bf16_f32 v117, v124, v125
	global_store_dwordx4 v[128:129], v[120:123], off
	global_store_dwordx4 v[128:129], v[114:117], off offset:256
	s_and_saveexec_b64 s[20:21], s[6:7]
	s_cbranch_execz .LBB0_1309
	v_readlane_b32 s44, v254, 18
	v_readlane_b32 s45, v254, 19
	v_readlane_b32 s49, v254, 23
	v_readlane_b32 s52, v254, 26
	v_readlane_b32 s48, v254, 22
	v_readlane_b32 s50, v254, 24
	v_readlane_b32 s51, v254, 25
	v_readlane_b32 s53, v254, 27
	v_readlane_b32 s54, v254, 28
	v_readlane_b32 s55, v254, 29
	v_readlane_b32 s56, v254, 30
	v_readlane_b32 s57, v254, 31
	v_readlane_b32 s58, v254, 32
	v_readlane_b32 s59, v254, 33
	s_mov_b32 s52, 0xff800000
	s_mov_b32 s49, s45
	v_readlane_b32 s46, v254, 20
	v_readlane_b32 s47, v254, 21
	v_writelane_b32 v254, s48, 18
	v_lshlrev_b64 v[114:115], 6, v[198:199]
	v_lshl_add_u64 v[114:115], s[12:13], 0, v[114:115]
	v_writelane_b32 v254, s49, 19
	v_writelane_b32 v254, s50, 20
	v_writelane_b32 v254, s51, 21
	v_writelane_b32 v254, s52, 22
	v_writelane_b32 v254, s53, 23
	v_writelane_b32 v254, s54, 24
	v_writelane_b32 v254, s55, 25
	v_writelane_b32 v254, s56, 26
	v_writelane_b32 v254, s57, 27
	v_writelane_b32 v254, s58, 28
	v_writelane_b32 v254, s59, 29
	v_writelane_b32 v254, s60, 30
	v_writelane_b32 v254, s61, 31
	v_lshl_add_u64 v[114:115], s[18:19], 2, v[114:115]
	s_lshl_b32 s44, s35, 2
	v_writelane_b32 v254, s62, 32
	v_writelane_b32 v254, s63, 33
	v_lshl_add_u64 v[114:115], v[114:115], 0, s[44:45]
	s_waitcnt lgkmcnt(0)
	v_add_f32_e32 v112, v112, v113
	global_store_dword v[114:115], v112, off
.LBB0_1309:
	s_or_b64 exec, exec, s[20:21]
	v_lshlrev_b32_e32 v114, 16, v156
	v_and_b32_e32 v115, 0xffff0000, v156
	v_lshlrev_b32_e32 v116, 16, v157
	v_and_b32_e32 v117, 0xffff0000, v157
	v_lshlrev_b32_e32 v118, 16, v158
	v_and_b32_e32 v119, 0xffff0000, v158
	v_lshlrev_b32_e32 v120, 16, v159
	v_and_b32_e32 v121, 0xffff0000, v159
	v_pk_add_f32 v[110:111], v[110:111], v[116:117]
	v_pk_add_f32 v[108:109], v[108:109], v[114:115]
	v_pk_add_f32 v[114:115], v[106:107], v[120:121]
	v_pk_add_f32 v[106:107], v[104:105], v[118:119]
	v_mul_f32_e32 v104, v109, v109
	v_mul_f32_e32 v105, v111, v111
	v_fmac_f32_e32 v104, v108, v108
	v_fmac_f32_e32 v105, v110, v110
	v_add_f32_e32 v104, v104, v105
	v_mul_f32_e32 v105, v107, v107
	v_mul_f32_e32 v116, v115, v115
	v_fmac_f32_e32 v105, v106, v106
	v_fmac_f32_e32 v116, v114, v114
	v_add_f32_e32 v105, v105, v116
	v_add_f32_e32 v118, v104, v105
	v_cvt_pk_bf16_f32 v104, v108, v109
	v_cvt_pk_bf16_f32 v105, v110, v111
	v_lshlrev_b32_e32 v108, 16, v152
	v_and_b32_e32 v109, 0xffff0000, v152
	v_lshlrev_b32_e32 v110, 16, v153
	v_and_b32_e32 v111, 0xffff0000, v153
	v_cvt_pk_bf16_f32 v106, v106, v107
	v_cvt_pk_bf16_f32 v107, v114, v115
	v_lshlrev_b32_e32 v114, 16, v154
	v_and_b32_e32 v115, 0xffff0000, v154
	v_pk_add_f32 v[102:103], v[102:103], v[110:111]
	v_pk_add_f32 v[100:101], v[100:101], v[108:109]
	v_lshlrev_b32_e32 v116, 16, v155
	v_and_b32_e32 v117, 0xffff0000, v155
	v_pk_add_f32 v[110:111], v[96:97], v[114:115]
	v_mul_f32_e32 v96, v101, v101
	v_mul_f32_e32 v97, v103, v103
	v_pk_add_f32 v[108:109], v[98:99], v[116:117]
	v_fmac_f32_e32 v96, v100, v100
	v_fmac_f32_e32 v97, v102, v102
	v_add_f32_e32 v96, v96, v97
	v_mul_f32_e32 v97, v111, v111
	v_mul_f32_e32 v98, v109, v109
	v_fmac_f32_e32 v97, v110, v110
	v_fmac_f32_e32 v98, v108, v108
	v_add_f32_e32 v97, v97, v98
	v_add_f32_e32 v96, v96, v97
	v_add_f32_e32 v99, v118, v96
	v_mov_b32_e32 v114, v99
	s_nop 1
	v_permlane16_swap_b32_e32 v99, v114
	s_waitcnt lgkmcnt(1)
	v_lshlrev_b64 v[112:113], 10, v[196:197]
	v_lshl_add_u64 v[96:97], v[112:113], 1, s[4:5]
	v_lshl_add_u64 v[112:113], v[188:189], 1, v[96:97]
	v_cvt_pk_bf16_f32 v98, v100, v101
	s_waitcnt lgkmcnt(0)
	v_add_f32_e32 v96, v99, v114
	v_mov_b32_e32 v97, v96
	s_nop 1
	v_permlane32_swap_b32_e32 v96, v97
	v_cvt_pk_bf16_f32 v99, v102, v103
	v_cvt_pk_bf16_f32 v100, v110, v111
	v_cvt_pk_bf16_f32 v101, v108, v109
	global_store_dwordx4 v[112:113], v[104:107], off
	global_store_dwordx4 v[112:113], v[98:101], off offset:256
	s_and_saveexec_b64 s[20:21], s[6:7]
	s_cbranch_execz .LBB0_1311
; #define GAS_ __attribute__((address_space(1)))
; __device__ __forceinline__ unsigned pk2(float lo, float hi) { f32x2_t v = {lo, hi}; bf16x2_t b = __builtin_convertvector(v, bf16x2_t); return __builtin_bit_cast(unsigned, b); }
;     __device__ __forceinline__ void operator()(const f32x4 (&acc)[2][2][4][2], const Unit& u, int wr, int wc, int fr, int fq) const {
;     ...
;             for (int m = 0; m < 4; ++m) {
;                 const size_t off = (size_t)(row0 + ai * 128 + m * 16) * ldc + col0;
;                 float ssq = 0.f;
; #pragma unroll
;                 for (int bj = 0; bj < 2; ++bj) {
;                     f32x4 b0, b1;
;                     if (BASE_F32) { b0 = bs[m][bj][0]; b1 = bs[m][bj][1]; }
;                     else { const u32x4 h = bh[m][bj];
;                         b0 = (f32x4){__builtin_bit_cast(float, h.x << 16), __builtin_bit_cast(float, h.x & 0xffff0000u), __builtin_bit_cast(float, h.y << 16), __builtin_bit_cast(float, h.y & 0xffff0000u)};
;                         b1 = (f32x4){__builtin_bit_cast(float, h.z << 16), __builtin_bit_cast(float, h.z & 0xffff0000u), __builtin_bit_cast(float, h.w << 16), __builtin_bit_cast(float, h.w & 0xffff0000u)}; }
;                     const f32x4 v0 = b0 + acc[ai][bj][m][0], v1 = b1 + acc[ai][bj][m][1];
;                     ssq += ((v0[0] * v0[0] + v0[1] * v0[1]) + (v0[2] * v0[2] + v0[3] * v0[3])) + ((v1[0] * v1[0] + v1[1] * v1[1]) + (v1[2] * v1[2] + v1[3] * v1[3]));
;                     u32x4 w; w.x = pk2(v0[0], v0[1]); w.y = pk2(v0[2], v0[3]); w.z = pk2(v1[0], v1[1]); w.w = pk2(v1[2], v1[3]); *(GAS_ u32x4*)(XB + off + bj * 128) = w;
;                 }
;                 ssq += __shfl_xor(ssq, 16); ssq += __shfl_xor(ssq, 32);
;                 if (fq == 0) *(GAS_ float*)(SS + (size_t)(row0 + ai * 128 + m * 16) * 16 + u.pn * 4 + wc) = ssq;
;             }
	v_readlane_b32 s44, v254, 18
	v_readlane_b32 s45, v254, 19
	v_readlane_b32 s49, v254, 23
	v_readlane_b32 s52, v254, 26
	v_readlane_b32 s48, v254, 22
	v_readlane_b32 s50, v254, 24
	v_readlane_b32 s51, v254, 25
	v_readlane_b32 s53, v254, 27
	v_readlane_b32 s54, v254, 28
	v_readlane_b32 s55, v254, 29
	v_readlane_b32 s56, v254, 30
	v_readlane_b32 s57, v254, 31
	v_readlane_b32 s58, v254, 32
	v_readlane_b32 s59, v254, 33
	s_mov_b32 s52, 0xff800000
	s_mov_b32 s49, s45
	v_readlane_b32 s46, v254, 20
	v_readlane_b32 s47, v254, 21
	v_writelane_b32 v254, s48, 18
	v_lshlrev_b64 v[98:99], 6, v[196:197]
	v_lshl_add_u64 v[98:99], s[12:13], 0, v[98:99]
	v_writelane_b32 v254, s49, 19
	v_writelane_b32 v254, s50, 20
	v_writelane_b32 v254, s51, 21
	v_writelane_b32 v254, s52, 22
	v_writelane_b32 v254, s53, 23
	v_writelane_b32 v254, s54, 24
	v_writelane_b32 v254, s55, 25
	v_writelane_b32 v254, s56, 26
	v_writelane_b32 v254, s57, 27
	v_writelane_b32 v254, s58, 28
	v_writelane_b32 v254, s59, 29
	v_writelane_b32 v254, s60, 30
	v_writelane_b32 v254, s61, 31
	v_lshl_add_u64 v[98:99], s[18:19], 2, v[98:99]
	s_lshl_b32 s44, s35, 2
	v_writelane_b32 v254, s62, 32
	v_writelane_b32 v254, s63, 33
	v_lshl_add_u64 v[98:99], v[98:99], 0, s[44:45]
	s_waitcnt lgkmcnt(0)
	v_add_f32_e32 v96, v96, v97
	global_store_dword v[98:99], v96, off
.LBB0_1311:
	s_or_b64 exec, exec, s[20:21]
	v_lshlrev_b32_e32 v98, 16, v148
	v_and_b32_e32 v99, 0xffff0000, v148
	v_lshlrev_b32_e32 v100, 16, v149
	v_and_b32_e32 v101, 0xffff0000, v149
	v_lshlrev_b32_e32 v102, 16, v150
	v_and_b32_e32 v103, 0xffff0000, v150
	v_lshlrev_b32_e32 v104, 16, v151
	v_and_b32_e32 v105, 0xffff0000, v151
	v_pk_add_f32 v[94:95], v[94:95], v[100:101]
	v_pk_add_f32 v[92:93], v[92:93], v[98:99]
	v_pk_add_f32 v[98:99], v[90:91], v[104:105]
	v_pk_add_f32 v[90:91], v[88:89], v[102:103]
	v_mul_f32_e32 v88, v93, v93
	v_mul_f32_e32 v89, v95, v95
	v_fmac_f32_e32 v88, v92, v92
	v_fmac_f32_e32 v89, v94, v94
	v_add_f32_e32 v88, v88, v89
	v_mul_f32_e32 v89, v91, v91
	v_mul_f32_e32 v100, v99, v99
	v_fmac_f32_e32 v89, v90, v90
	v_fmac_f32_e32 v100, v98, v98
	v_add_f32_e32 v89, v89, v100
	v_add_f32_e32 v102, v88, v89
	v_cvt_pk_bf16_f32 v88, v92, v93
	v_cvt_pk_bf16_f32 v89, v94, v95
	v_lshlrev_b32_e32 v92, 16, v144
	v_and_b32_e32 v93, 0xffff0000, v144
	v_lshlrev_b32_e32 v94, 16, v145
	v_and_b32_e32 v95, 0xffff0000, v145
	v_cvt_pk_bf16_f32 v90, v90, v91
	v_cvt_pk_bf16_f32 v91, v98, v99
	v_lshlrev_b32_e32 v98, 16, v146
	v_and_b32_e32 v99, 0xffff0000, v146
	v_pk_add_f32 v[86:87], v[86:87], v[94:95]
	v_pk_add_f32 v[84:85], v[84:85], v[92:93]
	v_lshlrev_b32_e32 v100, 16, v147
	v_and_b32_e32 v101, 0xffff0000, v147
	v_pk_add_f32 v[94:95], v[80:81], v[98:99]
	v_mul_f32_e32 v80, v85, v85
	v_mul_f32_e32 v81, v87, v87
	v_pk_add_f32 v[92:93], v[82:83], v[100:101]
	v_fmac_f32_e32 v80, v84, v84
	v_fmac_f32_e32 v81, v86, v86
	v_add_f32_e32 v80, v80, v81
	v_mul_f32_e32 v81, v95, v95
	v_mul_f32_e32 v82, v93, v93
	v_fmac_f32_e32 v81, v94, v94
	v_fmac_f32_e32 v82, v92, v92
	v_add_f32_e32 v81, v81, v82
	v_add_f32_e32 v80, v80, v81
	v_add_f32_e32 v83, v102, v80
	v_mov_b32_e32 v98, v83
	s_nop 1
	v_permlane16_swap_b32_e32 v83, v98
	s_waitcnt lgkmcnt(1)
	v_lshlrev_b64 v[96:97], 10, v[194:195]
	v_lshl_add_u64 v[80:81], v[96:97], 1, s[4:5]
	v_lshl_add_u64 v[96:97], v[188:189], 1, v[80:81]
	v_cvt_pk_bf16_f32 v82, v84, v85
	s_waitcnt lgkmcnt(0)
	v_add_f32_e32 v80, v83, v98
	v_mov_b32_e32 v81, v80
	s_nop 1
	v_permlane32_swap_b32_e32 v80, v81
	v_cvt_pk_bf16_f32 v83, v86, v87
	v_cvt_pk_bf16_f32 v84, v94, v95
	v_cvt_pk_bf16_f32 v85, v92, v93
	global_store_dwordx4 v[96:97], v[88:91], off
	global_store_dwordx4 v[96:97], v[82:85], off offset:256
	s_and_saveexec_b64 s[20:21], s[6:7]
	s_cbranch_execz .LBB0_1313
	v_readlane_b32 s44, v254, 18
	v_readlane_b32 s45, v254, 19
	v_readlane_b32 s49, v254, 23
	v_readlane_b32 s52, v254, 26
	v_readlane_b32 s48, v254, 22
	v_readlane_b32 s50, v254, 24
	v_readlane_b32 s51, v254, 25
	v_readlane_b32 s53, v254, 27
	v_readlane_b32 s54, v254, 28
	v_readlane_b32 s55, v254, 29
	v_readlane_b32 s56, v254, 30
	v_readlane_b32 s57, v254, 31
	v_readlane_b32 s58, v254, 32
	v_readlane_b32 s59, v254, 33
	s_mov_b32 s52, 0xff800000
	s_mov_b32 s49, s45
	v_readlane_b32 s46, v254, 20
	v_readlane_b32 s47, v254, 21
	v_writelane_b32 v254, s48, 18
	v_lshlrev_b64 v[82:83], 6, v[194:195]
	v_lshl_add_u64 v[82:83], s[12:13], 0, v[82:83]
	v_writelane_b32 v254, s49, 19
	v_writelane_b32 v254, s50, 20
	v_writelane_b32 v254, s51, 21
	v_writelane_b32 v254, s52, 22
	v_writelane_b32 v254, s53, 23
	v_writelane_b32 v254, s54, 24
	v_writelane_b32 v254, s55, 25
	v_writelane_b32 v254, s56, 26
	v_writelane_b32 v254, s57, 27
	v_writelane_b32 v254, s58, 28
	v_writelane_b32 v254, s59, 29
	v_writelane_b32 v254, s60, 30
	v_writelane_b32 v254, s61, 31
	v_lshl_add_u64 v[82:83], s[18:19], 2, v[82:83]
	s_lshl_b32 s44, s35, 2
	v_writelane_b32 v254, s62, 32
	v_writelane_b32 v254, s63, 33
	v_lshl_add_u64 v[82:83], v[82:83], 0, s[44:45]
	s_waitcnt lgkmcnt(0)
	v_add_f32_e32 v80, v80, v81
	global_store_dword v[82:83], v80, off
; #define GAS_ __attribute__((address_space(1)))
;     __device__ __forceinline__ void operator()(const f32x4 (&acc)[2][2][4][2], const Unit& u, int wr, int wc, int fr, int fq) const {
;     ...
;         for (int ai = 0; ai < 2; ++ai) {
;             f32x4 bs[4][2][2]; u32x4 bh[4][2];
; #pragma unroll
;             for (int m = 0; m < 4; ++m) { const size_t off = (size_t)(row0 + ai * 128 + m * 16) * ldc + col0;
; #pragma unroll
;                 for (int bj = 0; bj < 2; ++bj) {
;                     if (BASE_F32) { bs[m][bj][0] = *(const GAS_ f32x4*)(basef + off + bj * 128); bs[m][bj][1] = *(const GAS_ f32x4*)(basef + off + bj * 128 + 4); }
;                     else bh[m][bj] = *(const GAS_ u32x4*)(XB + off + bj * 128); } }
;             asm volatile("" ::: "memory");
; #pragma unroll
;             for (int m = 0; m < 4; ++m) {
;                 const size_t off = (size_t)(row0 + ai * 128 + m * 16) * ldc + col0;
;                 float ssq = 0.f;
; #pragma unroll
;                 for (int bj = 0; bj < 2; ++bj) {
;                     f32x4 b0, b1;
;                     if (BASE_F32) { b0 = bs[m][bj][0]; b1 = bs[m][bj][1]; }
;                     else { const u32x4 h = bh[m][bj];
;                         b0 = (f32x4){__builtin_bit_cast(float, h.x << 16), __builtin_bit_cast(float, h.x & 0xffff0000u), __builtin_bit_cast(float, h.y << 16), __builtin_bit_cast(float, h.y & 0xffff0000u)};
;                         b1 = (f32x4){__builtin_bit_cast(float, h.z << 16), __builtin_bit_cast(float, h.z & 0xffff0000u), __builtin_bit_cast(float, h.w << 16), __builtin_bit_cast(float, h.w & 0xffff0000u)}; }
;                     const f32x4 v0 = b0 + acc[ai][bj][m][0], v1 = b1 + acc[ai][bj][m][1];
;                     ssq += ((v0[0] * v0[0] + v0[1] * v0[1]) + (v0[2] * v0[2] + v0[3] * v0[3])) + ((v1[0] * v1[0] + v1[1] * v1[1]) + (v1[2] * v1[2] + v1[3] * v1[3]));
;                     u32x4 w; w.x = pk2(v0[0], v0[1]); w.y = pk2(v0[2], v0[3]); w.z = pk2(v1[0], v1[1]); w.w = pk2(v1[2], v1[3]); *(GAS_ u32x4*)(XB + off + bj * 128) = w;
;                 }
;                 ssq += __shfl_xor(ssq, 16); ssq += __shfl_xor(ssq, 32);
;                 if (fq == 0) *(GAS_ float*)(SS + (size_t)(row0 + ai * 128 + m * 16) * 16 + u.pn * 4 + wc) = ssq;
;             }
.LBB0_1313:
	s_or_b64 exec, exec, s[20:21]
	v_add_u32_e32 v110, 0x80, v192
	v_ashrrev_i32_e32 v111, 31, v110
	v_lshlrev_b64 v[120:121], 11, v[110:111]
	s_waitcnt lgkmcnt(0)
	v_lshl_add_u64 v[80:81], v[190:191], 0, v[120:121]
	global_load_dwordx4 v[112:115], v[80:81], off
	global_load_dwordx4 v[116:119], v[80:81], off offset:256
	v_add_u32_e32 v108, 0x90, v192
	v_ashrrev_i32_e32 v109, 31, v108
	v_lshlrev_b64 v[80:81], 11, v[108:109]
	v_add_u32_e32 v106, 0xa0, v192
	v_lshl_add_u64 v[80:81], v[190:191], 0, v[80:81]
	v_ashrrev_i32_e32 v107, 31, v106
	global_load_dwordx4 v[100:103], v[80:81], off
	global_load_dwordx4 v[96:99], v[80:81], off offset:256
	v_lshlrev_b64 v[80:81], 11, v[106:107]
	v_add_u32_e32 v104, 0xb0, v192
	v_lshl_add_u64 v[80:81], v[190:191], 0, v[80:81]
	v_ashrrev_i32_e32 v105, 31, v104
	global_load_dwordx4 v[92:95], v[80:81], off
	global_load_dwordx4 v[88:91], v[80:81], off offset:256
	v_lshlrev_b64 v[80:81], 11, v[104:105]
	v_lshl_add_u64 v[80:81], v[190:191], 0, v[80:81]
	global_load_dwordx4 v[84:87], v[80:81], off
	s_nop 0
	global_load_dwordx4 v[80:83], v[80:81], off offset:256
	s_waitcnt vmcnt(7)
	v_lshlrev_b32_e32 v122, 16, v112
	v_and_b32_e32 v123, 0xffff0000, v112
	v_lshlrev_b32_e32 v112, 16, v113
	v_and_b32_e32 v113, 0xffff0000, v113
	v_lshlrev_b32_e32 v124, 16, v114
	v_and_b32_e32 v125, 0xffff0000, v114
	v_lshlrev_b32_e32 v114, 16, v115
	v_and_b32_e32 v115, 0xffff0000, v115
	v_pk_add_f32 v[78:79], v[78:79], v[112:113]
	v_pk_add_f32 v[76:77], v[76:77], v[122:123]
	v_pk_add_f32 v[112:113], v[74:75], v[114:115]
	v_mul_f32_e32 v74, v77, v77
	v_mul_f32_e32 v75, v79, v79
	v_pk_add_f32 v[72:73], v[72:73], v[124:125]
	v_fmac_f32_e32 v74, v76, v76
	v_fmac_f32_e32 v75, v78, v78
	v_add_f32_e32 v74, v74, v75
	v_mul_f32_e32 v75, v73, v73
	v_mul_f32_e32 v114, v113, v113
	v_fmac_f32_e32 v75, v72, v72
	v_fmac_f32_e32 v114, v112, v112
	v_add_f32_e32 v75, v75, v114
	v_add_f32_e32 v114, v74, v75
	v_cvt_pk_bf16_f32 v74, v76, v77
	v_cvt_pk_bf16_f32 v76, v72, v73
	v_lshl_add_u64 v[72:73], s[4:5], 0, v[120:121]
	v_cvt_pk_bf16_f32 v75, v78, v79
	v_cvt_pk_bf16_f32 v77, v112, v113
	v_lshl_add_u64 v[72:73], v[188:189], 1, v[72:73]
	global_store_dwordx4 v[72:73], v[74:77], off
	s_waitcnt vmcnt(7)
	v_lshlrev_b32_e32 v78, 16, v118
	v_and_b32_e32 v79, 0xffff0000, v118
	v_lshlrev_b32_e32 v74, 16, v116
	v_and_b32_e32 v75, 0xffff0000, v116
	v_lshlrev_b32_e32 v76, 16, v117
	v_and_b32_e32 v77, 0xffff0000, v117
	v_lshlrev_b32_e32 v112, 16, v119
	v_and_b32_e32 v113, 0xffff0000, v119
	v_pk_add_f32 v[70:71], v[70:71], v[76:77]
	v_pk_add_f32 v[68:69], v[68:69], v[74:75]
	v_pk_add_f32 v[74:75], v[66:67], v[112:113]
	v_pk_add_f32 v[66:67], v[64:65], v[78:79]
	v_mul_f32_e32 v64, v69, v69
	v_mul_f32_e32 v65, v71, v71
	v_fmac_f32_e32 v64, v68, v68
	v_fmac_f32_e32 v65, v70, v70
	v_add_f32_e32 v64, v64, v65
	v_mul_f32_e32 v65, v67, v67
	v_mul_f32_e32 v76, v75, v75
	v_fmac_f32_e32 v65, v66, v66
	v_fmac_f32_e32 v76, v74, v74
	v_add_f32_e32 v65, v65, v76
	v_add_f32_e32 v64, v64, v65
	v_add_f32_e32 v76, v114, v64
	v_cvt_pk_bf16_f32 v64, v68, v69
	v_cvt_pk_bf16_f32 v65, v70, v71
	v_cvt_pk_bf16_f32 v66, v66, v67
	v_cvt_pk_bf16_f32 v67, v74, v75
	global_store_dwordx4 v[72:73], v[64:67], off offset:256
	s_nop 1
	v_mov_b32_e32 v64, v76
	s_nop 1
	v_permlane16_swap_b32_e32 v76, v64
	s_waitcnt lgkmcnt(0)
	v_add_f32_e32 v64, v76, v64
	v_mov_b32_e32 v65, v64
	s_nop 1
	v_permlane32_swap_b32_e32 v64, v65
	s_and_saveexec_b64 s[20:21], s[6:7]
	s_cbranch_execz .LBB0_1315
	v_readlane_b32 s44, v254, 18
	v_readlane_b32 s45, v254, 19
	v_readlane_b32 s49, v254, 23
	v_readlane_b32 s52, v254, 26
	v_readlane_b32 s48, v254, 22
	v_readlane_b32 s50, v254, 24
	v_readlane_b32 s51, v254, 25
	v_readlane_b32 s53, v254, 27
	v_readlane_b32 s54, v254, 28
	v_readlane_b32 s55, v254, 29
	v_readlane_b32 s56, v254, 30
	v_readlane_b32 s57, v254, 31
	v_readlane_b32 s58, v254, 32
	v_readlane_b32 s59, v254, 33
	s_mov_b32 s52, 0xff800000
	s_mov_b32 s49, s45
	v_readlane_b32 s46, v254, 20
	v_readlane_b32 s47, v254, 21
	v_writelane_b32 v254, s48, 18
	v_lshlrev_b64 v[66:67], 6, v[110:111]
	v_lshl_add_u64 v[66:67], s[12:13], 0, v[66:67]
	v_writelane_b32 v254, s49, 19
	v_writelane_b32 v254, s50, 20
	v_writelane_b32 v254, s51, 21
	v_writelane_b32 v254, s52, 22
	v_writelane_b32 v254, s53, 23
	v_writelane_b32 v254, s54, 24
	v_writelane_b32 v254, s55, 25
	v_writelane_b32 v254, s56, 26
	v_writelane_b32 v254, s57, 27
	v_writelane_b32 v254, s58, 28
	v_writelane_b32 v254, s59, 29
	v_writelane_b32 v254, s60, 30
	v_writelane_b32 v254, s61, 31
	v_lshl_add_u64 v[66:67], s[18:19], 2, v[66:67]
	s_lshl_b32 s44, s35, 2
	v_writelane_b32 v254, s62, 32
	v_writelane_b32 v254, s63, 33
	v_lshl_add_u64 v[66:67], v[66:67], 0, s[44:45]
	s_waitcnt lgkmcnt(0)
	v_add_f32_e32 v64, v64, v65
	global_store_dword v[66:67], v64, off
; #define GAS_ __attribute__((address_space(1)))
; __device__ __forceinline__ unsigned pk2(float lo, float hi) { f32x2_t v = {lo, hi}; bf16x2_t b = __builtin_convertvector(v, bf16x2_t); return __builtin_bit_cast(unsigned, b); }
;     __device__ __forceinline__ void operator()(const f32x4 (&acc)[2][2][4][2], const Unit& u, int wr, int wc, int fr, int fq) const {
;     ...
; #pragma unroll
;             for (int m = 0; m < 4; ++m) {
;                 const size_t off = (size_t)(row0 + ai * 128 + m * 16) * ldc + col0;
;                 float ssq = 0.f;
; #pragma unroll
;                 for (int bj = 0; bj < 2; ++bj) {
;                     f32x4 b0, b1;
;                     if (BASE_F32) { b0 = bs[m][bj][0]; b1 = bs[m][bj][1]; }
;                     else { const u32x4 h = bh[m][bj];
;                         b0 = (f32x4){__builtin_bit_cast(float, h.x << 16), __builtin_bit_cast(float, h.x & 0xffff0000u), __builtin_bit_cast(float, h.y << 16), __builtin_bit_cast(float, h.y & 0xffff0000u)};
;                         b1 = (f32x4){__builtin_bit_cast(float, h.z << 16), __builtin_bit_cast(float, h.z & 0xffff0000u), __builtin_bit_cast(float, h.w << 16), __builtin_bit_cast(float, h.w & 0xffff0000u)}; }
;                     const f32x4 v0 = b0 + acc[ai][bj][m][0], v1 = b1 + acc[ai][bj][m][1];
;                     ssq += ((v0[0] * v0[0] + v0[1] * v0[1]) + (v0[2] * v0[2] + v0[3] * v0[3])) + ((v1[0] * v1[0] + v1[1] * v1[1]) + (v1[2] * v1[2] + v1[3] * v1[3]));
;                     u32x4 w; w.x = pk2(v0[0], v0[1]); w.y = pk2(v0[2], v0[3]); w.z = pk2(v1[0], v1[1]); w.w = pk2(v1[2], v1[3]); *(GAS_ u32x4*)(XB + off + bj * 128) = w;
;                 }
;                 ssq += __shfl_xor(ssq, 16); ssq += __shfl_xor(ssq, 32);
;                 if (fq == 0) *(GAS_ float*)(SS + (size_t)(row0 + ai * 128 + m * 16) * 16 + u.pn * 4 + wc) = ssq;
;             }
.LBB0_1315:
	s_or_b64 exec, exec, s[20:21]
	s_waitcnt vmcnt(7)
	v_lshlrev_b32_e32 v66, 16, v100
	v_and_b32_e32 v67, 0xffff0000, v100
	v_lshlrev_b32_e32 v68, 16, v101
	v_and_b32_e32 v69, 0xffff0000, v101
	v_lshlrev_b32_e32 v70, 16, v102
	v_and_b32_e32 v71, 0xffff0000, v102
	v_lshlrev_b32_e32 v72, 16, v103
	v_and_b32_e32 v73, 0xffff0000, v103
	v_pk_add_f32 v[62:63], v[62:63], v[68:69]
	v_pk_add_f32 v[60:61], v[60:61], v[66:67]
	v_pk_add_f32 v[66:67], v[58:59], v[72:73]
	v_pk_add_f32 v[58:59], v[56:57], v[70:71]
	v_mul_f32_e32 v56, v61, v61
	v_mul_f32_e32 v57, v63, v63
	v_fmac_f32_e32 v56, v60, v60
	v_fmac_f32_e32 v57, v62, v62
	v_add_f32_e32 v56, v56, v57
	v_mul_f32_e32 v57, v59, v59
	v_mul_f32_e32 v68, v67, v67
	v_fmac_f32_e32 v57, v58, v58
	v_fmac_f32_e32 v68, v66, v66
	v_add_f32_e32 v57, v57, v68
	v_add_f32_e32 v70, v56, v57
	v_cvt_pk_bf16_f32 v56, v60, v61
	v_cvt_pk_bf16_f32 v57, v62, v63
	s_waitcnt vmcnt(6)
	v_lshlrev_b32_e32 v60, 16, v96
	v_and_b32_e32 v61, 0xffff0000, v96
	v_lshlrev_b32_e32 v62, 16, v97
	v_and_b32_e32 v63, 0xffff0000, v97
	v_cvt_pk_bf16_f32 v58, v58, v59
	v_cvt_pk_bf16_f32 v59, v66, v67
	v_lshlrev_b32_e32 v66, 16, v98
	v_and_b32_e32 v67, 0xffff0000, v98
	v_pk_add_f32 v[54:55], v[54:55], v[62:63]
	v_pk_add_f32 v[52:53], v[52:53], v[60:61]
	v_lshlrev_b32_e32 v68, 16, v99
	v_and_b32_e32 v69, 0xffff0000, v99
	v_pk_add_f32 v[62:63], v[48:49], v[66:67]
	v_mul_f32_e32 v48, v53, v53
	v_mul_f32_e32 v49, v55, v55
	v_pk_add_f32 v[60:61], v[50:51], v[68:69]
	v_fmac_f32_e32 v48, v52, v52
	v_fmac_f32_e32 v49, v54, v54
	v_add_f32_e32 v48, v48, v49
	v_mul_f32_e32 v49, v63, v63
	v_mul_f32_e32 v50, v61, v61
	v_fmac_f32_e32 v49, v62, v62
	v_fmac_f32_e32 v50, v60, v60
	v_add_f32_e32 v49, v49, v50
	v_add_f32_e32 v48, v48, v49
	v_add_f32_e32 v51, v70, v48
	v_mov_b32_e32 v66, v51
	s_nop 1
	v_permlane16_swap_b32_e32 v51, v66
	s_waitcnt lgkmcnt(1)
	v_lshlrev_b64 v[64:65], 10, v[108:109]
	v_lshl_add_u64 v[48:49], v[64:65], 1, s[4:5]
	v_lshl_add_u64 v[64:65], v[188:189], 1, v[48:49]
	v_cvt_pk_bf16_f32 v50, v52, v53
	s_waitcnt lgkmcnt(0)
	v_add_f32_e32 v48, v51, v66
	v_mov_b32_e32 v49, v48
	s_nop 1
	v_permlane32_swap_b32_e32 v48, v49
	v_cvt_pk_bf16_f32 v51, v54, v55
	v_cvt_pk_bf16_f32 v52, v62, v63
	v_cvt_pk_bf16_f32 v53, v60, v61
	global_store_dwordx4 v[64:65], v[56:59], off
	global_store_dwordx4 v[64:65], v[50:53], off offset:256
	s_and_saveexec_b64 s[20:21], s[6:7]
	s_cbranch_execz .LBB0_1317
	v_readlane_b32 s44, v254, 18
	v_readlane_b32 s45, v254, 19
	v_readlane_b32 s49, v254, 23
	v_readlane_b32 s52, v254, 26
	v_readlane_b32 s48, v254, 22
	v_readlane_b32 s50, v254, 24
	v_readlane_b32 s51, v254, 25
	v_readlane_b32 s53, v254, 27
	v_readlane_b32 s54, v254, 28
	v_readlane_b32 s55, v254, 29
	v_readlane_b32 s56, v254, 30
	v_readlane_b32 s57, v254, 31
	v_readlane_b32 s58, v254, 32
	v_readlane_b32 s59, v254, 33
	s_mov_b32 s52, 0xff800000
	s_mov_b32 s49, s45
	v_readlane_b32 s46, v254, 20
	v_readlane_b32 s47, v254, 21
	v_writelane_b32 v254, s48, 18
	v_lshlrev_b64 v[50:51], 6, v[108:109]
	v_lshl_add_u64 v[50:51], s[12:13], 0, v[50:51]
	v_writelane_b32 v254, s49, 19
	v_writelane_b32 v254, s50, 20
	v_writelane_b32 v254, s51, 21
	v_writelane_b32 v254, s52, 22
	v_writelane_b32 v254, s53, 23
	v_writelane_b32 v254, s54, 24
	v_writelane_b32 v254, s55, 25
	v_writelane_b32 v254, s56, 26
	v_writelane_b32 v254, s57, 27
	v_writelane_b32 v254, s58, 28
	v_writelane_b32 v254, s59, 29
	v_writelane_b32 v254, s60, 30
	v_writelane_b32 v254, s61, 31
	v_lshl_add_u64 v[50:51], s[18:19], 2, v[50:51]
	s_lshl_b32 s44, s35, 2
	v_writelane_b32 v254, s62, 32
	v_writelane_b32 v254, s63, 33
	v_lshl_add_u64 v[50:51], v[50:51], 0, s[44:45]
	s_waitcnt lgkmcnt(0)
	v_add_f32_e32 v48, v48, v49
	global_store_dword v[50:51], v48, off
.LBB0_1317:
	s_or_b64 exec, exec, s[20:21]
	s_waitcnt vmcnt(7)
	v_lshlrev_b32_e32 v50, 16, v92
	v_and_b32_e32 v51, 0xffff0000, v92
	v_lshlrev_b32_e32 v52, 16, v93
	v_and_b32_e32 v53, 0xffff0000, v93
	v_lshlrev_b32_e32 v54, 16, v94
	v_and_b32_e32 v55, 0xffff0000, v94
	v_lshlrev_b32_e32 v56, 16, v95
	v_and_b32_e32 v57, 0xffff0000, v95
	v_pk_add_f32 v[46:47], v[46:47], v[52:53]
	v_pk_add_f32 v[44:45], v[44:45], v[50:51]
	v_pk_add_f32 v[50:51], v[42:43], v[56:57]
	v_pk_add_f32 v[42:43], v[40:41], v[54:55]
	v_mul_f32_e32 v40, v45, v45
	v_mul_f32_e32 v41, v47, v47
	v_fmac_f32_e32 v40, v44, v44
	v_fmac_f32_e32 v41, v46, v46
	v_add_f32_e32 v40, v40, v41
	v_mul_f32_e32 v41, v43, v43
	v_mul_f32_e32 v52, v51, v51
	v_fmac_f32_e32 v41, v42, v42
	v_fmac_f32_e32 v52, v50, v50
	v_add_f32_e32 v41, v41, v52
	v_add_f32_e32 v54, v40, v41
	v_cvt_pk_bf16_f32 v40, v44, v45
	v_cvt_pk_bf16_f32 v41, v46, v47
	s_waitcnt vmcnt(6)
	v_lshlrev_b32_e32 v44, 16, v88
	v_and_b32_e32 v45, 0xffff0000, v88
	v_lshlrev_b32_e32 v46, 16, v89
	v_and_b32_e32 v47, 0xffff0000, v89
	v_cvt_pk_bf16_f32 v42, v42, v43
	v_cvt_pk_bf16_f32 v43, v50, v51
	v_lshlrev_b32_e32 v50, 16, v90
	v_and_b32_e32 v51, 0xffff0000, v90
	v_pk_add_f32 v[38:39], v[38:39], v[46:47]
	v_pk_add_f32 v[36:37], v[36:37], v[44:45]
	v_lshlrev_b32_e32 v52, 16, v91
	v_and_b32_e32 v53, 0xffff0000, v91
	v_pk_add_f32 v[46:47], v[32:33], v[50:51]
	v_mul_f32_e32 v32, v37, v37
	v_mul_f32_e32 v33, v39, v39
	v_pk_add_f32 v[44:45], v[34:35], v[52:53]
	v_fmac_f32_e32 v32, v36, v36
	v_fmac_f32_e32 v33, v38, v38
	v_add_f32_e32 v32, v32, v33
	v_mul_f32_e32 v33, v47, v47
	v_mul_f32_e32 v34, v45, v45
	v_fmac_f32_e32 v33, v46, v46
	v_fmac_f32_e32 v34, v44, v44
	v_add_f32_e32 v33, v33, v34
	v_add_f32_e32 v32, v32, v33
	v_add_f32_e32 v35, v54, v32
	v_mov_b32_e32 v50, v35
	s_nop 1
	v_permlane16_swap_b32_e32 v35, v50
	s_waitcnt lgkmcnt(1)
	v_lshlrev_b64 v[48:49], 10, v[106:107]
	v_lshl_add_u64 v[32:33], v[48:49], 1, s[4:5]
	v_lshl_add_u64 v[48:49], v[188:189], 1, v[32:33]
	v_cvt_pk_bf16_f32 v34, v36, v37
	s_waitcnt lgkmcnt(0)
	v_add_f32_e32 v32, v35, v50
	v_mov_b32_e32 v33, v32
	s_nop 1
	v_permlane32_swap_b32_e32 v32, v33
	v_cvt_pk_bf16_f32 v35, v38, v39
	v_cvt_pk_bf16_f32 v36, v46, v47
	v_cvt_pk_bf16_f32 v37, v44, v45
	global_store_dwordx4 v[48:49], v[40:43], off
	global_store_dwordx4 v[48:49], v[34:37], off offset:256
	s_and_saveexec_b64 s[20:21], s[6:7]
	s_cbranch_execz .LBB0_1319
; #define GAS_ __attribute__((address_space(1)))
; __device__ __forceinline__ unsigned pk2(float lo, float hi) { f32x2_t v = {lo, hi}; bf16x2_t b = __builtin_convertvector(v, bf16x2_t); return __builtin_bit_cast(unsigned, b); }
;     __device__ __forceinline__ void operator()(const f32x4 (&acc)[2][2][4][2], const Unit& u, int wr, int wc, int fr, int fq) const {
;     ...
; #pragma unroll
;             for (int m = 0; m < 4; ++m) {
;                 const size_t off = (size_t)(row0 + ai * 128 + m * 16) * ldc + col0;
;                 float ssq = 0.f;
; #pragma unroll
;                 for (int bj = 0; bj < 2; ++bj) {
;                     f32x4 b0, b1;
;                     if (BASE_F32) { b0 = bs[m][bj][0]; b1 = bs[m][bj][1]; }
;                     else { const u32x4 h = bh[m][bj];
;                         b0 = (f32x4){__builtin_bit_cast(float, h.x << 16), __builtin_bit_cast(float, h.x & 0xffff0000u), __builtin_bit_cast(float, h.y << 16), __builtin_bit_cast(float, h.y & 0xffff0000u)};
;                         b1 = (f32x4){__builtin_bit_cast(float, h.z << 16), __builtin_bit_cast(float, h.z & 0xffff0000u), __builtin_bit_cast(float, h.w << 16), __builtin_bit_cast(float, h.w & 0xffff0000u)}; }
;                     const f32x4 v0 = b0 + acc[ai][bj][m][0], v1 = b1 + acc[ai][bj][m][1];
;                     ssq += ((v0[0] * v0[0] + v0[1] * v0[1]) + (v0[2] * v0[2] + v0[3] * v0[3])) + ((v1[0] * v1[0] + v1[1] * v1[1]) + (v1[2] * v1[2] + v1[3] * v1[3]));
;                     u32x4 w; w.x = pk2(v0[0], v0[1]); w.y = pk2(v0[2], v0[3]); w.z = pk2(v1[0], v1[1]); w.w = pk2(v1[2], v1[3]); *(GAS_ u32x4*)(XB + off + bj * 128) = w;
;                 }
;                 ssq += __shfl_xor(ssq, 16); ssq += __shfl_xor(ssq, 32);
;                 if (fq == 0) *(GAS_ float*)(SS + (size_t)(row0 + ai * 128 + m * 16) * 16 + u.pn * 4 + wc) = ssq;
;             }
	v_readlane_b32 s44, v254, 18
	v_readlane_b32 s45, v254, 19
	v_readlane_b32 s49, v254, 23
	v_readlane_b32 s52, v254, 26
	v_readlane_b32 s48, v254, 22
	v_readlane_b32 s50, v254, 24
	v_readlane_b32 s51, v254, 25
	v_readlane_b32 s53, v254, 27
	v_readlane_b32 s54, v254, 28
	v_readlane_b32 s55, v254, 29
	v_readlane_b32 s56, v254, 30
	v_readlane_b32 s57, v254, 31
	v_readlane_b32 s58, v254, 32
	v_readlane_b32 s59, v254, 33
	s_mov_b32 s52, 0xff800000
	s_mov_b32 s49, s45
	v_readlane_b32 s46, v254, 20
	v_readlane_b32 s47, v254, 21
	v_writelane_b32 v254, s48, 18
	v_lshlrev_b64 v[34:35], 6, v[106:107]
	v_lshl_add_u64 v[34:35], s[12:13], 0, v[34:35]
	v_writelane_b32 v254, s49, 19
	v_writelane_b32 v254, s50, 20
	v_writelane_b32 v254, s51, 21
	v_writelane_b32 v254, s52, 22
	v_writelane_b32 v254, s53, 23
	v_writelane_b32 v254, s54, 24
	v_writelane_b32 v254, s55, 25
	v_writelane_b32 v254, s56, 26
	v_writelane_b32 v254, s57, 27
	v_writelane_b32 v254, s58, 28
	v_writelane_b32 v254, s59, 29
	v_writelane_b32 v254, s60, 30
	v_writelane_b32 v254, s61, 31
	v_lshl_add_u64 v[34:35], s[18:19], 2, v[34:35]
	s_lshl_b32 s44, s35, 2
	v_writelane_b32 v254, s62, 32
	v_writelane_b32 v254, s63, 33
	v_lshl_add_u64 v[34:35], v[34:35], 0, s[44:45]
	s_waitcnt lgkmcnt(0)
	v_add_f32_e32 v32, v32, v33
	global_store_dword v[34:35], v32, off
.LBB0_1319:
	s_or_b64 exec, exec, s[20:21]
	s_waitcnt vmcnt(7)
	v_lshlrev_b32_e32 v34, 16, v84
	v_and_b32_e32 v35, 0xffff0000, v84
	v_lshlrev_b32_e32 v36, 16, v85
	v_and_b32_e32 v37, 0xffff0000, v85
	v_lshlrev_b32_e32 v38, 16, v86
	v_and_b32_e32 v39, 0xffff0000, v86
	v_lshlrev_b32_e32 v40, 16, v87
	v_and_b32_e32 v41, 0xffff0000, v87
	v_pk_add_f32 v[30:31], v[30:31], v[36:37]
	v_pk_add_f32 v[28:29], v[28:29], v[34:35]
	v_pk_add_f32 v[34:35], v[26:27], v[40:41]
	v_pk_add_f32 v[26:27], v[24:25], v[38:39]
	v_mul_f32_e32 v24, v29, v29
	v_mul_f32_e32 v25, v31, v31
	v_fmac_f32_e32 v24, v28, v28
	v_fmac_f32_e32 v25, v30, v30
	v_add_f32_e32 v24, v24, v25
	v_mul_f32_e32 v25, v27, v27
	v_mul_f32_e32 v36, v35, v35
	v_fmac_f32_e32 v25, v26, v26
	v_fmac_f32_e32 v36, v34, v34
	v_add_f32_e32 v25, v25, v36
	v_add_f32_e32 v38, v24, v25
	v_cvt_pk_bf16_f32 v24, v28, v29
	v_cvt_pk_bf16_f32 v25, v30, v31
	s_waitcnt vmcnt(6)
	v_lshlrev_b32_e32 v28, 16, v80
	v_and_b32_e32 v29, 0xffff0000, v80
	v_lshlrev_b32_e32 v30, 16, v81
	v_and_b32_e32 v31, 0xffff0000, v81
	v_cvt_pk_bf16_f32 v26, v26, v27
	v_cvt_pk_bf16_f32 v27, v34, v35
	v_lshlrev_b32_e32 v34, 16, v82
	v_and_b32_e32 v35, 0xffff0000, v82
	v_pk_add_f32 v[22:23], v[22:23], v[30:31]
	v_pk_add_f32 v[20:21], v[20:21], v[28:29]
	v_lshlrev_b32_e32 v36, 16, v83
	v_and_b32_e32 v37, 0xffff0000, v83
	v_pk_add_f32 v[30:31], v[16:17], v[34:35]
	v_mul_f32_e32 v16, v21, v21
	v_mul_f32_e32 v17, v23, v23
	v_pk_add_f32 v[28:29], v[18:19], v[36:37]
	v_fmac_f32_e32 v16, v20, v20
	v_fmac_f32_e32 v17, v22, v22
	v_add_f32_e32 v16, v16, v17
	v_mul_f32_e32 v17, v31, v31
	v_mul_f32_e32 v18, v29, v29
	v_fmac_f32_e32 v17, v30, v30
	v_fmac_f32_e32 v18, v28, v28
	v_add_f32_e32 v17, v17, v18
	v_add_f32_e32 v16, v16, v17
	v_add_f32_e32 v19, v38, v16
	v_mov_b32_e32 v34, v19
	s_nop 1
	v_permlane16_swap_b32_e32 v19, v34
	s_waitcnt lgkmcnt(1)
	v_lshlrev_b64 v[32:33], 10, v[104:105]
	v_lshl_add_u64 v[16:17], v[32:33], 1, s[4:5]
	v_lshl_add_u64 v[32:33], v[188:189], 1, v[16:17]
	v_cvt_pk_bf16_f32 v18, v20, v21
	s_waitcnt lgkmcnt(0)
	v_add_f32_e32 v16, v19, v34
	v_mov_b32_e32 v17, v16
	s_nop 1
	v_permlane32_swap_b32_e32 v16, v17
	v_cvt_pk_bf16_f32 v19, v22, v23
	v_cvt_pk_bf16_f32 v20, v30, v31
	v_cvt_pk_bf16_f32 v21, v28, v29
	global_store_dwordx4 v[32:33], v[24:27], off
	global_store_dwordx4 v[32:33], v[18:21], off offset:256
	s_and_saveexec_b64 s[20:21], s[6:7]
	s_cbranch_execz .LBB0_1321
	v_readlane_b32 s44, v254, 18
	v_readlane_b32 s45, v254, 19
	v_readlane_b32 s49, v254, 23
	v_readlane_b32 s52, v254, 26
	v_readlane_b32 s48, v254, 22
	v_readlane_b32 s50, v254, 24
	v_readlane_b32 s51, v254, 25
	v_readlane_b32 s53, v254, 27
	v_readlane_b32 s54, v254, 28
	v_readlane_b32 s55, v254, 29
	v_readlane_b32 s56, v254, 30
	v_readlane_b32 s57, v254, 31
	v_readlane_b32 s58, v254, 32
	v_readlane_b32 s59, v254, 33
	s_mov_b32 s52, 0xff800000
	s_mov_b32 s49, s45
	v_readlane_b32 s46, v254, 20
	v_readlane_b32 s47, v254, 21
	v_writelane_b32 v254, s48, 18
	v_lshlrev_b64 v[18:19], 6, v[104:105]
	v_lshl_add_u64 v[18:19], s[12:13], 0, v[18:19]
	v_writelane_b32 v254, s49, 19
	v_writelane_b32 v254, s50, 20
	v_writelane_b32 v254, s51, 21
	v_writelane_b32 v254, s52, 22
	v_writelane_b32 v254, s53, 23
	v_writelane_b32 v254, s54, 24
	v_writelane_b32 v254, s55, 25
	v_writelane_b32 v254, s56, 26
	v_writelane_b32 v254, s57, 27
	v_writelane_b32 v254, s58, 28
	v_writelane_b32 v254, s59, 29
	v_writelane_b32 v254, s60, 30
	v_writelane_b32 v254, s61, 31
	v_lshl_add_u64 v[18:19], s[18:19], 2, v[18:19]
	s_lshl_b32 s44, s35, 2
	v_writelane_b32 v254, s62, 32
	v_writelane_b32 v254, s63, 33
	v_lshl_add_u64 v[18:19], v[18:19], 0, s[44:45]
	s_waitcnt lgkmcnt(0)
	v_add_f32_e32 v16, v16, v17
	global_store_dword v[18:19], v16, off
